# v66 + back-edge rotation (7.11) of the 5 peeled GEMM K-loops: loop-back barrier is the loop head; counter update, exit test and next-iteration scalar header run before it
# baseline (speedup 1.0000x reference)
; #define PG8_STAGE(bufoff, gbase, voff) do { _Pragma("unroll") for (int _i = 0; _i < 2; ++_i) \
;         __builtin_amdgcn_global_load_lds((const unsigned*)((const char*)(gbase) + (voff)[_i]), (LAS unsigned*)(lds + (bufoff) + ldsw + _i * 8192), 16, 0, 0); } while (0)
; #define PG8_LDA(dst, b, h) do { _Pragma("unroll") for (int m = 0; m < 4; ++m) _Pragma("unroll") for (int k = 0; k < 2; ++k) dst[m][k] = *(const LAS bf16x8*)(lds + PG8_SA(b, h) + aoff + m * 2048 + k * 1024); } while (0)
; #define PG8_LDB(dst, b, h) do { _Pragma("unroll") for (int n = 0; n < 2; ++n) _Pragma("unroll") for (int k = 0; k < 2; ++k) dst[n][k] = *(const LAS bf16x8*)(lds + PG8_SB(b, h) + boff + n * 2048 + k * 1024); } while (0)
; #define PG8_MMA(ai, bj, At, Bt) do { __builtin_amdgcn_s_setprio(1); _Pragma("unroll") for (int m = 0; m < 4; ++m) _Pragma("unroll") for (int n = 0; n < 2; ++n) _Pragma("unroll") for (int k = 0; k < 2; ++k) \
;         acc[ai][bj][m][n] = __builtin_amdgcn_mfma_f32_16x16x32_bf16(Bt[n][k], At[m][k], acc[ai][bj][m][n], 0, 0, 0); __builtin_amdgcn_s_setprio(0); } while (0)
; #define PG8_WAIT_V(n) asm volatile("s_waitcnt vmcnt(" #n ")" ::: "memory")
; #define PG8_WAIT_L(n) asm volatile("s_waitcnt lgkmcnt(" #n ")" ::: "memory")
; #define PG8_BAR __builtin_amdgcn_s_barrier()
; #define PG8_SCHED __builtin_amdgcn_sched_barrier(0)
; template <class Epi, bool ALIGN_EPI = PG8_ALIGN, bool SP2 = PG8_SP2>
; __device__ __forceinline__ void gemm_phase(LAS uchar* lds, const Gemm g, const StaticOrder& S, const Epi& E) {
;     ...
;             PG8_WAIT_V(8); PG8_WAIT_L(0); PG8_BAR; PG8_MMA(1, 0, At, B0); PG8_MMA(1, 1, At, B1); PG8_BAR; PG8_SCHED;
;             PG8_LDB(B0, 1, 0); PG8_LDB(B1, 1, 1); PG8_SCHED; PG8_LDA(At, 1, 0); PG8_STAGE(PG8_SA(0, 1), a2 + hstepA, voffA);
;             PG8_WAIT_V(8); PG8_WAIT_L(0); PG8_BAR; PG8_MMA(0, 0, At, B0); PG8_MMA(0, 1, At, B1); PG8_BAR; PG8_SCHED;
.Lrw_done_345_1_pl:
	s_waitcnt lgkmcnt(0)
	s_barrier
	s_setprio 1
	s_waitcnt lgkmcnt(0)
	v_mfma_f32_16x16x32_bf16 v[62:65], v[164:167], v[204:207], 0
	v_mfma_f32_16x16x32_bf16 v[58:61], v[176:179], v[204:207], 0
	v_mfma_f32_16x16x32_bf16 v[54:57], v[164:167], v[212:215], 0
	v_mfma_f32_16x16x32_bf16 v[46:49], v[176:179], v[212:215], 0
	v_mfma_f32_16x16x32_bf16 v[38:41], v[164:167], v[220:223], 0
	v_mfma_f32_16x16x32_bf16 v[30:33], v[176:179], v[220:223], 0
	v_mfma_f32_16x16x32_bf16 v[22:25], v[164:167], v[228:231], 0
	v_mfma_f32_16x16x32_bf16 v[14:17], v[176:179], v[228:231], 0
	v_mfma_f32_16x16x32_bf16 v[62:65], v[172:175], v[208:211], v[62:65]
	v_mfma_f32_16x16x32_bf16 v[58:61], v[184:187], v[208:211], v[58:61]
	v_mfma_f32_16x16x32_bf16 v[54:57], v[172:175], v[216:219], v[54:57]
	v_mfma_f32_16x16x32_bf16 v[46:49], v[184:187], v[216:219], v[46:49]
	v_mfma_f32_16x16x32_bf16 v[38:41], v[172:175], v[224:227], v[38:41]
	v_mfma_f32_16x16x32_bf16 v[30:33], v[184:187], v[224:227], v[30:33]
	v_mfma_f32_16x16x32_bf16 v[22:25], v[172:175], v[232:235], v[22:25]
	v_mfma_f32_16x16x32_bf16 v[14:17], v[184:187], v[232:235], v[14:17]
	s_setprio 0
	s_setprio 1
	v_mfma_f32_16x16x32_bf16 v[50:53], v[188:191], v[204:207], 0
	v_mfma_f32_16x16x32_bf16 v[42:45], v[196:199], v[204:207], 0
	v_mfma_f32_16x16x32_bf16 v[34:37], v[188:191], v[212:215], 0
	v_mfma_f32_16x16x32_bf16 v[26:29], v[196:199], v[212:215], 0
	v_mfma_f32_16x16x32_bf16 v[18:21], v[188:191], v[220:223], 0
	v_mfma_f32_16x16x32_bf16 v[10:13], v[196:199], v[220:223], 0
	v_mfma_f32_16x16x32_bf16 v[6:9], v[188:191], v[228:231], 0
	v_mfma_f32_16x16x32_bf16 v[2:5], v[196:199], v[228:231], 0
	v_mfma_f32_16x16x32_bf16 v[50:53], v[192:195], v[208:211], v[50:53]
	v_mfma_f32_16x16x32_bf16 v[42:45], v[200:203], v[208:211], v[42:45]
	v_mfma_f32_16x16x32_bf16 v[34:37], v[192:195], v[216:219], v[34:37]
	v_mfma_f32_16x16x32_bf16 v[26:29], v[200:203], v[216:219], v[26:29]
	v_mfma_f32_16x16x32_bf16 v[18:21], v[192:195], v[224:227], v[18:21]
	v_mfma_f32_16x16x32_bf16 v[10:13], v[200:203], v[224:227], v[10:13]
	v_mfma_f32_16x16x32_bf16 v[6:9], v[192:195], v[232:235], v[6:9]
	v_mfma_f32_16x16x32_bf16 v[2:5], v[200:203], v[232:235], v[2:5]
	s_setprio 0
	s_barrier
	s_add_i32 s41, 0, 0x18000
	s_add_i32 s42, 0, 0x1c000
	v_add_u32_e32 v184, s41, v139
	v_add_u32_e32 v200, s42, v139
	ds_read_b128 v[164:167], v184
	ds_read_b128 v[172:175], v184 offset:1024
	ds_read_b128 v[176:179], v184 offset:2048
	ds_read_b128 v[184:187], v184 offset:3072
	ds_read_b128 v[188:191], v200
	ds_read_b128 v[192:195], v200 offset:1024
	ds_read_b128 v[196:199], v200 offset:2048
	ds_read_b128 v[200:203], v200 offset:3072
	s_add_u32 s16, s20, 0x44000
	s_addc_u32 s17, s21, 0
	s_mov_b32 m0, s27
	v_lshl_add_u64 v[240:241], s[16:17], 0, v[156:157]
	ds_read_b128 v[204:207], v171 offset:32768
	ds_read_b128 v[208:211], v171 offset:33792
	ds_read_b128 v[212:215], v171 offset:34816
	ds_read_b128 v[216:219], v171 offset:35840
	ds_read_b128 v[220:223], v171 offset:36864
	ds_read_b128 v[224:227], v171 offset:37888
	ds_read_b128 v[228:231], v171 offset:38912
	ds_read_b128 v[232:235], v171 offset:39936
	global_load_lds_dwordx4 v[240:241], off
	v_lshl_add_u64 v[240:241], s[16:17], 0, v[132:133]
	s_mov_b32 m0, s28
	s_nop 0
	global_load_lds_dwordx4 v[240:241], off
	s_waitcnt vmcnt(8)
	s_waitcnt lgkmcnt(0)
	s_barrier
	s_setprio 1
	s_waitcnt lgkmcnt(0)
	v_mfma_f32_16x16x32_bf16 v[126:129], v[164:167], v[204:207], v[126:129]
	v_mfma_f32_16x16x32_bf16 v[122:125], v[176:179], v[204:207], v[122:125]
	v_mfma_f32_16x16x32_bf16 v[118:121], v[164:167], v[212:215], v[118:121]
	v_mfma_f32_16x16x32_bf16 v[110:113], v[176:179], v[212:215], v[110:113]
	v_mfma_f32_16x16x32_bf16 v[102:105], v[164:167], v[220:223], v[102:105]
	v_mfma_f32_16x16x32_bf16 v[94:97], v[176:179], v[220:223], v[94:97]
	v_mfma_f32_16x16x32_bf16 v[86:89], v[164:167], v[228:231], v[86:89]
	v_mfma_f32_16x16x32_bf16 v[78:81], v[176:179], v[228:231], v[78:81]
	v_mfma_f32_16x16x32_bf16 v[126:129], v[172:175], v[208:211], v[126:129]
	v_mfma_f32_16x16x32_bf16 v[122:125], v[184:187], v[208:211], v[122:125]
	v_mfma_f32_16x16x32_bf16 v[118:121], v[172:175], v[216:219], v[118:121]
	v_mfma_f32_16x16x32_bf16 v[110:113], v[184:187], v[216:219], v[110:113]
	v_mfma_f32_16x16x32_bf16 v[102:105], v[172:175], v[224:227], v[102:105]
	v_mfma_f32_16x16x32_bf16 v[94:97], v[184:187], v[224:227], v[94:97]
	v_mfma_f32_16x16x32_bf16 v[86:89], v[172:175], v[232:235], v[86:89]
	v_mfma_f32_16x16x32_bf16 v[78:81], v[184:187], v[232:235], v[78:81]
	s_setprio 0
	s_setprio 1
	v_mfma_f32_16x16x32_bf16 v[114:117], v[188:191], v[204:207], v[114:117]
	v_mfma_f32_16x16x32_bf16 v[106:109], v[196:199], v[204:207], v[106:109]
	v_mfma_f32_16x16x32_bf16 v[98:101], v[188:191], v[212:215], v[98:101]
	v_mfma_f32_16x16x32_bf16 v[90:93], v[196:199], v[212:215], v[90:93]
	v_mfma_f32_16x16x32_bf16 v[82:85], v[188:191], v[220:223], v[82:85]
	v_mfma_f32_16x16x32_bf16 v[74:77], v[196:199], v[220:223], v[74:77]
	v_mfma_f32_16x16x32_bf16 v[70:73], v[188:191], v[228:231], v[70:73]
	v_mfma_f32_16x16x32_bf16 v[66:69], v[196:199], v[228:231], v[66:69]
	v_mfma_f32_16x16x32_bf16 v[114:117], v[192:195], v[208:211], v[114:117]
	v_mfma_f32_16x16x32_bf16 v[106:109], v[200:203], v[208:211], v[106:109]
	v_mfma_f32_16x16x32_bf16 v[98:101], v[192:195], v[216:219], v[98:101]
	v_mfma_f32_16x16x32_bf16 v[90:93], v[200:203], v[216:219], v[90:93]
	v_mfma_f32_16x16x32_bf16 v[82:85], v[192:195], v[224:227], v[82:85]
	v_mfma_f32_16x16x32_bf16 v[74:77], v[200:203], v[224:227], v[74:77]
	v_mfma_f32_16x16x32_bf16 v[70:73], v[192:195], v[232:235], v[70:73]
	v_mfma_f32_16x16x32_bf16 v[66:69], v[200:203], v[232:235], v[66:69]
	s_setprio 0
	s_barrier
; #define PG8_STAGE(bufoff, gbase, voff) do { _Pragma("unroll") for (int _i = 0; _i < 2; ++_i) \
;         __builtin_amdgcn_global_load_lds((const unsigned*)((const char*)(gbase) + (voff)[_i]), (LAS unsigned*)(lds + (bufoff) + ldsw + _i * 8192), 16, 0, 0); } while (0)
; #define PG8_LDA(dst, b, h) do { _Pragma("unroll") for (int m = 0; m < 4; ++m) _Pragma("unroll") for (int k = 0; k < 2; ++k) dst[m][k] = *(const LAS bf16x8*)(lds + PG8_SA(b, h) + aoff + m * 2048 + k * 1024); } while (0)
; #define PG8_LDB(dst, b, h) do { _Pragma("unroll") for (int n = 0; n < 2; ++n) _Pragma("unroll") for (int k = 0; k < 2; ++k) dst[n][k] = *(const LAS bf16x8*)(lds + PG8_SB(b, h) + boff + n * 2048 + k * 1024); } while (0)
; #define PG8_BAR __builtin_amdgcn_s_barrier()
; template <class Epi, bool ALIGN_EPI = PG8_ALIGN, bool SP2 = PG8_SP2>
; __device__ __forceinline__ void gemm_phase(LAS uchar* lds, const Gemm g, const StaticOrder& S, const Epi& E) {
;     ...
;         for (int t = tb; t < tb + tblk; t += 2) {
;             const bool last = (t == nt - 2);
;             const char* a1 = cA + (size_t)(t + 1) * kstep;
;             const char* a2 = last ? nA : cA + (size_t)(t + 2) * kstep; const char* b2 = last ? nB : cB + (size_t)(t + 2) * kstep;
;             const char* a3 = a2 + kstep; const char* b3 = b2 + kstep;
;             if constexpr (SP2) {
;             PG8_LDB(B0, 0, 0); PG8_LDB(B1, 0, 1); PG8_SCHED; PG8_LDA(At, 0, 0); PG8_STAGE(PG8_SA(1, 1), a1 + hstepA, voffA);
;             PG8_WAIT_V(8); PG8_WAIT_L(0); PG8_BAR; PG8_MMA(0, 0, At, B0); PG8_MMA(0, 1, At, B1); PG8_BAR; PG8_SCHED;
;             PG8_LDA(At, 0, 1); PG8_STAGE(PG8_SB(0, 0), b2, voffB); PG8_STAGE(PG8_SB(0, 1), b2 + hstepB, voffB); PG8_STAGE(PG8_SA(0, 0), a2, voffA);
;             PG8_WAIT_V(8); PG8_WAIT_L(0); PG8_BAR; PG8_MMA(1, 0, At, B0); PG8_MMA(1, 1, At, B1); PG8_BAR; PG8_SCHED;
;             PG8_LDB(B0, 1, 0); PG8_LDB(B1, 1, 1); PG8_SCHED; PG8_LDA(At, 1, 0); PG8_STAGE(PG8_SA(0, 1), a2 + hstepA, voffA);
;             PG8_WAIT_V(8); PG8_WAIT_L(0); PG8_BAR; PG8_MMA(0, 0, At, B0); PG8_MMA(0, 1, At, B1); PG8_BAR; PG8_SCHED;
;             PG8_LDA(At, 1, 1); PG8_STAGE(PG8_SB(1, 0), b3, voffB); PG8_STAGE(PG8_SB(1, 1), b3 + hstepB, voffB); PG8_STAGE(PG8_SA(1, 0), a3, voffA);
;             PG8_WAIT_V(8); PG8_WAIT_L(0); PG8_BAR; PG8_MMA(1, 0, At, B0); PG8_MMA(1, 1, At, B1); PG8_BAR; PG8_SCHED;
	s_add_i32 s16, s41, s23
	v_lshl_add_u64 v[168:169], v[168:169], 0, s[84:85]
	s_mov_b32 m0, s16
	ds_read_b128 v[204:207], v171 offset:49152
	ds_read_b128 v[208:211], v171 offset:50176
	ds_read_b128 v[212:215], v171 offset:51200
	ds_read_b128 v[216:219], v171 offset:52224
	ds_read_b128 v[220:223], v171 offset:53248
	ds_read_b128 v[224:227], v171 offset:54272
	ds_read_b128 v[228:231], v171 offset:55296
	ds_read_b128 v[232:235], v171 offset:56320
	global_load_lds_dwordx4 v[168:169], off
	s_add_i32 m0, s16, 0x2000
	s_add_u32 s4, s4, 0x44080
	v_lshl_add_u64 v[168:169], v[180:181], 0, s[84:85]
	s_addc_u32 s5, s5, 0
	s_add_i32 s16, s42, s23
	global_load_lds_dwordx4 v[168:169], off
	v_lshl_add_u64 v[168:169], s[4:5], 0, v[134:135]
	s_mov_b32 m0, s16
	s_nop 0
	global_load_lds_dwordx4 v[168:169], off
	v_lshl_add_u64 v[168:169], s[4:5], 0, v[130:131]
	s_add_i32 m0, s16, 0x2000
	s_nop 0
	global_load_lds_dwordx4 v[168:169], off
	v_lshl_add_u64 v[168:169], v[236:237], 0, s[84:85]
	s_mov_b32 m0, s29
	s_nop 0
	global_load_lds_dwordx4 v[168:169], off
	v_lshl_add_u64 v[168:169], v[238:239], 0, s[84:85]
	s_mov_b32 m0, s30
	s_nop 0
	global_load_lds_dwordx4 v[168:169], off
	s_waitcnt vmcnt(8)
	s_waitcnt lgkmcnt(0)
	s_barrier
	s_setprio 1
	s_waitcnt lgkmcnt(0)
	v_mfma_f32_16x16x32_bf16 v[62:65], v[164:167], v[204:207], v[62:65]
	v_mfma_f32_16x16x32_bf16 v[58:61], v[176:179], v[204:207], v[58:61]
	v_mfma_f32_16x16x32_bf16 v[54:57], v[164:167], v[212:215], v[54:57]
	v_mfma_f32_16x16x32_bf16 v[46:49], v[176:179], v[212:215], v[46:49]
	v_mfma_f32_16x16x32_bf16 v[38:41], v[164:167], v[220:223], v[38:41]
	v_mfma_f32_16x16x32_bf16 v[30:33], v[176:179], v[220:223], v[30:33]
	v_mfma_f32_16x16x32_bf16 v[22:25], v[164:167], v[228:231], v[22:25]
	v_mfma_f32_16x16x32_bf16 v[14:17], v[176:179], v[228:231], v[14:17]
	v_mfma_f32_16x16x32_bf16 v[62:65], v[172:175], v[208:211], v[62:65]
	v_mfma_f32_16x16x32_bf16 v[58:61], v[184:187], v[208:211], v[58:61]
	v_mfma_f32_16x16x32_bf16 v[54:57], v[172:175], v[216:219], v[54:57]
	v_mfma_f32_16x16x32_bf16 v[46:49], v[184:187], v[216:219], v[46:49]
	v_mfma_f32_16x16x32_bf16 v[38:41], v[172:175], v[224:227], v[38:41]
	v_mfma_f32_16x16x32_bf16 v[30:33], v[184:187], v[224:227], v[30:33]
	v_mfma_f32_16x16x32_bf16 v[22:25], v[172:175], v[232:235], v[22:25]
	v_mfma_f32_16x16x32_bf16 v[14:17], v[184:187], v[232:235], v[14:17]
	s_setprio 0
	s_setprio 1
	v_mfma_f32_16x16x32_bf16 v[50:53], v[188:191], v[204:207], v[50:53]
	v_mfma_f32_16x16x32_bf16 v[42:45], v[196:199], v[204:207], v[42:45]
	v_mfma_f32_16x16x32_bf16 v[34:37], v[188:191], v[212:215], v[34:37]
	v_mfma_f32_16x16x32_bf16 v[26:29], v[196:199], v[212:215], v[26:29]
	v_mfma_f32_16x16x32_bf16 v[18:21], v[188:191], v[220:223], v[18:21]
	v_mfma_f32_16x16x32_bf16 v[10:13], v[196:199], v[220:223], v[10:13]
	v_mfma_f32_16x16x32_bf16 v[6:9], v[188:191], v[228:231], v[6:9]
	v_mfma_f32_16x16x32_bf16 v[2:5], v[196:199], v[228:231], v[2:5]
	v_mfma_f32_16x16x32_bf16 v[50:53], v[192:195], v[208:211], v[50:53]
	v_mfma_f32_16x16x32_bf16 v[42:45], v[200:203], v[208:211], v[42:45]
	v_mfma_f32_16x16x32_bf16 v[34:37], v[192:195], v[216:219], v[34:37]
	v_mfma_f32_16x16x32_bf16 v[26:29], v[200:203], v[216:219], v[26:29]
	v_mfma_f32_16x16x32_bf16 v[18:21], v[192:195], v[224:227], v[18:21]
	v_mfma_f32_16x16x32_bf16 v[10:13], v[200:203], v[224:227], v[10:13]
	v_mfma_f32_16x16x32_bf16 v[6:9], v[192:195], v[232:235], v[6:9]
	v_mfma_f32_16x16x32_bf16 v[2:5], v[200:203], v[232:235], v[2:5]
	s_setprio 0
	s_add_i32 s40, s40, 2
	s_add_u32 s38, s38, 0x100
	s_addc_u32 s39, s39, 0
	s_cmp_gt_u32 s40, 13
	s_mov_b64 s[16:17], s[18:19]
	s_add_u32 s18, s16, 0x100
	s_addc_u32 s19, s17, 0
	s_add_i32 s41, 0, 0x10000
	s_cmp_eq_u32 s40, 12
	s_cselect_b32 s21, s7, s19
	s_cselect_b32 s20, s6, s18
	s_cselect_b32 s5, s15, s39
	s_cselect_b32 s4, s14, s38
	s_add_i32 s42, 0, 0x14000
	v_add_u32_e32 v168, s41, v139
.LBB0_345:
	s_barrier
	ds_read_b128 v[164:167], v168
	ds_read_b128 v[172:175], v168 offset:1024
	ds_read_b128 v[176:179], v168 offset:2048
	ds_read_b128 v[184:187], v168 offset:3072
	v_add_u32_e32 v168, s42, v139
	ds_read_b128 v[188:191], v168
	ds_read_b128 v[192:195], v168 offset:1024
	ds_read_b128 v[196:199], v168 offset:2048
	ds_read_b128 v[200:203], v168 offset:3072
	v_lshl_add_u64 v[168:169], s[16:17], 0, v[160:161]
	s_add_i32 m0, s25, 0xc000
	ds_read_b128 v[204:207], v171
	ds_read_b128 v[208:211], v171 offset:1024
	ds_read_b128 v[212:215], v171 offset:2048
	ds_read_b128 v[216:219], v171 offset:3072
	ds_read_b128 v[220:223], v171 offset:4096
	ds_read_b128 v[224:227], v171 offset:5120
	ds_read_b128 v[228:231], v171 offset:6144
	ds_read_b128 v[232:235], v171 offset:7168
	global_load_lds_dwordx4 v[168:169], off
	v_lshl_add_u64 v[168:169], s[16:17], 0, v[162:163]
	s_add_i32 m0, s25, 0xe000
	s_nop 0
	global_load_lds_dwordx4 v[168:169], off
	s_waitcnt vmcnt(8)
	s_waitcnt lgkmcnt(0)
	s_barrier
; #define PG8_STAGE(bufoff, gbase, voff) do { _Pragma("unroll") for (int _i = 0; _i < 2; ++_i) \
;         __builtin_amdgcn_global_load_lds((const unsigned*)((const char*)(gbase) + (voff)[_i]), (LAS unsigned*)(lds + (bufoff) + ldsw + _i * 8192), 16, 0, 0); } while (0)
; #define PG8_LDA(dst, b, h) do { _Pragma("unroll") for (int m = 0; m < 4; ++m) _Pragma("unroll") for (int k = 0; k < 2; ++k) dst[m][k] = *(const LAS bf16x8*)(lds + PG8_SA(b, h) + aoff + m * 2048 + k * 1024); } while (0)
; #define PG8_MMA(ai, bj, At, Bt) do { __builtin_amdgcn_s_setprio(1); _Pragma("unroll") for (int m = 0; m < 4; ++m) _Pragma("unroll") for (int n = 0; n < 2; ++n) _Pragma("unroll") for (int k = 0; k < 2; ++k) \
;         acc[ai][bj][m][n] = __builtin_amdgcn_mfma_f32_16x16x32_bf16(Bt[n][k], At[m][k], acc[ai][bj][m][n], 0, 0, 0); __builtin_amdgcn_s_setprio(0); } while (0)
; #define PG8_WAIT_V(n) asm volatile("s_waitcnt vmcnt(" #n ")" ::: "memory")
; #define PG8_WAIT_L(n) asm volatile("s_waitcnt lgkmcnt(" #n ")" ::: "memory")
; #define PG8_BAR __builtin_amdgcn_s_barrier()
; #define PG8_SCHED __builtin_amdgcn_sched_barrier(0)
; template <class Epi, bool ALIGN_EPI = PG8_ALIGN, bool SP2 = PG8_SP2>
; __device__ __forceinline__ void gemm_phase(LAS uchar* lds, const Gemm g, const StaticOrder& S, const Epi& E) {
;     ...
;             PG8_WAIT_V(8); PG8_WAIT_L(0); PG8_BAR; PG8_MMA(0, 0, At, B0); PG8_MMA(0, 1, At, B1); PG8_BAR; PG8_SCHED;
;             PG8_LDA(At, 0, 1); PG8_STAGE(PG8_SB(0, 0), b2, voffB); PG8_STAGE(PG8_SB(0, 1), b2 + hstepB, voffB); PG8_STAGE(PG8_SA(0, 0), a2, voffA);
;             PG8_WAIT_V(8); PG8_WAIT_L(0); PG8_BAR; PG8_MMA(1, 0, At, B0); PG8_MMA(1, 1, At, B1); PG8_BAR; PG8_SCHED;
	s_setprio 1
	s_waitcnt lgkmcnt(0)
	v_mfma_f32_16x16x32_bf16 v[126:129], v[164:167], v[204:207], v[126:129]
	v_mfma_f32_16x16x32_bf16 v[122:125], v[176:179], v[204:207], v[122:125]
	v_mfma_f32_16x16x32_bf16 v[118:121], v[164:167], v[212:215], v[118:121]
	v_mfma_f32_16x16x32_bf16 v[110:113], v[176:179], v[212:215], v[110:113]
	v_mfma_f32_16x16x32_bf16 v[102:105], v[164:167], v[220:223], v[102:105]
	v_mfma_f32_16x16x32_bf16 v[94:97], v[176:179], v[220:223], v[94:97]
	v_mfma_f32_16x16x32_bf16 v[86:89], v[164:167], v[228:231], v[86:89]
	v_mfma_f32_16x16x32_bf16 v[78:81], v[176:179], v[228:231], v[78:81]
	v_mfma_f32_16x16x32_bf16 v[126:129], v[172:175], v[208:211], v[126:129]
	v_mfma_f32_16x16x32_bf16 v[122:125], v[184:187], v[208:211], v[122:125]
	v_mfma_f32_16x16x32_bf16 v[118:121], v[172:175], v[216:219], v[118:121]
	v_mfma_f32_16x16x32_bf16 v[110:113], v[184:187], v[216:219], v[110:113]
	v_mfma_f32_16x16x32_bf16 v[102:105], v[172:175], v[224:227], v[102:105]
	v_mfma_f32_16x16x32_bf16 v[94:97], v[184:187], v[224:227], v[94:97]
	v_mfma_f32_16x16x32_bf16 v[86:89], v[172:175], v[232:235], v[86:89]
	v_mfma_f32_16x16x32_bf16 v[78:81], v[184:187], v[232:235], v[78:81]
	s_setprio 0
	s_setprio 1
	v_mfma_f32_16x16x32_bf16 v[114:117], v[188:191], v[204:207], v[114:117]
	v_mfma_f32_16x16x32_bf16 v[106:109], v[196:199], v[204:207], v[106:109]
	v_mfma_f32_16x16x32_bf16 v[98:101], v[188:191], v[212:215], v[98:101]
	v_mfma_f32_16x16x32_bf16 v[90:93], v[196:199], v[212:215], v[90:93]
	v_mfma_f32_16x16x32_bf16 v[82:85], v[188:191], v[220:223], v[82:85]
	v_mfma_f32_16x16x32_bf16 v[74:77], v[196:199], v[220:223], v[74:77]
	v_mfma_f32_16x16x32_bf16 v[70:73], v[188:191], v[228:231], v[70:73]
	v_mfma_f32_16x16x32_bf16 v[66:69], v[196:199], v[228:231], v[66:69]
	v_mfma_f32_16x16x32_bf16 v[114:117], v[192:195], v[208:211], v[114:117]
	v_mfma_f32_16x16x32_bf16 v[106:109], v[200:203], v[208:211], v[106:109]
	v_mfma_f32_16x16x32_bf16 v[98:101], v[192:195], v[216:219], v[98:101]
	v_mfma_f32_16x16x32_bf16 v[90:93], v[200:203], v[216:219], v[90:93]
	v_mfma_f32_16x16x32_bf16 v[82:85], v[192:195], v[224:227], v[82:85]
	v_mfma_f32_16x16x32_bf16 v[74:77], v[200:203], v[224:227], v[74:77]
	v_mfma_f32_16x16x32_bf16 v[70:73], v[192:195], v[232:235], v[70:73]
	v_mfma_f32_16x16x32_bf16 v[66:69], v[200:203], v[232:235], v[66:69]
	s_setprio 0
	s_barrier
	s_add_i32 s16, s41, s23
	v_lshl_add_u64 v[168:169], s[4:5], 0, v[134:135]
	s_mov_b32 m0, s16
	ds_read_b128 v[204:207], v171 offset:16384
	ds_read_b128 v[208:211], v171 offset:17408
	ds_read_b128 v[212:215], v171 offset:18432
	ds_read_b128 v[216:219], v171 offset:19456
	ds_read_b128 v[220:223], v171 offset:20480
	ds_read_b128 v[224:227], v171 offset:21504
	ds_read_b128 v[228:231], v171 offset:22528
	ds_read_b128 v[232:235], v171 offset:23552
	global_load_lds_dwordx4 v[168:169], off
	s_add_i32 m0, s16, 0x2000
	s_add_u32 s16, s4, 0x44000
	v_lshl_add_u64 v[180:181], s[4:5], 0, v[130:131]
	s_addc_u32 s17, s5, 0
	s_add_i32 s41, s42, s23
	global_load_lds_dwordx4 v[180:181], off
	v_lshl_add_u64 v[236:237], s[16:17], 0, v[134:135]
	s_mov_b32 m0, s41
	v_lshl_add_u64 v[238:239], s[20:21], 0, v[132:133]
	global_load_lds_dwordx4 v[236:237], off
	v_lshl_add_u64 v[236:237], s[16:17], 0, v[130:131]
	s_add_i32 m0, s41, 0x2000
	s_nop 0
	global_load_lds_dwordx4 v[236:237], off
	v_lshl_add_u64 v[236:237], s[20:21], 0, v[156:157]
	s_mov_b32 m0, s25
	s_nop 0
	global_load_lds_dwordx4 v[236:237], off
	s_mov_b32 m0, s26
	s_nop 0
	global_load_lds_dwordx4 v[238:239], off
	s_waitcnt vmcnt(8)
	s_waitcnt lgkmcnt(0)
	s_barrier
	s_setprio 1
	s_waitcnt lgkmcnt(0)
	v_mfma_f32_16x16x32_bf16 v[62:65], v[164:167], v[204:207], v[62:65]
	v_mfma_f32_16x16x32_bf16 v[58:61], v[176:179], v[204:207], v[58:61]
	v_mfma_f32_16x16x32_bf16 v[54:57], v[164:167], v[212:215], v[54:57]
	v_mfma_f32_16x16x32_bf16 v[46:49], v[176:179], v[212:215], v[46:49]
	v_mfma_f32_16x16x32_bf16 v[38:41], v[164:167], v[220:223], v[38:41]
	v_mfma_f32_16x16x32_bf16 v[30:33], v[176:179], v[220:223], v[30:33]
	v_mfma_f32_16x16x32_bf16 v[22:25], v[164:167], v[228:231], v[22:25]
	v_mfma_f32_16x16x32_bf16 v[14:17], v[176:179], v[228:231], v[14:17]
	v_mfma_f32_16x16x32_bf16 v[62:65], v[172:175], v[208:211], v[62:65]
	v_mfma_f32_16x16x32_bf16 v[58:61], v[184:187], v[208:211], v[58:61]
	v_mfma_f32_16x16x32_bf16 v[54:57], v[172:175], v[216:219], v[54:57]
	v_mfma_f32_16x16x32_bf16 v[46:49], v[184:187], v[216:219], v[46:49]
	v_mfma_f32_16x16x32_bf16 v[38:41], v[172:175], v[224:227], v[38:41]
	v_mfma_f32_16x16x32_bf16 v[30:33], v[184:187], v[224:227], v[30:33]
	v_mfma_f32_16x16x32_bf16 v[22:25], v[172:175], v[232:235], v[22:25]
	v_mfma_f32_16x16x32_bf16 v[14:17], v[184:187], v[232:235], v[14:17]
	s_setprio 0
	s_setprio 1
	v_mfma_f32_16x16x32_bf16 v[50:53], v[188:191], v[204:207], v[50:53]
	v_mfma_f32_16x16x32_bf16 v[42:45], v[196:199], v[204:207], v[42:45]
	v_mfma_f32_16x16x32_bf16 v[34:37], v[188:191], v[212:215], v[34:37]
	v_mfma_f32_16x16x32_bf16 v[26:29], v[196:199], v[212:215], v[26:29]
	v_mfma_f32_16x16x32_bf16 v[18:21], v[188:191], v[220:223], v[18:21]
	v_mfma_f32_16x16x32_bf16 v[10:13], v[196:199], v[220:223], v[10:13]
	v_mfma_f32_16x16x32_bf16 v[6:9], v[188:191], v[228:231], v[6:9]
	v_mfma_f32_16x16x32_bf16 v[2:5], v[196:199], v[228:231], v[2:5]
	v_mfma_f32_16x16x32_bf16 v[50:53], v[192:195], v[208:211], v[50:53]
	v_mfma_f32_16x16x32_bf16 v[42:45], v[200:203], v[208:211], v[42:45]
	v_mfma_f32_16x16x32_bf16 v[34:37], v[192:195], v[216:219], v[34:37]
	v_mfma_f32_16x16x32_bf16 v[26:29], v[200:203], v[216:219], v[26:29]
	v_mfma_f32_16x16x32_bf16 v[18:21], v[192:195], v[224:227], v[18:21]
	v_mfma_f32_16x16x32_bf16 v[10:13], v[200:203], v[224:227], v[10:13]
	v_mfma_f32_16x16x32_bf16 v[6:9], v[192:195], v[232:235], v[6:9]
	v_mfma_f32_16x16x32_bf16 v[2:5], v[200:203], v[232:235], v[2:5]
	s_setprio 0
	s_barrier
; #define PG8_STAGE(bufoff, gbase, voff) do { _Pragma("unroll") for (int _i = 0; _i < 2; ++_i) \
;         __builtin_amdgcn_global_load_lds((const unsigned*)((const char*)(gbase) + (voff)[_i]), (LAS unsigned*)(lds + (bufoff) + ldsw + _i * 8192), 16, 0, 0); } while (0)
; #define PG8_LDA(dst, b, h) do { _Pragma("unroll") for (int m = 0; m < 4; ++m) _Pragma("unroll") for (int k = 0; k < 2; ++k) dst[m][k] = *(const LAS bf16x8*)(lds + PG8_SA(b, h) + aoff + m * 2048 + k * 1024); } while (0)
; #define PG8_LDB(dst, b, h) do { _Pragma("unroll") for (int n = 0; n < 2; ++n) _Pragma("unroll") for (int k = 0; k < 2; ++k) dst[n][k] = *(const LAS bf16x8*)(lds + PG8_SB(b, h) + boff + n * 2048 + k * 1024); } while (0)
; #define PG8_MMA(ai, bj, At, Bt) do { __builtin_amdgcn_s_setprio(1); _Pragma("unroll") for (int m = 0; m < 4; ++m) _Pragma("unroll") for (int n = 0; n < 2; ++n) _Pragma("unroll") for (int k = 0; k < 2; ++k) \
;         acc[ai][bj][m][n] = __builtin_amdgcn_mfma_f32_16x16x32_bf16(Bt[n][k], At[m][k], acc[ai][bj][m][n], 0, 0, 0); __builtin_amdgcn_s_setprio(0); } while (0)
; #define PG8_WAIT_V(n) asm volatile("s_waitcnt vmcnt(" #n ")" ::: "memory")
; #define PG8_WAIT_L(n) asm volatile("s_waitcnt lgkmcnt(" #n ")" ::: "memory")
; #define PG8_BAR __builtin_amdgcn_s_barrier()
; #define PG8_SCHED __builtin_amdgcn_sched_barrier(0)
; template <class Epi, bool ALIGN_EPI = PG8_ALIGN, bool SP2 = PG8_SP2>
; __device__ __forceinline__ void gemm_phase(LAS uchar* lds, const Gemm g, const StaticOrder& S, const Epi& E) {
;     ...
;             PG8_LDB(B0, 1, 0); PG8_LDB(B1, 1, 1); PG8_SCHED; PG8_LDA(At, 1, 0); PG8_STAGE(PG8_SA(0, 1), a2 + hstepA, voffA);
;             PG8_WAIT_V(8); PG8_WAIT_L(0); PG8_BAR; PG8_MMA(0, 0, At, B0); PG8_MMA(0, 1, At, B1); PG8_BAR; PG8_SCHED;
	s_add_i32 s41, 0, 0x18000
	s_add_i32 s42, 0, 0x1c000
	v_add_u32_e32 v184, s41, v139
	v_add_u32_e32 v200, s42, v139
	ds_read_b128 v[164:167], v184
	ds_read_b128 v[172:175], v184 offset:1024
	ds_read_b128 v[176:179], v184 offset:2048
	ds_read_b128 v[184:187], v184 offset:3072
	ds_read_b128 v[188:191], v200
	ds_read_b128 v[192:195], v200 offset:1024
	ds_read_b128 v[196:199], v200 offset:2048
	ds_read_b128 v[200:203], v200 offset:3072
	s_add_u32 s16, s20, 0x44000
	s_addc_u32 s17, s21, 0
	s_mov_b32 m0, s27
	v_lshl_add_u64 v[240:241], s[16:17], 0, v[156:157]
	ds_read_b128 v[204:207], v171 offset:32768
	ds_read_b128 v[208:211], v171 offset:33792
	ds_read_b128 v[212:215], v171 offset:34816
	ds_read_b128 v[216:219], v171 offset:35840
	ds_read_b128 v[220:223], v171 offset:36864
	ds_read_b128 v[224:227], v171 offset:37888
	ds_read_b128 v[228:231], v171 offset:38912
	ds_read_b128 v[232:235], v171 offset:39936
	global_load_lds_dwordx4 v[240:241], off
	v_lshl_add_u64 v[240:241], s[16:17], 0, v[132:133]
	s_mov_b32 m0, s28
	s_nop 0
	global_load_lds_dwordx4 v[240:241], off
	s_waitcnt vmcnt(8)
	s_waitcnt lgkmcnt(0)
	s_barrier
	s_setprio 1
	s_waitcnt lgkmcnt(0)
	v_mfma_f32_16x16x32_bf16 v[126:129], v[164:167], v[204:207], v[126:129]
	v_mfma_f32_16x16x32_bf16 v[122:125], v[176:179], v[204:207], v[122:125]
	v_mfma_f32_16x16x32_bf16 v[118:121], v[164:167], v[212:215], v[118:121]
	v_mfma_f32_16x16x32_bf16 v[110:113], v[176:179], v[212:215], v[110:113]
	v_mfma_f32_16x16x32_bf16 v[102:105], v[164:167], v[220:223], v[102:105]
	v_mfma_f32_16x16x32_bf16 v[94:97], v[176:179], v[220:223], v[94:97]
	v_mfma_f32_16x16x32_bf16 v[86:89], v[164:167], v[228:231], v[86:89]
	v_mfma_f32_16x16x32_bf16 v[78:81], v[176:179], v[228:231], v[78:81]
	v_mfma_f32_16x16x32_bf16 v[126:129], v[172:175], v[208:211], v[126:129]
	v_mfma_f32_16x16x32_bf16 v[122:125], v[184:187], v[208:211], v[122:125]
	v_mfma_f32_16x16x32_bf16 v[118:121], v[172:175], v[216:219], v[118:121]
	v_mfma_f32_16x16x32_bf16 v[110:113], v[184:187], v[216:219], v[110:113]
	v_mfma_f32_16x16x32_bf16 v[102:105], v[172:175], v[224:227], v[102:105]
	v_mfma_f32_16x16x32_bf16 v[94:97], v[184:187], v[224:227], v[94:97]
	v_mfma_f32_16x16x32_bf16 v[86:89], v[172:175], v[232:235], v[86:89]
	v_mfma_f32_16x16x32_bf16 v[78:81], v[184:187], v[232:235], v[78:81]
	s_setprio 0
	s_setprio 1
	v_mfma_f32_16x16x32_bf16 v[114:117], v[188:191], v[204:207], v[114:117]
	v_mfma_f32_16x16x32_bf16 v[106:109], v[196:199], v[204:207], v[106:109]
	v_mfma_f32_16x16x32_bf16 v[98:101], v[188:191], v[212:215], v[98:101]
	v_mfma_f32_16x16x32_bf16 v[90:93], v[196:199], v[212:215], v[90:93]
	v_mfma_f32_16x16x32_bf16 v[82:85], v[188:191], v[220:223], v[82:85]
	v_mfma_f32_16x16x32_bf16 v[74:77], v[196:199], v[220:223], v[74:77]
	v_mfma_f32_16x16x32_bf16 v[70:73], v[188:191], v[228:231], v[70:73]
	v_mfma_f32_16x16x32_bf16 v[66:69], v[196:199], v[228:231], v[66:69]
	v_mfma_f32_16x16x32_bf16 v[114:117], v[192:195], v[208:211], v[114:117]
	v_mfma_f32_16x16x32_bf16 v[106:109], v[200:203], v[208:211], v[106:109]
	v_mfma_f32_16x16x32_bf16 v[98:101], v[192:195], v[216:219], v[98:101]
	v_mfma_f32_16x16x32_bf16 v[90:93], v[200:203], v[216:219], v[90:93]
	v_mfma_f32_16x16x32_bf16 v[82:85], v[192:195], v[224:227], v[82:85]
	v_mfma_f32_16x16x32_bf16 v[74:77], v[200:203], v[224:227], v[74:77]
	v_mfma_f32_16x16x32_bf16 v[70:73], v[192:195], v[232:235], v[70:73]
	v_mfma_f32_16x16x32_bf16 v[66:69], v[200:203], v[232:235], v[66:69]
	s_setprio 0
	s_barrier
; #define PG8_STAGE(bufoff, gbase, voff) do { _Pragma("unroll") for (int _i = 0; _i < 2; ++_i) \
;         __builtin_amdgcn_global_load_lds((const unsigned*)((const char*)(gbase) + (voff)[_i]), (LAS unsigned*)(lds + (bufoff) + ldsw + _i * 8192), 16, 0, 0); } while (0)
; #define PG8_LDA(dst, b, h) do { _Pragma("unroll") for (int m = 0; m < 4; ++m) _Pragma("unroll") for (int k = 0; k < 2; ++k) dst[m][k] = *(const LAS bf16x8*)(lds + PG8_SA(b, h) + aoff + m * 2048 + k * 1024); } while (0)
; #define PG8_MMA(ai, bj, At, Bt) do { __builtin_amdgcn_s_setprio(1); _Pragma("unroll") for (int m = 0; m < 4; ++m) _Pragma("unroll") for (int n = 0; n < 2; ++n) _Pragma("unroll") for (int k = 0; k < 2; ++k) \
;         acc[ai][bj][m][n] = __builtin_amdgcn_mfma_f32_16x16x32_bf16(Bt[n][k], At[m][k], acc[ai][bj][m][n], 0, 0, 0); __builtin_amdgcn_s_setprio(0); } while (0)
; #define PG8_WAIT_V(n) asm volatile("s_waitcnt vmcnt(" #n ")" ::: "memory")
; #define PG8_WAIT_L(n) asm volatile("s_waitcnt lgkmcnt(" #n ")" ::: "memory")
; #define PG8_BAR __builtin_amdgcn_s_barrier()
; #define PG8_SCHED __builtin_amdgcn_sched_barrier(0)
; template <class Epi, bool ALIGN_EPI = PG8_ALIGN, bool SP2 = PG8_SP2>
; __device__ __forceinline__ void gemm_phase(LAS uchar* lds, const Gemm g, const StaticOrder& S, const Epi& E) {
;     ...
;             PG8_WAIT_V(8); PG8_WAIT_L(0); PG8_BAR; PG8_MMA(0, 0, At, B0); PG8_MMA(0, 1, At, B1); PG8_BAR; PG8_SCHED;
;             PG8_LDA(At, 1, 1); PG8_STAGE(PG8_SB(1, 0), b3, voffB); PG8_STAGE(PG8_SB(1, 1), b3 + hstepB, voffB); PG8_STAGE(PG8_SA(1, 0), a3, voffA);
;             PG8_WAIT_V(8); PG8_WAIT_L(0); PG8_BAR; PG8_MMA(1, 0, At, B0); PG8_MMA(1, 1, At, B1); PG8_BAR; PG8_SCHED;
;     __device__ __forceinline__ void operator()(const f32x4 (&acc)[2][2][4][2], const pg8::Unit& u, int wr, int wc, int fr, int fq, int) const {
;         const int row0 = u.pm * 256 + wr * 64 + fr;
;         if (u.pn < 24) {
	s_add_i32 s16, s41, s23
	v_lshl_add_u64 v[168:169], v[168:169], 0, s[84:85]
	s_mov_b32 m0, s16
	ds_read_b128 v[204:207], v171 offset:49152
	ds_read_b128 v[208:211], v171 offset:50176
	ds_read_b128 v[212:215], v171 offset:51200
	ds_read_b128 v[216:219], v171 offset:52224
	ds_read_b128 v[220:223], v171 offset:53248
	ds_read_b128 v[224:227], v171 offset:54272
	ds_read_b128 v[228:231], v171 offset:55296
	ds_read_b128 v[232:235], v171 offset:56320
	global_load_lds_dwordx4 v[168:169], off
	s_add_i32 m0, s16, 0x2000
	s_add_u32 s4, s4, 0x44080
	v_lshl_add_u64 v[168:169], v[180:181], 0, s[84:85]
	s_addc_u32 s5, s5, 0
	s_add_i32 s16, s42, s23
	global_load_lds_dwordx4 v[168:169], off
	v_lshl_add_u64 v[168:169], s[4:5], 0, v[134:135]
	s_mov_b32 m0, s16
	s_nop 0
	global_load_lds_dwordx4 v[168:169], off
	v_lshl_add_u64 v[168:169], s[4:5], 0, v[130:131]
	s_add_i32 m0, s16, 0x2000
	s_nop 0
	global_load_lds_dwordx4 v[168:169], off
	v_lshl_add_u64 v[168:169], v[236:237], 0, s[84:85]
	s_mov_b32 m0, s29
	s_nop 0
	global_load_lds_dwordx4 v[168:169], off
	v_lshl_add_u64 v[168:169], v[238:239], 0, s[84:85]
	s_mov_b32 m0, s30
	s_nop 0
	global_load_lds_dwordx4 v[168:169], off
	s_waitcnt vmcnt(8)
	s_waitcnt lgkmcnt(0)
	s_barrier
	s_setprio 1
	s_waitcnt lgkmcnt(0)
	v_mfma_f32_16x16x32_bf16 v[62:65], v[164:167], v[204:207], v[62:65]
	v_mfma_f32_16x16x32_bf16 v[58:61], v[176:179], v[204:207], v[58:61]
	v_mfma_f32_16x16x32_bf16 v[54:57], v[164:167], v[212:215], v[54:57]
	v_mfma_f32_16x16x32_bf16 v[46:49], v[176:179], v[212:215], v[46:49]
	v_mfma_f32_16x16x32_bf16 v[38:41], v[164:167], v[220:223], v[38:41]
	v_mfma_f32_16x16x32_bf16 v[30:33], v[176:179], v[220:223], v[30:33]
	v_mfma_f32_16x16x32_bf16 v[22:25], v[164:167], v[228:231], v[22:25]
	v_mfma_f32_16x16x32_bf16 v[14:17], v[176:179], v[228:231], v[14:17]
	v_mfma_f32_16x16x32_bf16 v[62:65], v[172:175], v[208:211], v[62:65]
	v_mfma_f32_16x16x32_bf16 v[58:61], v[184:187], v[208:211], v[58:61]
	v_mfma_f32_16x16x32_bf16 v[54:57], v[172:175], v[216:219], v[54:57]
	v_mfma_f32_16x16x32_bf16 v[46:49], v[184:187], v[216:219], v[46:49]
	v_mfma_f32_16x16x32_bf16 v[38:41], v[172:175], v[224:227], v[38:41]
	v_mfma_f32_16x16x32_bf16 v[30:33], v[184:187], v[224:227], v[30:33]
	v_mfma_f32_16x16x32_bf16 v[22:25], v[172:175], v[232:235], v[22:25]
	v_mfma_f32_16x16x32_bf16 v[14:17], v[184:187], v[232:235], v[14:17]
	s_setprio 0
	s_setprio 1
	v_mfma_f32_16x16x32_bf16 v[50:53], v[188:191], v[204:207], v[50:53]
	v_mfma_f32_16x16x32_bf16 v[42:45], v[196:199], v[204:207], v[42:45]
	v_mfma_f32_16x16x32_bf16 v[34:37], v[188:191], v[212:215], v[34:37]
	v_mfma_f32_16x16x32_bf16 v[26:29], v[196:199], v[212:215], v[26:29]
	v_mfma_f32_16x16x32_bf16 v[18:21], v[188:191], v[220:223], v[18:21]
	v_mfma_f32_16x16x32_bf16 v[10:13], v[196:199], v[220:223], v[10:13]
	v_mfma_f32_16x16x32_bf16 v[6:9], v[188:191], v[228:231], v[6:9]
	v_mfma_f32_16x16x32_bf16 v[2:5], v[196:199], v[228:231], v[2:5]
	v_mfma_f32_16x16x32_bf16 v[50:53], v[192:195], v[208:211], v[50:53]
	v_mfma_f32_16x16x32_bf16 v[42:45], v[200:203], v[208:211], v[42:45]
	v_mfma_f32_16x16x32_bf16 v[34:37], v[192:195], v[216:219], v[34:37]
	v_mfma_f32_16x16x32_bf16 v[26:29], v[200:203], v[216:219], v[26:29]
	v_mfma_f32_16x16x32_bf16 v[18:21], v[192:195], v[224:227], v[18:21]
	v_mfma_f32_16x16x32_bf16 v[10:13], v[200:203], v[224:227], v[10:13]
	v_mfma_f32_16x16x32_bf16 v[6:9], v[192:195], v[232:235], v[6:9]
	v_mfma_f32_16x16x32_bf16 v[2:5], v[200:203], v[232:235], v[2:5]
	s_setprio 0
	s_add_i32 s40, s40, 2
	s_add_u32 s38, s38, 0x100
	s_addc_u32 s39, s39, 0
	s_cmp_gt_u32 s40, 13
	s_mov_b64 s[16:17], s[18:19]
	s_cbranch_scc1 .Lrot_exit_345
	s_add_u32 s18, s16, 0x100
	s_addc_u32 s19, s17, 0
	s_add_i32 s41, 0, 0x10000
	s_cmp_eq_u32 s40, 12
	s_cselect_b32 s21, s7, s19
	s_cselect_b32 s20, s6, s18
	s_cselect_b32 s5, s15, s39
	s_cselect_b32 s4, s14, s38
	s_add_i32 s42, 0, 0x14000
	v_add_u32_e32 v168, s41, v139
	s_branch .LBB0_345
.Lrot_exit_345:
	s_barrier
	s_mov_b32 s97, 0
	s_and_b64 vcc, exec, s[10:11]
	s_cbranch_vccnz .LBB0_350
	v_lshl_add_u32 v164, s37, 8, v1
	s_cmp_gt_i32 s36, 23
	s_mov_b64 s[4:5], -1
	s_cbranch_scc1 .LBB0_351

; #define PG8_STAGE(bufoff, gbase, voff) do { _Pragma("unroll") for (int _i = 0; _i < 2; ++_i) \
;         __builtin_amdgcn_global_load_lds((const unsigned*)((const char*)(gbase) + (voff)[_i]), (LAS unsigned*)(lds + (bufoff) + ldsw + _i * 8192), 16, 0, 0); } while (0)
; #define PG8_LDA(dst, b, h) do { _Pragma("unroll") for (int m = 0; m < 4; ++m) _Pragma("unroll") for (int k = 0; k < 2; ++k) dst[m][k] = *(const LAS bf16x8*)(lds + PG8_SA(b, h) + aoff + m * 2048 + k * 1024); } while (0)
; #define PG8_LDB(dst, b, h) do { _Pragma("unroll") for (int n = 0; n < 2; ++n) _Pragma("unroll") for (int k = 0; k < 2; ++k) dst[n][k] = *(const LAS bf16x8*)(lds + PG8_SB(b, h) + boff + n * 2048 + k * 1024); } while (0)
; #define PG8_MMA(ai, bj, At, Bt) do { __builtin_amdgcn_s_setprio(1); _Pragma("unroll") for (int m = 0; m < 4; ++m) _Pragma("unroll") for (int n = 0; n < 2; ++n) _Pragma("unroll") for (int k = 0; k < 2; ++k) \
;         acc[ai][bj][m][n] = __builtin_amdgcn_mfma_f32_16x16x32_bf16(Bt[n][k], At[m][k], acc[ai][bj][m][n], 0, 0, 0); __builtin_amdgcn_s_setprio(0); } while (0)
; #define PG8_WAIT_V(n) asm volatile("s_waitcnt vmcnt(" #n ")" ::: "memory")
; #define PG8_WAIT_L(n) asm volatile("s_waitcnt lgkmcnt(" #n ")" ::: "memory")
; #define PG8_BAR __builtin_amdgcn_s_barrier()
; #define PG8_SCHED __builtin_amdgcn_sched_barrier(0)
; template <class Epi, bool ALIGN_EPI = PG8_ALIGN, bool SP2 = PG8_SP2>
; __device__ __forceinline__ void gemm_phase(LAS uchar* lds, const Gemm g, const StaticOrder& S, const Epi& E) {
;     ...
;             const char* a1 = cA + (size_t)(t + 1) * kstep;
;             const char* a2 = last ? nA : cA + (size_t)(t + 2) * kstep; const char* b2 = last ? nB : cB + (size_t)(t + 2) * kstep;
;             const char* a3 = a2 + kstep; const char* b3 = b2 + kstep;
;             if constexpr (SP2) {
;             PG8_LDB(B0, 0, 0); PG8_LDB(B1, 0, 1); PG8_SCHED; PG8_LDA(At, 0, 0); PG8_STAGE(PG8_SA(1, 1), a1 + hstepA, voffA);
;             PG8_WAIT_V(8); PG8_WAIT_L(0); PG8_BAR; PG8_MMA(0, 0, At, B0); PG8_MMA(0, 1, At, B1); PG8_BAR; PG8_SCHED;
;             PG8_LDA(At, 0, 1); PG8_STAGE(PG8_SB(0, 0), b2, voffB); PG8_STAGE(PG8_SB(0, 1), b2 + hstepB, voffB); PG8_STAGE(PG8_SA(0, 0), a2, voffA);
;             PG8_WAIT_V(8); PG8_WAIT_L(0); PG8_BAR; PG8_MMA(1, 0, At, B0); PG8_MMA(1, 1, At, B1); PG8_BAR; PG8_SCHED;
.LBB0_668:
	s_add_u32 s36, s14, 0x100
	s_addc_u32 s37, s15, 0
	s_mov_b32 s38, -2
	s_add_u32 s14, s12, 0x100
	s_addc_u32 s15, s13, 0
	s_add_i32 s39, 0, 0x10000
	s_cmp_eq_u32 s38, 12
	s_cselect_b32 s19, s5, s15
	s_cselect_b32 s18, s4, s14
	s_cselect_b32 s17, s11, s37
	s_cselect_b32 s16, s10, s36
	s_add_i32 s40, 0, 0x14000
	v_add_u32_e32 v174, s39, v139
	v_add_u32_e32 v192, s40, v139
	ds_read_b128 v[160:163], v174
	ds_read_b128 v[164:167], v174 offset:1024
	ds_read_b128 v[168:171], v174 offset:2048
	ds_read_b128 v[174:177], v174 offset:3072
	ds_read_b128 v[178:181], v192
	ds_read_b128 v[184:187], v192 offset:1024
	ds_read_b128 v[188:191], v192 offset:2048
	ds_read_b128 v[192:195], v192 offset:3072
	v_lshl_add_u64 v[228:229], s[12:13], 0, v[156:157]
	s_add_i32 m0, s23, 0xc000
	ds_read_b128 v[196:199], v173
	ds_read_b128 v[200:203], v173 offset:1024
	ds_read_b128 v[204:207], v173 offset:2048
	ds_read_b128 v[208:211], v173 offset:3072
	ds_read_b128 v[212:215], v173 offset:4096
	ds_read_b128 v[216:219], v173 offset:5120
	ds_read_b128 v[220:223], v173 offset:6144
	ds_read_b128 v[224:227], v173 offset:7168
	global_load_lds_dwordx4 v[228:229], off
	v_lshl_add_u64 v[228:229], s[12:13], 0, v[158:159]
	s_add_i32 m0, s23, 0xe000
	s_nop 0
	global_load_lds_dwordx4 v[228:229], off
	s_waitcnt vmcnt(8)
	s_waitcnt lgkmcnt(0)
	s_barrier
	s_setprio 1
	s_waitcnt lgkmcnt(0)
	v_mfma_f32_16x16x32_bf16 v[126:129], v[160:163], v[196:199], 0
	v_mfma_f32_16x16x32_bf16 v[122:125], v[168:171], v[196:199], 0
	v_mfma_f32_16x16x32_bf16 v[118:121], v[160:163], v[204:207], 0
	v_mfma_f32_16x16x32_bf16 v[110:113], v[168:171], v[204:207], 0
	v_mfma_f32_16x16x32_bf16 v[102:105], v[160:163], v[212:215], 0
	v_mfma_f32_16x16x32_bf16 v[94:97], v[168:171], v[212:215], 0
	v_mfma_f32_16x16x32_bf16 v[86:89], v[160:163], v[220:223], 0
	v_mfma_f32_16x16x32_bf16 v[78:81], v[168:171], v[220:223], 0
	v_mfma_f32_16x16x32_bf16 v[126:129], v[164:167], v[200:203], v[126:129]
	v_mfma_f32_16x16x32_bf16 v[122:125], v[174:177], v[200:203], v[122:125]
	v_mfma_f32_16x16x32_bf16 v[118:121], v[164:167], v[208:211], v[118:121]
	v_mfma_f32_16x16x32_bf16 v[110:113], v[174:177], v[208:211], v[110:113]
	v_mfma_f32_16x16x32_bf16 v[102:105], v[164:167], v[216:219], v[102:105]
	v_mfma_f32_16x16x32_bf16 v[94:97], v[174:177], v[216:219], v[94:97]
	v_mfma_f32_16x16x32_bf16 v[86:89], v[164:167], v[224:227], v[86:89]
	v_mfma_f32_16x16x32_bf16 v[78:81], v[174:177], v[224:227], v[78:81]
	s_setprio 0
	s_setprio 1
	v_mfma_f32_16x16x32_bf16 v[114:117], v[178:181], v[196:199], 0
	v_mfma_f32_16x16x32_bf16 v[106:109], v[188:191], v[196:199], 0
	v_mfma_f32_16x16x32_bf16 v[98:101], v[178:181], v[204:207], 0
	v_mfma_f32_16x16x32_bf16 v[90:93], v[188:191], v[204:207], 0
	v_mfma_f32_16x16x32_bf16 v[82:85], v[178:181], v[212:215], 0
	v_mfma_f32_16x16x32_bf16 v[74:77], v[188:191], v[212:215], 0
	v_mfma_f32_16x16x32_bf16 v[70:73], v[178:181], v[220:223], 0
	v_mfma_f32_16x16x32_bf16 v[66:69], v[188:191], v[220:223], 0
	v_mfma_f32_16x16x32_bf16 v[114:117], v[184:187], v[200:203], v[114:117]
	v_mfma_f32_16x16x32_bf16 v[106:109], v[192:195], v[200:203], v[106:109]
	v_mfma_f32_16x16x32_bf16 v[98:101], v[184:187], v[208:211], v[98:101]
	v_mfma_f32_16x16x32_bf16 v[90:93], v[192:195], v[208:211], v[90:93]
	v_mfma_f32_16x16x32_bf16 v[82:85], v[184:187], v[216:219], v[82:85]
	v_mfma_f32_16x16x32_bf16 v[74:77], v[192:195], v[216:219], v[74:77]
	v_mfma_f32_16x16x32_bf16 v[70:73], v[184:187], v[224:227], v[70:73]
	v_mfma_f32_16x16x32_bf16 v[66:69], v[192:195], v[224:227], v[66:69]
	s_setprio 0
	s_barrier
	s_add_i32 s12, s39, s21
	v_lshl_add_u64 v[228:229], s[16:17], 0, v[134:135]
	s_mov_b32 m0, s12
	ds_read_b128 v[196:199], v173 offset:16384
	ds_read_b128 v[200:203], v173 offset:17408
	ds_read_b128 v[204:207], v173 offset:18432
	ds_read_b128 v[208:211], v173 offset:19456
	ds_read_b128 v[212:215], v173 offset:20480
	ds_read_b128 v[216:219], v173 offset:21504
	ds_read_b128 v[220:223], v173 offset:22528
	ds_read_b128 v[224:227], v173 offset:23552
	global_load_lds_dwordx4 v[228:229], off
	s_add_i32 m0, s12, 0x2000
	s_add_u32 s12, s16, 0x44000
	v_lshl_add_u64 v[230:231], s[16:17], 0, v[130:131]
	s_addc_u32 s13, s17, 0
	s_add_i32 s39, s40, s21
	global_load_lds_dwordx4 v[230:231], off
	v_lshl_add_u64 v[232:233], s[12:13], 0, v[134:135]
	s_mov_b32 m0, s39
	v_lshl_add_u64 v[234:235], s[18:19], 0, v[132:133]
	global_load_lds_dwordx4 v[232:233], off
	v_lshl_add_u64 v[232:233], s[12:13], 0, v[130:131]
	s_add_i32 m0, s39, 0x2000
	s_nop 0
	global_load_lds_dwordx4 v[232:233], off
	v_lshl_add_u64 v[232:233], s[18:19], 0, v[152:153]
	s_mov_b32 m0, s23
	s_nop 0
	global_load_lds_dwordx4 v[232:233], off
	s_mov_b32 m0, s24
	s_nop 0
	global_load_lds_dwordx4 v[234:235], off
	s_waitcnt vmcnt(8)
	s_waitcnt lgkmcnt(0)
	s_barrier
; #define PG8_STAGE(bufoff, gbase, voff) do { _Pragma("unroll") for (int _i = 0; _i < 2; ++_i) \
;         __builtin_amdgcn_global_load_lds((const unsigned*)((const char*)(gbase) + (voff)[_i]), (LAS unsigned*)(lds + (bufoff) + ldsw + _i * 8192), 16, 0, 0); } while (0)
; #define PG8_LDA(dst, b, h) do { _Pragma("unroll") for (int m = 0; m < 4; ++m) _Pragma("unroll") for (int k = 0; k < 2; ++k) dst[m][k] = *(const LAS bf16x8*)(lds + PG8_SA(b, h) + aoff + m * 2048 + k * 1024); } while (0)
; #define PG8_LDB(dst, b, h) do { _Pragma("unroll") for (int n = 0; n < 2; ++n) _Pragma("unroll") for (int k = 0; k < 2; ++k) dst[n][k] = *(const LAS bf16x8*)(lds + PG8_SB(b, h) + boff + n * 2048 + k * 1024); } while (0)
; #define PG8_MMA(ai, bj, At, Bt) do { __builtin_amdgcn_s_setprio(1); _Pragma("unroll") for (int m = 0; m < 4; ++m) _Pragma("unroll") for (int n = 0; n < 2; ++n) _Pragma("unroll") for (int k = 0; k < 2; ++k) \
;         acc[ai][bj][m][n] = __builtin_amdgcn_mfma_f32_16x16x32_bf16(Bt[n][k], At[m][k], acc[ai][bj][m][n], 0, 0, 0); __builtin_amdgcn_s_setprio(0); } while (0)
; #define PG8_WAIT_V(n) asm volatile("s_waitcnt vmcnt(" #n ")" ::: "memory")
; #define PG8_WAIT_L(n) asm volatile("s_waitcnt lgkmcnt(" #n ")" ::: "memory")
; #define PG8_BAR __builtin_amdgcn_s_barrier()
; #define PG8_SCHED __builtin_amdgcn_sched_barrier(0)
; template <class Epi, bool ALIGN_EPI = PG8_ALIGN, bool SP2 = PG8_SP2>
; __device__ __forceinline__ void gemm_phase(LAS uchar* lds, const Gemm g, const StaticOrder& S, const Epi& E) {
;     ...
;             PG8_WAIT_V(8); PG8_WAIT_L(0); PG8_BAR; PG8_MMA(1, 0, At, B0); PG8_MMA(1, 1, At, B1); PG8_BAR; PG8_SCHED;
;             PG8_LDB(B0, 1, 0); PG8_LDB(B1, 1, 1); PG8_SCHED; PG8_LDA(At, 1, 0); PG8_STAGE(PG8_SA(0, 1), a2 + hstepA, voffA);
;             PG8_WAIT_V(8); PG8_WAIT_L(0); PG8_BAR; PG8_MMA(0, 0, At, B0); PG8_MMA(0, 1, At, B1); PG8_BAR; PG8_SCHED;
	s_setprio 1
	s_waitcnt lgkmcnt(0)
	v_mfma_f32_16x16x32_bf16 v[62:65], v[160:163], v[196:199], 0
	v_mfma_f32_16x16x32_bf16 v[58:61], v[168:171], v[196:199], 0
	v_mfma_f32_16x16x32_bf16 v[54:57], v[160:163], v[204:207], 0
	v_mfma_f32_16x16x32_bf16 v[46:49], v[168:171], v[204:207], 0
	v_mfma_f32_16x16x32_bf16 v[38:41], v[160:163], v[212:215], 0
	v_mfma_f32_16x16x32_bf16 v[30:33], v[168:171], v[212:215], 0
	v_mfma_f32_16x16x32_bf16 v[22:25], v[160:163], v[220:223], 0
	v_mfma_f32_16x16x32_bf16 v[14:17], v[168:171], v[220:223], 0
	v_mfma_f32_16x16x32_bf16 v[62:65], v[164:167], v[200:203], v[62:65]
	v_mfma_f32_16x16x32_bf16 v[58:61], v[174:177], v[200:203], v[58:61]
	v_mfma_f32_16x16x32_bf16 v[54:57], v[164:167], v[208:211], v[54:57]
	v_mfma_f32_16x16x32_bf16 v[46:49], v[174:177], v[208:211], v[46:49]
	v_mfma_f32_16x16x32_bf16 v[38:41], v[164:167], v[216:219], v[38:41]
	v_mfma_f32_16x16x32_bf16 v[30:33], v[174:177], v[216:219], v[30:33]
	v_mfma_f32_16x16x32_bf16 v[22:25], v[164:167], v[224:227], v[22:25]
	v_mfma_f32_16x16x32_bf16 v[14:17], v[174:177], v[224:227], v[14:17]
	s_setprio 0
	s_setprio 1
	v_mfma_f32_16x16x32_bf16 v[50:53], v[178:181], v[196:199], 0
	v_mfma_f32_16x16x32_bf16 v[42:45], v[188:191], v[196:199], 0
	v_mfma_f32_16x16x32_bf16 v[34:37], v[178:181], v[204:207], 0
	v_mfma_f32_16x16x32_bf16 v[26:29], v[188:191], v[204:207], 0
	v_mfma_f32_16x16x32_bf16 v[18:21], v[178:181], v[212:215], 0
	v_mfma_f32_16x16x32_bf16 v[10:13], v[188:191], v[212:215], 0
	v_mfma_f32_16x16x32_bf16 v[6:9], v[178:181], v[220:223], 0
	v_mfma_f32_16x16x32_bf16 v[2:5], v[188:191], v[220:223], 0
	v_mfma_f32_16x16x32_bf16 v[50:53], v[184:187], v[200:203], v[50:53]
	v_mfma_f32_16x16x32_bf16 v[42:45], v[192:195], v[200:203], v[42:45]
	v_mfma_f32_16x16x32_bf16 v[34:37], v[184:187], v[208:211], v[34:37]
	v_mfma_f32_16x16x32_bf16 v[26:29], v[192:195], v[208:211], v[26:29]
	v_mfma_f32_16x16x32_bf16 v[18:21], v[184:187], v[216:219], v[18:21]
	v_mfma_f32_16x16x32_bf16 v[10:13], v[192:195], v[216:219], v[10:13]
	v_mfma_f32_16x16x32_bf16 v[6:9], v[184:187], v[224:227], v[6:9]
	v_mfma_f32_16x16x32_bf16 v[2:5], v[192:195], v[224:227], v[2:5]
	s_setprio 0
	s_barrier
	s_add_i32 s39, 0, 0x18000
	s_add_i32 s40, 0, 0x1c000
	v_add_u32_e32 v174, s39, v139
	v_add_u32_e32 v192, s40, v139
	ds_read_b128 v[160:163], v174
	ds_read_b128 v[164:167], v174 offset:1024
	ds_read_b128 v[168:171], v174 offset:2048
	ds_read_b128 v[174:177], v174 offset:3072
	ds_read_b128 v[178:181], v192
	ds_read_b128 v[184:187], v192 offset:1024
	ds_read_b128 v[188:191], v192 offset:2048
	ds_read_b128 v[192:195], v192 offset:3072
	s_add_u32 s12, s18, 0x44000
	s_addc_u32 s13, s19, 0
	s_mov_b32 m0, s25
	v_lshl_add_u64 v[236:237], s[12:13], 0, v[152:153]
	ds_read_b128 v[196:199], v173 offset:32768
	ds_read_b128 v[200:203], v173 offset:33792
	ds_read_b128 v[204:207], v173 offset:34816
	ds_read_b128 v[208:211], v173 offset:35840
	ds_read_b128 v[212:215], v173 offset:36864
	ds_read_b128 v[216:219], v173 offset:37888
	ds_read_b128 v[220:223], v173 offset:38912
	ds_read_b128 v[224:227], v173 offset:39936
	global_load_lds_dwordx4 v[236:237], off
	v_lshl_add_u64 v[236:237], s[12:13], 0, v[132:133]
	s_mov_b32 m0, s26
	s_nop 0
	global_load_lds_dwordx4 v[236:237], off
	s_waitcnt vmcnt(8)
	s_waitcnt lgkmcnt(0)
	s_barrier
	s_setprio 1
	s_waitcnt lgkmcnt(0)
	v_mfma_f32_16x16x32_bf16 v[126:129], v[160:163], v[196:199], v[126:129]
	v_mfma_f32_16x16x32_bf16 v[122:125], v[168:171], v[196:199], v[122:125]
	v_mfma_f32_16x16x32_bf16 v[118:121], v[160:163], v[204:207], v[118:121]
	v_mfma_f32_16x16x32_bf16 v[110:113], v[168:171], v[204:207], v[110:113]
	v_mfma_f32_16x16x32_bf16 v[102:105], v[160:163], v[212:215], v[102:105]
	v_mfma_f32_16x16x32_bf16 v[94:97], v[168:171], v[212:215], v[94:97]
	v_mfma_f32_16x16x32_bf16 v[86:89], v[160:163], v[220:223], v[86:89]
	v_mfma_f32_16x16x32_bf16 v[78:81], v[168:171], v[220:223], v[78:81]
	v_mfma_f32_16x16x32_bf16 v[126:129], v[164:167], v[200:203], v[126:129]
	v_mfma_f32_16x16x32_bf16 v[122:125], v[174:177], v[200:203], v[122:125]
	v_mfma_f32_16x16x32_bf16 v[118:121], v[164:167], v[208:211], v[118:121]
	v_mfma_f32_16x16x32_bf16 v[110:113], v[174:177], v[208:211], v[110:113]
	v_mfma_f32_16x16x32_bf16 v[102:105], v[164:167], v[216:219], v[102:105]
	v_mfma_f32_16x16x32_bf16 v[94:97], v[174:177], v[216:219], v[94:97]
	v_mfma_f32_16x16x32_bf16 v[86:89], v[164:167], v[224:227], v[86:89]
	v_mfma_f32_16x16x32_bf16 v[78:81], v[174:177], v[224:227], v[78:81]
	s_setprio 0
	s_setprio 1
	v_mfma_f32_16x16x32_bf16 v[114:117], v[178:181], v[196:199], v[114:117]
	v_mfma_f32_16x16x32_bf16 v[106:109], v[188:191], v[196:199], v[106:109]
	v_mfma_f32_16x16x32_bf16 v[98:101], v[178:181], v[204:207], v[98:101]
	v_mfma_f32_16x16x32_bf16 v[90:93], v[188:191], v[204:207], v[90:93]
	v_mfma_f32_16x16x32_bf16 v[82:85], v[178:181], v[212:215], v[82:85]
	v_mfma_f32_16x16x32_bf16 v[74:77], v[188:191], v[212:215], v[74:77]
	v_mfma_f32_16x16x32_bf16 v[70:73], v[178:181], v[220:223], v[70:73]
	v_mfma_f32_16x16x32_bf16 v[66:69], v[188:191], v[220:223], v[66:69]
	v_mfma_f32_16x16x32_bf16 v[114:117], v[184:187], v[200:203], v[114:117]
	v_mfma_f32_16x16x32_bf16 v[106:109], v[192:195], v[200:203], v[106:109]
	v_mfma_f32_16x16x32_bf16 v[98:101], v[184:187], v[208:211], v[98:101]
	v_mfma_f32_16x16x32_bf16 v[90:93], v[192:195], v[208:211], v[90:93]
	v_mfma_f32_16x16x32_bf16 v[82:85], v[184:187], v[216:219], v[82:85]
	v_mfma_f32_16x16x32_bf16 v[74:77], v[192:195], v[216:219], v[74:77]
	v_mfma_f32_16x16x32_bf16 v[70:73], v[184:187], v[224:227], v[70:73]
	v_mfma_f32_16x16x32_bf16 v[66:69], v[192:195], v[224:227], v[66:69]
	s_setprio 0
	s_barrier
; #define PG8_STAGE(bufoff, gbase, voff) do { _Pragma("unroll") for (int _i = 0; _i < 2; ++_i) \
;         __builtin_amdgcn_global_load_lds((const unsigned*)((const char*)(gbase) + (voff)[_i]), (LAS unsigned*)(lds + (bufoff) + ldsw + _i * 8192), 16, 0, 0); } while (0)
; #define PG8_LDA(dst, b, h) do { _Pragma("unroll") for (int m = 0; m < 4; ++m) _Pragma("unroll") for (int k = 0; k < 2; ++k) dst[m][k] = *(const LAS bf16x8*)(lds + PG8_SA(b, h) + aoff + m * 2048 + k * 1024); } while (0)
; #define PG8_LDB(dst, b, h) do { _Pragma("unroll") for (int n = 0; n < 2; ++n) _Pragma("unroll") for (int k = 0; k < 2; ++k) dst[n][k] = *(const LAS bf16x8*)(lds + PG8_SB(b, h) + boff + n * 2048 + k * 1024); } while (0)
; #define PG8_BAR __builtin_amdgcn_s_barrier()
; template <class Epi, bool ALIGN_EPI = PG8_ALIGN, bool SP2 = PG8_SP2>
; __device__ __forceinline__ void gemm_phase(LAS uchar* lds, const Gemm g, const StaticOrder& S, const Epi& E) {
;     ...
;         for (int t = tb; t < tb + tblk; t += 2) {
;             const bool last = (t == nt - 2);
;             const char* a1 = cA + (size_t)(t + 1) * kstep;
;             const char* a2 = last ? nA : cA + (size_t)(t + 2) * kstep; const char* b2 = last ? nB : cB + (size_t)(t + 2) * kstep;
;             const char* a3 = a2 + kstep; const char* b3 = b2 + kstep;
;             if constexpr (SP2) {
;             PG8_LDB(B0, 0, 0); PG8_LDB(B1, 0, 1); PG8_SCHED; PG8_LDA(At, 0, 0); PG8_STAGE(PG8_SA(1, 1), a1 + hstepA, voffA);
;             PG8_WAIT_V(8); PG8_WAIT_L(0); PG8_BAR; PG8_MMA(0, 0, At, B0); PG8_MMA(0, 1, At, B1); PG8_BAR; PG8_SCHED;
;             PG8_LDA(At, 0, 1); PG8_STAGE(PG8_SB(0, 0), b2, voffB); PG8_STAGE(PG8_SB(0, 1), b2 + hstepB, voffB); PG8_STAGE(PG8_SA(0, 0), a2, voffA);
;             PG8_WAIT_V(8); PG8_WAIT_L(0); PG8_BAR; PG8_MMA(1, 0, At, B0); PG8_MMA(1, 1, At, B1); PG8_BAR; PG8_SCHED;
;             PG8_LDB(B0, 1, 0); PG8_LDB(B1, 1, 1); PG8_SCHED; PG8_LDA(At, 1, 0); PG8_STAGE(PG8_SA(0, 1), a2 + hstepA, voffA);
;             PG8_WAIT_V(8); PG8_WAIT_L(0); PG8_BAR; PG8_MMA(0, 0, At, B0); PG8_MMA(0, 1, At, B1); PG8_BAR; PG8_SCHED;
;             PG8_LDA(At, 1, 1); PG8_STAGE(PG8_SB(1, 0), b3, voffB); PG8_STAGE(PG8_SB(1, 1), b3 + hstepB, voffB); PG8_STAGE(PG8_SA(1, 0), a3, voffA);
;             PG8_WAIT_V(8); PG8_WAIT_L(0); PG8_BAR; PG8_MMA(1, 0, At, B0); PG8_MMA(1, 1, At, B1); PG8_BAR; PG8_SCHED;
	s_add_i32 s12, s39, s21
	v_lshl_add_u64 v[228:229], v[228:229], 0, s[84:85]
	s_mov_b32 m0, s12
	ds_read_b128 v[196:199], v173 offset:49152
	ds_read_b128 v[200:203], v173 offset:50176
	ds_read_b128 v[204:207], v173 offset:51200
	ds_read_b128 v[208:211], v173 offset:52224
	ds_read_b128 v[212:215], v173 offset:53248
	ds_read_b128 v[216:219], v173 offset:54272
	ds_read_b128 v[220:223], v173 offset:55296
	ds_read_b128 v[224:227], v173 offset:56320
	global_load_lds_dwordx4 v[228:229], off
	s_add_i32 m0, s12, 0x2000
	s_add_u32 s12, s16, 0x44080
	v_lshl_add_u64 v[228:229], v[230:231], 0, s[84:85]
	s_addc_u32 s13, s17, 0
	s_add_i32 s16, s40, s21
	global_load_lds_dwordx4 v[228:229], off
	v_lshl_add_u64 v[228:229], s[12:13], 0, v[134:135]
	s_mov_b32 m0, s16
	s_nop 0
	global_load_lds_dwordx4 v[228:229], off
	v_lshl_add_u64 v[228:229], s[12:13], 0, v[130:131]
	s_add_i32 m0, s16, 0x2000
	s_nop 0
	global_load_lds_dwordx4 v[228:229], off
	v_lshl_add_u64 v[228:229], v[232:233], 0, s[84:85]
	s_mov_b32 m0, s27
	s_nop 0
	global_load_lds_dwordx4 v[228:229], off
	v_lshl_add_u64 v[228:229], v[234:235], 0, s[84:85]
	s_mov_b32 m0, s28
	s_nop 0
	global_load_lds_dwordx4 v[228:229], off
	s_waitcnt vmcnt(8)
	s_waitcnt lgkmcnt(0)
	s_barrier
	s_setprio 1
	s_waitcnt lgkmcnt(0)
	v_mfma_f32_16x16x32_bf16 v[62:65], v[160:163], v[196:199], v[62:65]
	v_mfma_f32_16x16x32_bf16 v[58:61], v[168:171], v[196:199], v[58:61]
	v_mfma_f32_16x16x32_bf16 v[54:57], v[160:163], v[204:207], v[54:57]
	v_mfma_f32_16x16x32_bf16 v[46:49], v[168:171], v[204:207], v[46:49]
	v_mfma_f32_16x16x32_bf16 v[38:41], v[160:163], v[212:215], v[38:41]
	v_mfma_f32_16x16x32_bf16 v[30:33], v[168:171], v[212:215], v[30:33]
	v_mfma_f32_16x16x32_bf16 v[22:25], v[160:163], v[220:223], v[22:25]
	v_mfma_f32_16x16x32_bf16 v[14:17], v[168:171], v[220:223], v[14:17]
	v_mfma_f32_16x16x32_bf16 v[62:65], v[164:167], v[200:203], v[62:65]
	v_mfma_f32_16x16x32_bf16 v[58:61], v[174:177], v[200:203], v[58:61]
	v_mfma_f32_16x16x32_bf16 v[54:57], v[164:167], v[208:211], v[54:57]
	v_mfma_f32_16x16x32_bf16 v[46:49], v[174:177], v[208:211], v[46:49]
	v_mfma_f32_16x16x32_bf16 v[38:41], v[164:167], v[216:219], v[38:41]
	v_mfma_f32_16x16x32_bf16 v[30:33], v[174:177], v[216:219], v[30:33]
	v_mfma_f32_16x16x32_bf16 v[22:25], v[164:167], v[224:227], v[22:25]
	v_mfma_f32_16x16x32_bf16 v[14:17], v[174:177], v[224:227], v[14:17]
	s_setprio 0
	s_setprio 1
	v_mfma_f32_16x16x32_bf16 v[50:53], v[178:181], v[196:199], v[50:53]
	v_mfma_f32_16x16x32_bf16 v[42:45], v[188:191], v[196:199], v[42:45]
	v_mfma_f32_16x16x32_bf16 v[34:37], v[178:181], v[204:207], v[34:37]
	v_mfma_f32_16x16x32_bf16 v[26:29], v[188:191], v[204:207], v[26:29]
	v_mfma_f32_16x16x32_bf16 v[18:21], v[178:181], v[212:215], v[18:21]
	v_mfma_f32_16x16x32_bf16 v[10:13], v[188:191], v[212:215], v[10:13]
	v_mfma_f32_16x16x32_bf16 v[6:9], v[178:181], v[220:223], v[6:9]
	v_mfma_f32_16x16x32_bf16 v[2:5], v[188:191], v[220:223], v[2:5]
	v_mfma_f32_16x16x32_bf16 v[50:53], v[184:187], v[200:203], v[50:53]
	v_mfma_f32_16x16x32_bf16 v[42:45], v[192:195], v[200:203], v[42:45]
	v_mfma_f32_16x16x32_bf16 v[34:37], v[184:187], v[208:211], v[34:37]
	v_mfma_f32_16x16x32_bf16 v[26:29], v[192:195], v[208:211], v[26:29]
	v_mfma_f32_16x16x32_bf16 v[18:21], v[184:187], v[216:219], v[18:21]
	v_mfma_f32_16x16x32_bf16 v[10:13], v[192:195], v[216:219], v[10:13]
	v_mfma_f32_16x16x32_bf16 v[6:9], v[184:187], v[224:227], v[6:9]
	v_mfma_f32_16x16x32_bf16 v[2:5], v[192:195], v[224:227], v[2:5]
	s_setprio 0
	s_add_i32 s38, s38, 2
	s_add_u32 s36, s36, 0x100
	s_addc_u32 s37, s37, 0
	s_cmp_gt_u32 s38, 13
	s_mov_b64 s[12:13], s[14:15]
	s_add_u32 s14, s12, 0x100
	s_addc_u32 s15, s13, 0
	s_add_i32 s39, 0, 0x10000
	s_cmp_eq_u32 s38, 12
	s_cselect_b32 s19, s5, s15
	s_cselect_b32 s18, s4, s14
	s_cselect_b32 s17, s11, s37
	s_cselect_b32 s16, s10, s36
	s_add_i32 s40, 0, 0x14000
	v_add_u32_e32 v174, s39, v139
	v_add_u32_e32 v192, s40, v139
.LBB0_669:
	s_barrier
	ds_read_b128 v[160:163], v174
	ds_read_b128 v[164:167], v174 offset:1024
	ds_read_b128 v[168:171], v174 offset:2048
	ds_read_b128 v[174:177], v174 offset:3072
	ds_read_b128 v[178:181], v192
	ds_read_b128 v[184:187], v192 offset:1024
	ds_read_b128 v[188:191], v192 offset:2048
	ds_read_b128 v[192:195], v192 offset:3072
	v_lshl_add_u64 v[228:229], s[12:13], 0, v[156:157]
	s_add_i32 m0, s23, 0xc000
	ds_read_b128 v[196:199], v173
	ds_read_b128 v[200:203], v173 offset:1024
	ds_read_b128 v[204:207], v173 offset:2048
	ds_read_b128 v[208:211], v173 offset:3072
	ds_read_b128 v[212:215], v173 offset:4096
	ds_read_b128 v[216:219], v173 offset:5120
	ds_read_b128 v[220:223], v173 offset:6144
	ds_read_b128 v[224:227], v173 offset:7168
	global_load_lds_dwordx4 v[228:229], off
	v_lshl_add_u64 v[228:229], s[12:13], 0, v[158:159]
	s_add_i32 m0, s23, 0xe000
	s_nop 0
	global_load_lds_dwordx4 v[228:229], off
	s_waitcnt vmcnt(8)
	s_waitcnt lgkmcnt(0)
	s_barrier
; #define PG8_STAGE(bufoff, gbase, voff) do { _Pragma("unroll") for (int _i = 0; _i < 2; ++_i) \
;         __builtin_amdgcn_global_load_lds((const unsigned*)((const char*)(gbase) + (voff)[_i]), (LAS unsigned*)(lds + (bufoff) + ldsw + _i * 8192), 16, 0, 0); } while (0)
; #define PG8_LDA(dst, b, h) do { _Pragma("unroll") for (int m = 0; m < 4; ++m) _Pragma("unroll") for (int k = 0; k < 2; ++k) dst[m][k] = *(const LAS bf16x8*)(lds + PG8_SA(b, h) + aoff + m * 2048 + k * 1024); } while (0)
; #define PG8_MMA(ai, bj, At, Bt) do { __builtin_amdgcn_s_setprio(1); _Pragma("unroll") for (int m = 0; m < 4; ++m) _Pragma("unroll") for (int n = 0; n < 2; ++n) _Pragma("unroll") for (int k = 0; k < 2; ++k) \
;         acc[ai][bj][m][n] = __builtin_amdgcn_mfma_f32_16x16x32_bf16(Bt[n][k], At[m][k], acc[ai][bj][m][n], 0, 0, 0); __builtin_amdgcn_s_setprio(0); } while (0)
; #define PG8_WAIT_V(n) asm volatile("s_waitcnt vmcnt(" #n ")" ::: "memory")
; #define PG8_WAIT_L(n) asm volatile("s_waitcnt lgkmcnt(" #n ")" ::: "memory")
; #define PG8_BAR __builtin_amdgcn_s_barrier()
; #define PG8_SCHED __builtin_amdgcn_sched_barrier(0)
; template <class Epi, bool ALIGN_EPI = PG8_ALIGN, bool SP2 = PG8_SP2>
; __device__ __forceinline__ void gemm_phase(LAS uchar* lds, const Gemm g, const StaticOrder& S, const Epi& E) {
;     ...
;             PG8_WAIT_V(8); PG8_WAIT_L(0); PG8_BAR; PG8_MMA(0, 0, At, B0); PG8_MMA(0, 1, At, B1); PG8_BAR; PG8_SCHED;
;             PG8_LDA(At, 0, 1); PG8_STAGE(PG8_SB(0, 0), b2, voffB); PG8_STAGE(PG8_SB(0, 1), b2 + hstepB, voffB); PG8_STAGE(PG8_SA(0, 0), a2, voffA);
;             PG8_WAIT_V(8); PG8_WAIT_L(0); PG8_BAR; PG8_MMA(1, 0, At, B0); PG8_MMA(1, 1, At, B1); PG8_BAR; PG8_SCHED;
	s_setprio 1
	s_waitcnt lgkmcnt(0)
	v_mfma_f32_16x16x32_bf16 v[126:129], v[160:163], v[196:199], v[126:129]
	v_mfma_f32_16x16x32_bf16 v[122:125], v[168:171], v[196:199], v[122:125]
	v_mfma_f32_16x16x32_bf16 v[118:121], v[160:163], v[204:207], v[118:121]
	v_mfma_f32_16x16x32_bf16 v[110:113], v[168:171], v[204:207], v[110:113]
	v_mfma_f32_16x16x32_bf16 v[102:105], v[160:163], v[212:215], v[102:105]
	v_mfma_f32_16x16x32_bf16 v[94:97], v[168:171], v[212:215], v[94:97]
	v_mfma_f32_16x16x32_bf16 v[86:89], v[160:163], v[220:223], v[86:89]
	v_mfma_f32_16x16x32_bf16 v[78:81], v[168:171], v[220:223], v[78:81]
	v_mfma_f32_16x16x32_bf16 v[126:129], v[164:167], v[200:203], v[126:129]
	v_mfma_f32_16x16x32_bf16 v[122:125], v[174:177], v[200:203], v[122:125]
	v_mfma_f32_16x16x32_bf16 v[118:121], v[164:167], v[208:211], v[118:121]
	v_mfma_f32_16x16x32_bf16 v[110:113], v[174:177], v[208:211], v[110:113]
	v_mfma_f32_16x16x32_bf16 v[102:105], v[164:167], v[216:219], v[102:105]
	v_mfma_f32_16x16x32_bf16 v[94:97], v[174:177], v[216:219], v[94:97]
	v_mfma_f32_16x16x32_bf16 v[86:89], v[164:167], v[224:227], v[86:89]
	v_mfma_f32_16x16x32_bf16 v[78:81], v[174:177], v[224:227], v[78:81]
	s_setprio 0
	s_setprio 1
	v_mfma_f32_16x16x32_bf16 v[114:117], v[178:181], v[196:199], v[114:117]
	v_mfma_f32_16x16x32_bf16 v[106:109], v[188:191], v[196:199], v[106:109]
	v_mfma_f32_16x16x32_bf16 v[98:101], v[178:181], v[204:207], v[98:101]
	v_mfma_f32_16x16x32_bf16 v[90:93], v[188:191], v[204:207], v[90:93]
	v_mfma_f32_16x16x32_bf16 v[82:85], v[178:181], v[212:215], v[82:85]
	v_mfma_f32_16x16x32_bf16 v[74:77], v[188:191], v[212:215], v[74:77]
	v_mfma_f32_16x16x32_bf16 v[70:73], v[178:181], v[220:223], v[70:73]
	v_mfma_f32_16x16x32_bf16 v[66:69], v[188:191], v[220:223], v[66:69]
	v_mfma_f32_16x16x32_bf16 v[114:117], v[184:187], v[200:203], v[114:117]
	v_mfma_f32_16x16x32_bf16 v[106:109], v[192:195], v[200:203], v[106:109]
	v_mfma_f32_16x16x32_bf16 v[98:101], v[184:187], v[208:211], v[98:101]
	v_mfma_f32_16x16x32_bf16 v[90:93], v[192:195], v[208:211], v[90:93]
	v_mfma_f32_16x16x32_bf16 v[82:85], v[184:187], v[216:219], v[82:85]
	v_mfma_f32_16x16x32_bf16 v[74:77], v[192:195], v[216:219], v[74:77]
	v_mfma_f32_16x16x32_bf16 v[70:73], v[184:187], v[224:227], v[70:73]
	v_mfma_f32_16x16x32_bf16 v[66:69], v[192:195], v[224:227], v[66:69]
	s_setprio 0
	s_barrier
	s_add_i32 s12, s39, s21
	v_lshl_add_u64 v[228:229], s[16:17], 0, v[134:135]
	s_mov_b32 m0, s12
	ds_read_b128 v[196:199], v173 offset:16384
	ds_read_b128 v[200:203], v173 offset:17408
	ds_read_b128 v[204:207], v173 offset:18432
	ds_read_b128 v[208:211], v173 offset:19456
	ds_read_b128 v[212:215], v173 offset:20480
	ds_read_b128 v[216:219], v173 offset:21504
	ds_read_b128 v[220:223], v173 offset:22528
	ds_read_b128 v[224:227], v173 offset:23552
	global_load_lds_dwordx4 v[228:229], off
	s_add_i32 m0, s12, 0x2000
	s_add_u32 s12, s16, 0x44000
	v_lshl_add_u64 v[230:231], s[16:17], 0, v[130:131]
	s_addc_u32 s13, s17, 0
	s_add_i32 s39, s40, s21
	global_load_lds_dwordx4 v[230:231], off
	v_lshl_add_u64 v[232:233], s[12:13], 0, v[134:135]
	s_mov_b32 m0, s39
	v_lshl_add_u64 v[234:235], s[18:19], 0, v[132:133]
	global_load_lds_dwordx4 v[232:233], off
	v_lshl_add_u64 v[232:233], s[12:13], 0, v[130:131]
	s_add_i32 m0, s39, 0x2000
	s_nop 0
	global_load_lds_dwordx4 v[232:233], off
	v_lshl_add_u64 v[232:233], s[18:19], 0, v[152:153]
	s_mov_b32 m0, s23
	s_nop 0
	global_load_lds_dwordx4 v[232:233], off
	s_mov_b32 m0, s24
	s_nop 0
	global_load_lds_dwordx4 v[234:235], off
	s_waitcnt vmcnt(8)
	s_waitcnt lgkmcnt(0)
	s_barrier
	s_setprio 1
	s_waitcnt lgkmcnt(0)
	v_mfma_f32_16x16x32_bf16 v[62:65], v[160:163], v[196:199], v[62:65]
	v_mfma_f32_16x16x32_bf16 v[58:61], v[168:171], v[196:199], v[58:61]
	v_mfma_f32_16x16x32_bf16 v[54:57], v[160:163], v[204:207], v[54:57]
	v_mfma_f32_16x16x32_bf16 v[46:49], v[168:171], v[204:207], v[46:49]
	v_mfma_f32_16x16x32_bf16 v[38:41], v[160:163], v[212:215], v[38:41]
	v_mfma_f32_16x16x32_bf16 v[30:33], v[168:171], v[212:215], v[30:33]
	v_mfma_f32_16x16x32_bf16 v[22:25], v[160:163], v[220:223], v[22:25]
	v_mfma_f32_16x16x32_bf16 v[14:17], v[168:171], v[220:223], v[14:17]
	v_mfma_f32_16x16x32_bf16 v[62:65], v[164:167], v[200:203], v[62:65]
	v_mfma_f32_16x16x32_bf16 v[58:61], v[174:177], v[200:203], v[58:61]
	v_mfma_f32_16x16x32_bf16 v[54:57], v[164:167], v[208:211], v[54:57]
	v_mfma_f32_16x16x32_bf16 v[46:49], v[174:177], v[208:211], v[46:49]
	v_mfma_f32_16x16x32_bf16 v[38:41], v[164:167], v[216:219], v[38:41]
	v_mfma_f32_16x16x32_bf16 v[30:33], v[174:177], v[216:219], v[30:33]
	v_mfma_f32_16x16x32_bf16 v[22:25], v[164:167], v[224:227], v[22:25]
	v_mfma_f32_16x16x32_bf16 v[14:17], v[174:177], v[224:227], v[14:17]
	s_setprio 0
	s_setprio 1
	v_mfma_f32_16x16x32_bf16 v[50:53], v[178:181], v[196:199], v[50:53]
	v_mfma_f32_16x16x32_bf16 v[42:45], v[188:191], v[196:199], v[42:45]
	v_mfma_f32_16x16x32_bf16 v[34:37], v[178:181], v[204:207], v[34:37]
	v_mfma_f32_16x16x32_bf16 v[26:29], v[188:191], v[204:207], v[26:29]
	v_mfma_f32_16x16x32_bf16 v[18:21], v[178:181], v[212:215], v[18:21]
	v_mfma_f32_16x16x32_bf16 v[10:13], v[188:191], v[212:215], v[10:13]
	v_mfma_f32_16x16x32_bf16 v[6:9], v[178:181], v[220:223], v[6:9]
	v_mfma_f32_16x16x32_bf16 v[2:5], v[188:191], v[220:223], v[2:5]
	v_mfma_f32_16x16x32_bf16 v[50:53], v[184:187], v[200:203], v[50:53]
	v_mfma_f32_16x16x32_bf16 v[42:45], v[192:195], v[200:203], v[42:45]
	v_mfma_f32_16x16x32_bf16 v[34:37], v[184:187], v[208:211], v[34:37]
	v_mfma_f32_16x16x32_bf16 v[26:29], v[192:195], v[208:211], v[26:29]
	v_mfma_f32_16x16x32_bf16 v[18:21], v[184:187], v[216:219], v[18:21]
	v_mfma_f32_16x16x32_bf16 v[10:13], v[192:195], v[216:219], v[10:13]
	v_mfma_f32_16x16x32_bf16 v[6:9], v[184:187], v[224:227], v[6:9]
	v_mfma_f32_16x16x32_bf16 v[2:5], v[192:195], v[224:227], v[2:5]
	s_setprio 0
	s_barrier
; #define PG8_STAGE(bufoff, gbase, voff) do { _Pragma("unroll") for (int _i = 0; _i < 2; ++_i) \
;         __builtin_amdgcn_global_load_lds((const unsigned*)((const char*)(gbase) + (voff)[_i]), (LAS unsigned*)(lds + (bufoff) + ldsw + _i * 8192), 16, 0, 0); } while (0)
; #define PG8_LDA(dst, b, h) do { _Pragma("unroll") for (int m = 0; m < 4; ++m) _Pragma("unroll") for (int k = 0; k < 2; ++k) dst[m][k] = *(const LAS bf16x8*)(lds + PG8_SA(b, h) + aoff + m * 2048 + k * 1024); } while (0)
; #define PG8_LDB(dst, b, h) do { _Pragma("unroll") for (int n = 0; n < 2; ++n) _Pragma("unroll") for (int k = 0; k < 2; ++k) dst[n][k] = *(const LAS bf16x8*)(lds + PG8_SB(b, h) + boff + n * 2048 + k * 1024); } while (0)
; #define PG8_MMA(ai, bj, At, Bt) do { __builtin_amdgcn_s_setprio(1); _Pragma("unroll") for (int m = 0; m < 4; ++m) _Pragma("unroll") for (int n = 0; n < 2; ++n) _Pragma("unroll") for (int k = 0; k < 2; ++k) \
;         acc[ai][bj][m][n] = __builtin_amdgcn_mfma_f32_16x16x32_bf16(Bt[n][k], At[m][k], acc[ai][bj][m][n], 0, 0, 0); __builtin_amdgcn_s_setprio(0); } while (0)
; #define PG8_WAIT_V(n) asm volatile("s_waitcnt vmcnt(" #n ")" ::: "memory")
; #define PG8_WAIT_L(n) asm volatile("s_waitcnt lgkmcnt(" #n ")" ::: "memory")
; #define PG8_BAR __builtin_amdgcn_s_barrier()
; #define PG8_SCHED __builtin_amdgcn_sched_barrier(0)
; template <class Epi, bool ALIGN_EPI = PG8_ALIGN, bool SP2 = PG8_SP2>
; __device__ __forceinline__ void gemm_phase(LAS uchar* lds, const Gemm g, const StaticOrder& S, const Epi& E) {
;     ...
;             PG8_LDB(B0, 1, 0); PG8_LDB(B1, 1, 1); PG8_SCHED; PG8_LDA(At, 1, 0); PG8_STAGE(PG8_SA(0, 1), a2 + hstepA, voffA);
;             PG8_WAIT_V(8); PG8_WAIT_L(0); PG8_BAR; PG8_MMA(0, 0, At, B0); PG8_MMA(0, 1, At, B1); PG8_BAR; PG8_SCHED;
	s_add_i32 s39, 0, 0x18000
	s_add_i32 s40, 0, 0x1c000
	v_add_u32_e32 v174, s39, v139
	v_add_u32_e32 v192, s40, v139
	ds_read_b128 v[160:163], v174
	ds_read_b128 v[164:167], v174 offset:1024
	ds_read_b128 v[168:171], v174 offset:2048
	ds_read_b128 v[174:177], v174 offset:3072
	ds_read_b128 v[178:181], v192
	ds_read_b128 v[184:187], v192 offset:1024
	ds_read_b128 v[188:191], v192 offset:2048
	ds_read_b128 v[192:195], v192 offset:3072
	s_add_u32 s12, s18, 0x44000
	s_addc_u32 s13, s19, 0
	s_mov_b32 m0, s25
	v_lshl_add_u64 v[236:237], s[12:13], 0, v[152:153]
	ds_read_b128 v[196:199], v173 offset:32768
	ds_read_b128 v[200:203], v173 offset:33792
	ds_read_b128 v[204:207], v173 offset:34816
	ds_read_b128 v[208:211], v173 offset:35840
	ds_read_b128 v[212:215], v173 offset:36864
	ds_read_b128 v[216:219], v173 offset:37888
	ds_read_b128 v[220:223], v173 offset:38912
	ds_read_b128 v[224:227], v173 offset:39936
	global_load_lds_dwordx4 v[236:237], off
	v_lshl_add_u64 v[236:237], s[12:13], 0, v[132:133]
	s_mov_b32 m0, s26
	s_nop 0
	global_load_lds_dwordx4 v[236:237], off
	s_waitcnt vmcnt(8)
	s_waitcnt lgkmcnt(0)
	s_barrier
	s_setprio 1
	s_waitcnt lgkmcnt(0)
	v_mfma_f32_16x16x32_bf16 v[126:129], v[160:163], v[196:199], v[126:129]
	v_mfma_f32_16x16x32_bf16 v[122:125], v[168:171], v[196:199], v[122:125]
	v_mfma_f32_16x16x32_bf16 v[118:121], v[160:163], v[204:207], v[118:121]
	v_mfma_f32_16x16x32_bf16 v[110:113], v[168:171], v[204:207], v[110:113]
	v_mfma_f32_16x16x32_bf16 v[102:105], v[160:163], v[212:215], v[102:105]
	v_mfma_f32_16x16x32_bf16 v[94:97], v[168:171], v[212:215], v[94:97]
	v_mfma_f32_16x16x32_bf16 v[86:89], v[160:163], v[220:223], v[86:89]
	v_mfma_f32_16x16x32_bf16 v[78:81], v[168:171], v[220:223], v[78:81]
	v_mfma_f32_16x16x32_bf16 v[126:129], v[164:167], v[200:203], v[126:129]
	v_mfma_f32_16x16x32_bf16 v[122:125], v[174:177], v[200:203], v[122:125]
	v_mfma_f32_16x16x32_bf16 v[118:121], v[164:167], v[208:211], v[118:121]
	v_mfma_f32_16x16x32_bf16 v[110:113], v[174:177], v[208:211], v[110:113]
	v_mfma_f32_16x16x32_bf16 v[102:105], v[164:167], v[216:219], v[102:105]
	v_mfma_f32_16x16x32_bf16 v[94:97], v[174:177], v[216:219], v[94:97]
	v_mfma_f32_16x16x32_bf16 v[86:89], v[164:167], v[224:227], v[86:89]
	v_mfma_f32_16x16x32_bf16 v[78:81], v[174:177], v[224:227], v[78:81]
	s_setprio 0
	s_setprio 1
	v_mfma_f32_16x16x32_bf16 v[114:117], v[178:181], v[196:199], v[114:117]
	v_mfma_f32_16x16x32_bf16 v[106:109], v[188:191], v[196:199], v[106:109]
	v_mfma_f32_16x16x32_bf16 v[98:101], v[178:181], v[204:207], v[98:101]
	v_mfma_f32_16x16x32_bf16 v[90:93], v[188:191], v[204:207], v[90:93]
	v_mfma_f32_16x16x32_bf16 v[82:85], v[178:181], v[212:215], v[82:85]
	v_mfma_f32_16x16x32_bf16 v[74:77], v[188:191], v[212:215], v[74:77]
	v_mfma_f32_16x16x32_bf16 v[70:73], v[178:181], v[220:223], v[70:73]
	v_mfma_f32_16x16x32_bf16 v[66:69], v[188:191], v[220:223], v[66:69]
	v_mfma_f32_16x16x32_bf16 v[114:117], v[184:187], v[200:203], v[114:117]
	v_mfma_f32_16x16x32_bf16 v[106:109], v[192:195], v[200:203], v[106:109]
	v_mfma_f32_16x16x32_bf16 v[98:101], v[184:187], v[208:211], v[98:101]
	v_mfma_f32_16x16x32_bf16 v[90:93], v[192:195], v[208:211], v[90:93]
	v_mfma_f32_16x16x32_bf16 v[82:85], v[184:187], v[216:219], v[82:85]
	v_mfma_f32_16x16x32_bf16 v[74:77], v[192:195], v[216:219], v[74:77]
	v_mfma_f32_16x16x32_bf16 v[70:73], v[184:187], v[224:227], v[70:73]
	v_mfma_f32_16x16x32_bf16 v[66:69], v[192:195], v[224:227], v[66:69]
	s_setprio 0
	s_barrier
; #define PG8_STAGE(bufoff, gbase, voff) do { _Pragma("unroll") for (int _i = 0; _i < 2; ++_i) \
;         __builtin_amdgcn_global_load_lds((const unsigned*)((const char*)(gbase) + (voff)[_i]), (LAS unsigned*)(lds + (bufoff) + ldsw + _i * 8192), 16, 0, 0); } while (0)
; #define PG8_LDA(dst, b, h) do { _Pragma("unroll") for (int m = 0; m < 4; ++m) _Pragma("unroll") for (int k = 0; k < 2; ++k) dst[m][k] = *(const LAS bf16x8*)(lds + PG8_SA(b, h) + aoff + m * 2048 + k * 1024); } while (0)
; #define PG8_MMA(ai, bj, At, Bt) do { __builtin_amdgcn_s_setprio(1); _Pragma("unroll") for (int m = 0; m < 4; ++m) _Pragma("unroll") for (int n = 0; n < 2; ++n) _Pragma("unroll") for (int k = 0; k < 2; ++k) \
;         acc[ai][bj][m][n] = __builtin_amdgcn_mfma_f32_16x16x32_bf16(Bt[n][k], At[m][k], acc[ai][bj][m][n], 0, 0, 0); __builtin_amdgcn_s_setprio(0); } while (0)
; #define PG8_WAIT_V(n) asm volatile("s_waitcnt vmcnt(" #n ")" ::: "memory")
; #define PG8_WAIT_L(n) asm volatile("s_waitcnt lgkmcnt(" #n ")" ::: "memory")
; #define PG8_BAR __builtin_amdgcn_s_barrier()
; #define PG8_SCHED __builtin_amdgcn_sched_barrier(0)
; template <class Epi, bool ALIGN_EPI = PG8_ALIGN, bool SP2 = PG8_SP2>
; __device__ __forceinline__ void gemm_phase(LAS uchar* lds, const Gemm g, const StaticOrder& S, const Epi& E) {
;     ...
;             PG8_WAIT_V(8); PG8_WAIT_L(0); PG8_BAR; PG8_MMA(0, 0, At, B0); PG8_MMA(0, 1, At, B1); PG8_BAR; PG8_SCHED;
;             PG8_LDA(At, 1, 1); PG8_STAGE(PG8_SB(1, 0), b3, voffB); PG8_STAGE(PG8_SB(1, 1), b3 + hstepB, voffB); PG8_STAGE(PG8_SA(1, 0), a3, voffA);
;             PG8_WAIT_V(8); PG8_WAIT_L(0); PG8_BAR; PG8_MMA(1, 0, At, B0); PG8_MMA(1, 1, At, B1); PG8_BAR; PG8_SCHED;
;     ...
;         if constexpr (ALIGN_EPI) { if (wr == 0) PG8_BAR; }
;         E(acc, cur, wr, wc, fr, fq, ui);
	s_add_i32 s12, s39, s21
	v_lshl_add_u64 v[228:229], v[228:229], 0, s[84:85]
	s_mov_b32 m0, s12
	ds_read_b128 v[196:199], v173 offset:49152
	ds_read_b128 v[200:203], v173 offset:50176
	ds_read_b128 v[204:207], v173 offset:51200
	ds_read_b128 v[208:211], v173 offset:52224
	ds_read_b128 v[212:215], v173 offset:53248
	ds_read_b128 v[216:219], v173 offset:54272
	ds_read_b128 v[220:223], v173 offset:55296
	ds_read_b128 v[224:227], v173 offset:56320
	global_load_lds_dwordx4 v[228:229], off
	s_add_i32 m0, s12, 0x2000
	s_add_u32 s12, s16, 0x44080
	v_lshl_add_u64 v[228:229], v[230:231], 0, s[84:85]
	s_addc_u32 s13, s17, 0
	s_add_i32 s16, s40, s21
	global_load_lds_dwordx4 v[228:229], off
	v_lshl_add_u64 v[228:229], s[12:13], 0, v[134:135]
	s_mov_b32 m0, s16
	s_nop 0
	global_load_lds_dwordx4 v[228:229], off
	v_lshl_add_u64 v[228:229], s[12:13], 0, v[130:131]
	s_add_i32 m0, s16, 0x2000
	s_nop 0
	global_load_lds_dwordx4 v[228:229], off
	v_lshl_add_u64 v[228:229], v[232:233], 0, s[84:85]
	s_mov_b32 m0, s27
	s_nop 0
	global_load_lds_dwordx4 v[228:229], off
	v_lshl_add_u64 v[228:229], v[234:235], 0, s[84:85]
	s_mov_b32 m0, s28
	s_nop 0
	global_load_lds_dwordx4 v[228:229], off
	s_waitcnt vmcnt(8)
	s_waitcnt lgkmcnt(0)
	s_barrier
	s_setprio 1
	s_waitcnt lgkmcnt(0)
	v_mfma_f32_16x16x32_bf16 v[62:65], v[160:163], v[196:199], v[62:65]
	v_mfma_f32_16x16x32_bf16 v[58:61], v[168:171], v[196:199], v[58:61]
	v_mfma_f32_16x16x32_bf16 v[54:57], v[160:163], v[204:207], v[54:57]
	v_mfma_f32_16x16x32_bf16 v[46:49], v[168:171], v[204:207], v[46:49]
	v_mfma_f32_16x16x32_bf16 v[38:41], v[160:163], v[212:215], v[38:41]
	v_mfma_f32_16x16x32_bf16 v[30:33], v[168:171], v[212:215], v[30:33]
	v_mfma_f32_16x16x32_bf16 v[22:25], v[160:163], v[220:223], v[22:25]
	v_mfma_f32_16x16x32_bf16 v[14:17], v[168:171], v[220:223], v[14:17]
	v_mfma_f32_16x16x32_bf16 v[62:65], v[164:167], v[200:203], v[62:65]
	v_mfma_f32_16x16x32_bf16 v[58:61], v[174:177], v[200:203], v[58:61]
	v_mfma_f32_16x16x32_bf16 v[54:57], v[164:167], v[208:211], v[54:57]
	v_mfma_f32_16x16x32_bf16 v[46:49], v[174:177], v[208:211], v[46:49]
	v_mfma_f32_16x16x32_bf16 v[38:41], v[164:167], v[216:219], v[38:41]
	v_mfma_f32_16x16x32_bf16 v[30:33], v[174:177], v[216:219], v[30:33]
	v_mfma_f32_16x16x32_bf16 v[22:25], v[164:167], v[224:227], v[22:25]
	v_mfma_f32_16x16x32_bf16 v[14:17], v[174:177], v[224:227], v[14:17]
	s_setprio 0
	s_setprio 1
	v_mfma_f32_16x16x32_bf16 v[50:53], v[178:181], v[196:199], v[50:53]
	v_mfma_f32_16x16x32_bf16 v[42:45], v[188:191], v[196:199], v[42:45]
	v_mfma_f32_16x16x32_bf16 v[34:37], v[178:181], v[204:207], v[34:37]
	v_mfma_f32_16x16x32_bf16 v[26:29], v[188:191], v[204:207], v[26:29]
	v_mfma_f32_16x16x32_bf16 v[18:21], v[178:181], v[212:215], v[18:21]
	v_mfma_f32_16x16x32_bf16 v[10:13], v[188:191], v[212:215], v[10:13]
	v_mfma_f32_16x16x32_bf16 v[6:9], v[178:181], v[220:223], v[6:9]
	v_mfma_f32_16x16x32_bf16 v[2:5], v[188:191], v[220:223], v[2:5]
	v_mfma_f32_16x16x32_bf16 v[50:53], v[184:187], v[200:203], v[50:53]
	v_mfma_f32_16x16x32_bf16 v[42:45], v[192:195], v[200:203], v[42:45]
	v_mfma_f32_16x16x32_bf16 v[34:37], v[184:187], v[208:211], v[34:37]
	v_mfma_f32_16x16x32_bf16 v[26:29], v[192:195], v[208:211], v[26:29]
	v_mfma_f32_16x16x32_bf16 v[18:21], v[184:187], v[216:219], v[18:21]
	v_mfma_f32_16x16x32_bf16 v[10:13], v[192:195], v[216:219], v[10:13]
	v_mfma_f32_16x16x32_bf16 v[6:9], v[184:187], v[224:227], v[6:9]
	v_mfma_f32_16x16x32_bf16 v[2:5], v[192:195], v[224:227], v[2:5]
	s_setprio 0
	s_add_i32 s38, s38, 2
	s_add_u32 s36, s36, 0x100
	s_addc_u32 s37, s37, 0
	s_cmp_gt_u32 s38, 13
	s_mov_b64 s[12:13], s[14:15]
	s_cbranch_scc1 .Lrot_exit_669
	s_add_u32 s14, s12, 0x100
	s_addc_u32 s15, s13, 0
	s_add_i32 s39, 0, 0x10000
	s_cmp_eq_u32 s38, 12
	s_cselect_b32 s19, s5, s15
	s_cselect_b32 s18, s4, s14
	s_cselect_b32 s17, s11, s37
	s_cselect_b32 s16, s10, s36
	s_add_i32 s40, 0, 0x14000
	v_add_u32_e32 v174, s39, v139
	v_add_u32_e32 v192, s40, v139
	s_branch .LBB0_669
.Lrot_exit_669:
	s_barrier
	s_and_b64 vcc, exec, s[8:9]
	s_cbranch_vccz .LBB0_672
	s_barrier

; #define PG8_STAGE(bufoff, gbase, voff) do { _Pragma("unroll") for (int _i = 0; _i < 2; ++_i) \
;         __builtin_amdgcn_global_load_lds((const unsigned*)((const char*)(gbase) + (voff)[_i]), (LAS unsigned*)(lds + (bufoff) + ldsw + _i * 8192), 16, 0, 0); } while (0)
; #define PG8_LDA(dst, b, h) do { _Pragma("unroll") for (int m = 0; m < 4; ++m) _Pragma("unroll") for (int k = 0; k < 2; ++k) dst[m][k] = *(const LAS bf16x8*)(lds + PG8_SA(b, h) + aoff + m * 2048 + k * 1024); } while (0)
; #define PG8_LDB(dst, b, h) do { _Pragma("unroll") for (int n = 0; n < 2; ++n) _Pragma("unroll") for (int k = 0; k < 2; ++k) dst[n][k] = *(const LAS bf16x8*)(lds + PG8_SB(b, h) + boff + n * 2048 + k * 1024); } while (0)
; #define PG8_MMA(ai, bj, At, Bt) do { __builtin_amdgcn_s_setprio(1); _Pragma("unroll") for (int m = 0; m < 4; ++m) _Pragma("unroll") for (int n = 0; n < 2; ++n) _Pragma("unroll") for (int k = 0; k < 2; ++k) \
;         acc[ai][bj][m][n] = __builtin_amdgcn_mfma_f32_16x16x32_bf16(Bt[n][k], At[m][k], acc[ai][bj][m][n], 0, 0, 0); __builtin_amdgcn_s_setprio(0); } while (0)
; #define PG8_WAIT_V(n) asm volatile("s_waitcnt vmcnt(" #n ")" ::: "memory")
; #define PG8_WAIT_L(n) asm volatile("s_waitcnt lgkmcnt(" #n ")" ::: "memory")
; #define PG8_BAR __builtin_amdgcn_s_barrier()
; #define PG8_SCHED __builtin_amdgcn_sched_barrier(0)
; template <class Epi, bool ALIGN_EPI = PG8_ALIGN, bool SP2 = PG8_SP2>
; __device__ __forceinline__ void gemm_phase(LAS uchar* lds, const Gemm g, const StaticOrder& S, const Epi& E) {
;     ...
;             const char* a1 = cA + (size_t)(t + 1) * kstep;
;             const char* a2 = last ? nA : cA + (size_t)(t + 2) * kstep; const char* b2 = last ? nB : cB + (size_t)(t + 2) * kstep;
;             const char* a3 = a2 + kstep; const char* b3 = b2 + kstep;
;             if constexpr (SP2) {
;             PG8_LDB(B0, 0, 0); PG8_LDB(B1, 0, 1); PG8_SCHED; PG8_LDA(At, 0, 0); PG8_STAGE(PG8_SA(1, 1), a1 + hstepA, voffA);
;             PG8_WAIT_V(8); PG8_WAIT_L(0); PG8_BAR; PG8_MMA(0, 0, At, B0); PG8_MMA(0, 1, At, B1); PG8_BAR; PG8_SCHED;
;             PG8_LDA(At, 0, 1); PG8_STAGE(PG8_SB(0, 0), b2, voffB); PG8_STAGE(PG8_SB(0, 1), b2 + hstepB, voffB); PG8_STAGE(PG8_SA(0, 0), a2, voffA);
;             PG8_WAIT_V(8); PG8_WAIT_L(0); PG8_BAR; PG8_MMA(1, 0, At, B0); PG8_MMA(1, 1, At, B1); PG8_BAR; PG8_SCHED;
.LBB0_836:
	s_add_u32 s36, s14, 0x100
	s_addc_u32 s37, s15, 0
	s_mov_b32 s38, -2
	s_add_u32 s14, s12, 0x100
	s_addc_u32 s15, s13, 0
	s_add_i32 s39, 0, 0x10000
	s_cmp_eq_u32 s38, 12
	s_cselect_b32 s19, s5, s15
	s_cselect_b32 s18, s4, s14
	s_cselect_b32 s17, s11, s37
	s_cselect_b32 s16, s10, s36
	s_add_i32 s40, 0, 0x14000
	v_add_u32_e32 v174, s39, v139
	v_add_u32_e32 v192, s40, v139
	ds_read_b128 v[160:163], v174
	ds_read_b128 v[166:169], v174 offset:1024
	ds_read_b128 v[170:173], v174 offset:2048
	ds_read_b128 v[174:177], v174 offset:3072
	ds_read_b128 v[178:181], v192
	ds_read_b128 v[184:187], v192 offset:1024
	ds_read_b128 v[188:191], v192 offset:2048
	ds_read_b128 v[192:195], v192 offset:3072
	v_lshl_add_u64 v[228:229], s[12:13], 0, v[156:157]
	s_add_i32 m0, s23, 0xc000
	ds_read_b128 v[196:199], v165
	ds_read_b128 v[200:203], v165 offset:1024
	ds_read_b128 v[204:207], v165 offset:2048
	ds_read_b128 v[208:211], v165 offset:3072
	ds_read_b128 v[212:215], v165 offset:4096
	ds_read_b128 v[216:219], v165 offset:5120
	ds_read_b128 v[220:223], v165 offset:6144
	ds_read_b128 v[224:227], v165 offset:7168
	global_load_lds_dwordx4 v[228:229], off
	v_lshl_add_u64 v[228:229], s[12:13], 0, v[158:159]
	s_add_i32 m0, s23, 0xe000
	s_nop 0
	global_load_lds_dwordx4 v[228:229], off
	s_waitcnt vmcnt(8)
	s_waitcnt lgkmcnt(0)
	s_barrier
	s_setprio 1
	s_waitcnt lgkmcnt(0)
	v_mfma_f32_16x16x32_bf16 v[126:129], v[160:163], v[196:199], 0
	v_mfma_f32_16x16x32_bf16 v[122:125], v[170:173], v[196:199], 0
	v_mfma_f32_16x16x32_bf16 v[118:121], v[160:163], v[204:207], 0
	v_mfma_f32_16x16x32_bf16 v[110:113], v[170:173], v[204:207], 0
	v_mfma_f32_16x16x32_bf16 v[102:105], v[160:163], v[212:215], 0
	v_mfma_f32_16x16x32_bf16 v[94:97], v[170:173], v[212:215], 0
	v_mfma_f32_16x16x32_bf16 v[86:89], v[160:163], v[220:223], 0
	v_mfma_f32_16x16x32_bf16 v[78:81], v[170:173], v[220:223], 0
	v_mfma_f32_16x16x32_bf16 v[126:129], v[166:169], v[200:203], v[126:129]
	v_mfma_f32_16x16x32_bf16 v[122:125], v[174:177], v[200:203], v[122:125]
	v_mfma_f32_16x16x32_bf16 v[118:121], v[166:169], v[208:211], v[118:121]
	v_mfma_f32_16x16x32_bf16 v[110:113], v[174:177], v[208:211], v[110:113]
	v_mfma_f32_16x16x32_bf16 v[102:105], v[166:169], v[216:219], v[102:105]
	v_mfma_f32_16x16x32_bf16 v[94:97], v[174:177], v[216:219], v[94:97]
	v_mfma_f32_16x16x32_bf16 v[86:89], v[166:169], v[224:227], v[86:89]
	v_mfma_f32_16x16x32_bf16 v[78:81], v[174:177], v[224:227], v[78:81]
	s_setprio 0
	s_setprio 1
	v_mfma_f32_16x16x32_bf16 v[114:117], v[178:181], v[196:199], 0
	v_mfma_f32_16x16x32_bf16 v[106:109], v[188:191], v[196:199], 0
	v_mfma_f32_16x16x32_bf16 v[98:101], v[178:181], v[204:207], 0
	v_mfma_f32_16x16x32_bf16 v[90:93], v[188:191], v[204:207], 0
	v_mfma_f32_16x16x32_bf16 v[82:85], v[178:181], v[212:215], 0
	v_mfma_f32_16x16x32_bf16 v[74:77], v[188:191], v[212:215], 0
	v_mfma_f32_16x16x32_bf16 v[70:73], v[178:181], v[220:223], 0
	v_mfma_f32_16x16x32_bf16 v[66:69], v[188:191], v[220:223], 0
	v_mfma_f32_16x16x32_bf16 v[114:117], v[184:187], v[200:203], v[114:117]
	v_mfma_f32_16x16x32_bf16 v[106:109], v[192:195], v[200:203], v[106:109]
	v_mfma_f32_16x16x32_bf16 v[98:101], v[184:187], v[208:211], v[98:101]
	v_mfma_f32_16x16x32_bf16 v[90:93], v[192:195], v[208:211], v[90:93]
	v_mfma_f32_16x16x32_bf16 v[82:85], v[184:187], v[216:219], v[82:85]
	v_mfma_f32_16x16x32_bf16 v[74:77], v[192:195], v[216:219], v[74:77]
	v_mfma_f32_16x16x32_bf16 v[70:73], v[184:187], v[224:227], v[70:73]
	v_mfma_f32_16x16x32_bf16 v[66:69], v[192:195], v[224:227], v[66:69]
	s_setprio 0
	s_barrier
	s_add_i32 s12, s39, s22
	v_lshl_add_u64 v[228:229], s[16:17], 0, v[132:133]
	s_mov_b32 m0, s12
	ds_read_b128 v[196:199], v165 offset:16384
	ds_read_b128 v[200:203], v165 offset:17408
	ds_read_b128 v[204:207], v165 offset:18432
	ds_read_b128 v[208:211], v165 offset:19456
	ds_read_b128 v[212:215], v165 offset:20480
	ds_read_b128 v[216:219], v165 offset:21504
	ds_read_b128 v[220:223], v165 offset:22528
	ds_read_b128 v[224:227], v165 offset:23552
	global_load_lds_dwordx4 v[228:229], off
	s_add_i32 m0, s12, 0x2000
	s_add_u32 s12, s16, 0x44000
	v_lshl_add_u64 v[230:231], s[16:17], 0, v[152:153]
	s_addc_u32 s13, s17, 0
	s_add_i32 s39, s40, s22
	global_load_lds_dwordx4 v[230:231], off
	v_lshl_add_u64 v[232:233], s[12:13], 0, v[132:133]
	s_mov_b32 m0, s39
	v_lshl_add_u64 v[234:235], s[18:19], 0, v[134:135]
	global_load_lds_dwordx4 v[232:233], off
	v_lshl_add_u64 v[232:233], s[12:13], 0, v[152:153]
	s_add_i32 m0, s39, 0x2000
	s_nop 0
	global_load_lds_dwordx4 v[232:233], off
	v_lshl_add_u64 v[232:233], s[18:19], 0, v[130:131]
	s_mov_b32 m0, s23
	s_nop 0
	global_load_lds_dwordx4 v[232:233], off
	s_mov_b32 m0, s24
	s_nop 0
	global_load_lds_dwordx4 v[234:235], off
	s_waitcnt vmcnt(8)
	s_waitcnt lgkmcnt(0)
	s_barrier
; #define PG8_STAGE(bufoff, gbase, voff) do { _Pragma("unroll") for (int _i = 0; _i < 2; ++_i) \
;         __builtin_amdgcn_global_load_lds((const unsigned*)((const char*)(gbase) + (voff)[_i]), (LAS unsigned*)(lds + (bufoff) + ldsw + _i * 8192), 16, 0, 0); } while (0)
; #define PG8_LDA(dst, b, h) do { _Pragma("unroll") for (int m = 0; m < 4; ++m) _Pragma("unroll") for (int k = 0; k < 2; ++k) dst[m][k] = *(const LAS bf16x8*)(lds + PG8_SA(b, h) + aoff + m * 2048 + k * 1024); } while (0)
; #define PG8_LDB(dst, b, h) do { _Pragma("unroll") for (int n = 0; n < 2; ++n) _Pragma("unroll") for (int k = 0; k < 2; ++k) dst[n][k] = *(const LAS bf16x8*)(lds + PG8_SB(b, h) + boff + n * 2048 + k * 1024); } while (0)
; #define PG8_MMA(ai, bj, At, Bt) do { __builtin_amdgcn_s_setprio(1); _Pragma("unroll") for (int m = 0; m < 4; ++m) _Pragma("unroll") for (int n = 0; n < 2; ++n) _Pragma("unroll") for (int k = 0; k < 2; ++k) \
;         acc[ai][bj][m][n] = __builtin_amdgcn_mfma_f32_16x16x32_bf16(Bt[n][k], At[m][k], acc[ai][bj][m][n], 0, 0, 0); __builtin_amdgcn_s_setprio(0); } while (0)
; #define PG8_WAIT_V(n) asm volatile("s_waitcnt vmcnt(" #n ")" ::: "memory")
; #define PG8_WAIT_L(n) asm volatile("s_waitcnt lgkmcnt(" #n ")" ::: "memory")
; #define PG8_BAR __builtin_amdgcn_s_barrier()
; #define PG8_SCHED __builtin_amdgcn_sched_barrier(0)
; template <class Epi, bool ALIGN_EPI = PG8_ALIGN, bool SP2 = PG8_SP2>
; __device__ __forceinline__ void gemm_phase(LAS uchar* lds, const Gemm g, const StaticOrder& S, const Epi& E) {
;     ...
;             PG8_WAIT_V(8); PG8_WAIT_L(0); PG8_BAR; PG8_MMA(1, 0, At, B0); PG8_MMA(1, 1, At, B1); PG8_BAR; PG8_SCHED;
;             PG8_LDB(B0, 1, 0); PG8_LDB(B1, 1, 1); PG8_SCHED; PG8_LDA(At, 1, 0); PG8_STAGE(PG8_SA(0, 1), a2 + hstepA, voffA);
;             PG8_WAIT_V(8); PG8_WAIT_L(0); PG8_BAR; PG8_MMA(0, 0, At, B0); PG8_MMA(0, 1, At, B1); PG8_BAR; PG8_SCHED;
	s_setprio 1
	s_waitcnt lgkmcnt(0)
	v_mfma_f32_16x16x32_bf16 v[62:65], v[160:163], v[196:199], 0
	v_mfma_f32_16x16x32_bf16 v[58:61], v[170:173], v[196:199], 0
	v_mfma_f32_16x16x32_bf16 v[54:57], v[160:163], v[204:207], 0
	v_mfma_f32_16x16x32_bf16 v[46:49], v[170:173], v[204:207], 0
	v_mfma_f32_16x16x32_bf16 v[38:41], v[160:163], v[212:215], 0
	v_mfma_f32_16x16x32_bf16 v[30:33], v[170:173], v[212:215], 0
	v_mfma_f32_16x16x32_bf16 v[22:25], v[160:163], v[220:223], 0
	v_mfma_f32_16x16x32_bf16 v[14:17], v[170:173], v[220:223], 0
	v_mfma_f32_16x16x32_bf16 v[62:65], v[166:169], v[200:203], v[62:65]
	v_mfma_f32_16x16x32_bf16 v[58:61], v[174:177], v[200:203], v[58:61]
	v_mfma_f32_16x16x32_bf16 v[54:57], v[166:169], v[208:211], v[54:57]
	v_mfma_f32_16x16x32_bf16 v[46:49], v[174:177], v[208:211], v[46:49]
	v_mfma_f32_16x16x32_bf16 v[38:41], v[166:169], v[216:219], v[38:41]
	v_mfma_f32_16x16x32_bf16 v[30:33], v[174:177], v[216:219], v[30:33]
	v_mfma_f32_16x16x32_bf16 v[22:25], v[166:169], v[224:227], v[22:25]
	v_mfma_f32_16x16x32_bf16 v[14:17], v[174:177], v[224:227], v[14:17]
	s_setprio 0
	s_setprio 1
	v_mfma_f32_16x16x32_bf16 v[50:53], v[178:181], v[196:199], 0
	v_mfma_f32_16x16x32_bf16 v[42:45], v[188:191], v[196:199], 0
	v_mfma_f32_16x16x32_bf16 v[34:37], v[178:181], v[204:207], 0
	v_mfma_f32_16x16x32_bf16 v[26:29], v[188:191], v[204:207], 0
	v_mfma_f32_16x16x32_bf16 v[18:21], v[178:181], v[212:215], 0
	v_mfma_f32_16x16x32_bf16 v[10:13], v[188:191], v[212:215], 0
	v_mfma_f32_16x16x32_bf16 v[6:9], v[178:181], v[220:223], 0
	v_mfma_f32_16x16x32_bf16 v[2:5], v[188:191], v[220:223], 0
	v_mfma_f32_16x16x32_bf16 v[50:53], v[184:187], v[200:203], v[50:53]
	v_mfma_f32_16x16x32_bf16 v[42:45], v[192:195], v[200:203], v[42:45]
	v_mfma_f32_16x16x32_bf16 v[34:37], v[184:187], v[208:211], v[34:37]
	v_mfma_f32_16x16x32_bf16 v[26:29], v[192:195], v[208:211], v[26:29]
	v_mfma_f32_16x16x32_bf16 v[18:21], v[184:187], v[216:219], v[18:21]
	v_mfma_f32_16x16x32_bf16 v[10:13], v[192:195], v[216:219], v[10:13]
	v_mfma_f32_16x16x32_bf16 v[6:9], v[184:187], v[224:227], v[6:9]
	v_mfma_f32_16x16x32_bf16 v[2:5], v[192:195], v[224:227], v[2:5]
	s_setprio 0
	s_barrier
	s_add_i32 s39, 0, 0x18000
	s_add_i32 s40, 0, 0x1c000
	v_add_u32_e32 v174, s39, v139
	v_add_u32_e32 v192, s40, v139
	ds_read_b128 v[160:163], v174
	ds_read_b128 v[166:169], v174 offset:1024
	ds_read_b128 v[170:173], v174 offset:2048
	ds_read_b128 v[174:177], v174 offset:3072
	ds_read_b128 v[178:181], v192
	ds_read_b128 v[184:187], v192 offset:1024
	ds_read_b128 v[188:191], v192 offset:2048
	ds_read_b128 v[192:195], v192 offset:3072
	s_add_u32 s12, s18, 0x44000
	s_addc_u32 s13, s19, 0
	s_mov_b32 m0, s25
	v_lshl_add_u64 v[236:237], s[12:13], 0, v[130:131]
	ds_read_b128 v[196:199], v165 offset:32768
	ds_read_b128 v[200:203], v165 offset:33792
	ds_read_b128 v[204:207], v165 offset:34816
	ds_read_b128 v[208:211], v165 offset:35840
	ds_read_b128 v[212:215], v165 offset:36864
	ds_read_b128 v[216:219], v165 offset:37888
	ds_read_b128 v[220:223], v165 offset:38912
	ds_read_b128 v[224:227], v165 offset:39936
	global_load_lds_dwordx4 v[236:237], off
	v_lshl_add_u64 v[236:237], s[12:13], 0, v[134:135]
	s_mov_b32 m0, s26
	s_nop 0
	global_load_lds_dwordx4 v[236:237], off
	s_waitcnt vmcnt(8)
	s_waitcnt lgkmcnt(0)
	s_barrier
	s_setprio 1
	s_waitcnt lgkmcnt(0)
	v_mfma_f32_16x16x32_bf16 v[126:129], v[160:163], v[196:199], v[126:129]
	v_mfma_f32_16x16x32_bf16 v[122:125], v[170:173], v[196:199], v[122:125]
	v_mfma_f32_16x16x32_bf16 v[118:121], v[160:163], v[204:207], v[118:121]
	v_mfma_f32_16x16x32_bf16 v[110:113], v[170:173], v[204:207], v[110:113]
	v_mfma_f32_16x16x32_bf16 v[102:105], v[160:163], v[212:215], v[102:105]
	v_mfma_f32_16x16x32_bf16 v[94:97], v[170:173], v[212:215], v[94:97]
	v_mfma_f32_16x16x32_bf16 v[86:89], v[160:163], v[220:223], v[86:89]
	v_mfma_f32_16x16x32_bf16 v[78:81], v[170:173], v[220:223], v[78:81]
	v_mfma_f32_16x16x32_bf16 v[126:129], v[166:169], v[200:203], v[126:129]
	v_mfma_f32_16x16x32_bf16 v[122:125], v[174:177], v[200:203], v[122:125]
	v_mfma_f32_16x16x32_bf16 v[118:121], v[166:169], v[208:211], v[118:121]
	v_mfma_f32_16x16x32_bf16 v[110:113], v[174:177], v[208:211], v[110:113]
	v_mfma_f32_16x16x32_bf16 v[102:105], v[166:169], v[216:219], v[102:105]
	v_mfma_f32_16x16x32_bf16 v[94:97], v[174:177], v[216:219], v[94:97]
	v_mfma_f32_16x16x32_bf16 v[86:89], v[166:169], v[224:227], v[86:89]
	v_mfma_f32_16x16x32_bf16 v[78:81], v[174:177], v[224:227], v[78:81]
	s_setprio 0
	s_setprio 1
	v_mfma_f32_16x16x32_bf16 v[114:117], v[178:181], v[196:199], v[114:117]
	v_mfma_f32_16x16x32_bf16 v[106:109], v[188:191], v[196:199], v[106:109]
	v_mfma_f32_16x16x32_bf16 v[98:101], v[178:181], v[204:207], v[98:101]
	v_mfma_f32_16x16x32_bf16 v[90:93], v[188:191], v[204:207], v[90:93]
	v_mfma_f32_16x16x32_bf16 v[82:85], v[178:181], v[212:215], v[82:85]
	v_mfma_f32_16x16x32_bf16 v[74:77], v[188:191], v[212:215], v[74:77]
	v_mfma_f32_16x16x32_bf16 v[70:73], v[178:181], v[220:223], v[70:73]
	v_mfma_f32_16x16x32_bf16 v[66:69], v[188:191], v[220:223], v[66:69]
	v_mfma_f32_16x16x32_bf16 v[114:117], v[184:187], v[200:203], v[114:117]
	v_mfma_f32_16x16x32_bf16 v[106:109], v[192:195], v[200:203], v[106:109]
	v_mfma_f32_16x16x32_bf16 v[98:101], v[184:187], v[208:211], v[98:101]
	v_mfma_f32_16x16x32_bf16 v[90:93], v[192:195], v[208:211], v[90:93]
	v_mfma_f32_16x16x32_bf16 v[82:85], v[184:187], v[216:219], v[82:85]
	v_mfma_f32_16x16x32_bf16 v[74:77], v[192:195], v[216:219], v[74:77]
	v_mfma_f32_16x16x32_bf16 v[70:73], v[184:187], v[224:227], v[70:73]
	v_mfma_f32_16x16x32_bf16 v[66:69], v[192:195], v[224:227], v[66:69]
	s_setprio 0
	s_barrier
; #define PG8_STAGE(bufoff, gbase, voff) do { _Pragma("unroll") for (int _i = 0; _i < 2; ++_i) \
;         __builtin_amdgcn_global_load_lds((const unsigned*)((const char*)(gbase) + (voff)[_i]), (LAS unsigned*)(lds + (bufoff) + ldsw + _i * 8192), 16, 0, 0); } while (0)
; #define PG8_LDA(dst, b, h) do { _Pragma("unroll") for (int m = 0; m < 4; ++m) _Pragma("unroll") for (int k = 0; k < 2; ++k) dst[m][k] = *(const LAS bf16x8*)(lds + PG8_SA(b, h) + aoff + m * 2048 + k * 1024); } while (0)
; #define PG8_LDB(dst, b, h) do { _Pragma("unroll") for (int n = 0; n < 2; ++n) _Pragma("unroll") for (int k = 0; k < 2; ++k) dst[n][k] = *(const LAS bf16x8*)(lds + PG8_SB(b, h) + boff + n * 2048 + k * 1024); } while (0)
; #define PG8_BAR __builtin_amdgcn_s_barrier()
; template <class Epi, bool ALIGN_EPI = PG8_ALIGN, bool SP2 = PG8_SP2>
; __device__ __forceinline__ void gemm_phase(LAS uchar* lds, const Gemm g, const StaticOrder& S, const Epi& E) {
;     ...
;         for (int t = tb; t < tb + tblk; t += 2) {
;             const bool last = (t == nt - 2);
;             const char* a1 = cA + (size_t)(t + 1) * kstep;
;             const char* a2 = last ? nA : cA + (size_t)(t + 2) * kstep; const char* b2 = last ? nB : cB + (size_t)(t + 2) * kstep;
;             const char* a3 = a2 + kstep; const char* b3 = b2 + kstep;
;             if constexpr (SP2) {
;             PG8_LDB(B0, 0, 0); PG8_LDB(B1, 0, 1); PG8_SCHED; PG8_LDA(At, 0, 0); PG8_STAGE(PG8_SA(1, 1), a1 + hstepA, voffA);
;             PG8_WAIT_V(8); PG8_WAIT_L(0); PG8_BAR; PG8_MMA(0, 0, At, B0); PG8_MMA(0, 1, At, B1); PG8_BAR; PG8_SCHED;
;             PG8_LDA(At, 0, 1); PG8_STAGE(PG8_SB(0, 0), b2, voffB); PG8_STAGE(PG8_SB(0, 1), b2 + hstepB, voffB); PG8_STAGE(PG8_SA(0, 0), a2, voffA);
;             PG8_WAIT_V(8); PG8_WAIT_L(0); PG8_BAR; PG8_MMA(1, 0, At, B0); PG8_MMA(1, 1, At, B1); PG8_BAR; PG8_SCHED;
;             PG8_LDB(B0, 1, 0); PG8_LDB(B1, 1, 1); PG8_SCHED; PG8_LDA(At, 1, 0); PG8_STAGE(PG8_SA(0, 1), a2 + hstepA, voffA);
;             PG8_WAIT_V(8); PG8_WAIT_L(0); PG8_BAR; PG8_MMA(0, 0, At, B0); PG8_MMA(0, 1, At, B1); PG8_BAR; PG8_SCHED;
;             PG8_LDA(At, 1, 1); PG8_STAGE(PG8_SB(1, 0), b3, voffB); PG8_STAGE(PG8_SB(1, 1), b3 + hstepB, voffB); PG8_STAGE(PG8_SA(1, 0), a3, voffA);
;             PG8_WAIT_V(8); PG8_WAIT_L(0); PG8_BAR; PG8_MMA(1, 0, At, B0); PG8_MMA(1, 1, At, B1); PG8_BAR; PG8_SCHED;
	s_add_i32 s12, s39, s22
	v_lshl_add_u64 v[228:229], v[228:229], 0, s[84:85]
	s_mov_b32 m0, s12
	ds_read_b128 v[196:199], v165 offset:49152
	ds_read_b128 v[200:203], v165 offset:50176
	ds_read_b128 v[204:207], v165 offset:51200
	ds_read_b128 v[208:211], v165 offset:52224
	ds_read_b128 v[212:215], v165 offset:53248
	ds_read_b128 v[216:219], v165 offset:54272
	ds_read_b128 v[220:223], v165 offset:55296
	ds_read_b128 v[224:227], v165 offset:56320
	global_load_lds_dwordx4 v[228:229], off
	s_add_i32 m0, s12, 0x2000
	s_add_u32 s12, s16, 0x44080
	v_lshl_add_u64 v[228:229], v[230:231], 0, s[84:85]
	s_addc_u32 s13, s17, 0
	s_add_i32 s16, s40, s22
	global_load_lds_dwordx4 v[228:229], off
	v_lshl_add_u64 v[228:229], s[12:13], 0, v[132:133]
	s_mov_b32 m0, s16
	s_nop 0
	global_load_lds_dwordx4 v[228:229], off
	v_lshl_add_u64 v[228:229], s[12:13], 0, v[152:153]
	s_add_i32 m0, s16, 0x2000
	s_nop 0
	global_load_lds_dwordx4 v[228:229], off
	v_lshl_add_u64 v[228:229], v[232:233], 0, s[84:85]
	s_mov_b32 m0, s27
	s_nop 0
	global_load_lds_dwordx4 v[228:229], off
	v_lshl_add_u64 v[228:229], v[234:235], 0, s[84:85]
	s_mov_b32 m0, s28
	s_nop 0
	global_load_lds_dwordx4 v[228:229], off
	s_waitcnt vmcnt(8)
	s_waitcnt lgkmcnt(0)
	s_barrier
	s_setprio 1
	s_waitcnt lgkmcnt(0)
	v_mfma_f32_16x16x32_bf16 v[62:65], v[160:163], v[196:199], v[62:65]
	v_mfma_f32_16x16x32_bf16 v[58:61], v[170:173], v[196:199], v[58:61]
	v_mfma_f32_16x16x32_bf16 v[54:57], v[160:163], v[204:207], v[54:57]
	v_mfma_f32_16x16x32_bf16 v[46:49], v[170:173], v[204:207], v[46:49]
	v_mfma_f32_16x16x32_bf16 v[38:41], v[160:163], v[212:215], v[38:41]
	v_mfma_f32_16x16x32_bf16 v[30:33], v[170:173], v[212:215], v[30:33]
	v_mfma_f32_16x16x32_bf16 v[22:25], v[160:163], v[220:223], v[22:25]
	v_mfma_f32_16x16x32_bf16 v[14:17], v[170:173], v[220:223], v[14:17]
	v_mfma_f32_16x16x32_bf16 v[62:65], v[166:169], v[200:203], v[62:65]
	v_mfma_f32_16x16x32_bf16 v[58:61], v[174:177], v[200:203], v[58:61]
	v_mfma_f32_16x16x32_bf16 v[54:57], v[166:169], v[208:211], v[54:57]
	v_mfma_f32_16x16x32_bf16 v[46:49], v[174:177], v[208:211], v[46:49]
	v_mfma_f32_16x16x32_bf16 v[38:41], v[166:169], v[216:219], v[38:41]
	v_mfma_f32_16x16x32_bf16 v[30:33], v[174:177], v[216:219], v[30:33]
	v_mfma_f32_16x16x32_bf16 v[22:25], v[166:169], v[224:227], v[22:25]
	v_mfma_f32_16x16x32_bf16 v[14:17], v[174:177], v[224:227], v[14:17]
	s_setprio 0
	s_setprio 1
	v_mfma_f32_16x16x32_bf16 v[50:53], v[178:181], v[196:199], v[50:53]
	v_mfma_f32_16x16x32_bf16 v[42:45], v[188:191], v[196:199], v[42:45]
	v_mfma_f32_16x16x32_bf16 v[34:37], v[178:181], v[204:207], v[34:37]
	v_mfma_f32_16x16x32_bf16 v[26:29], v[188:191], v[204:207], v[26:29]
	v_mfma_f32_16x16x32_bf16 v[18:21], v[178:181], v[212:215], v[18:21]
	v_mfma_f32_16x16x32_bf16 v[10:13], v[188:191], v[212:215], v[10:13]
	v_mfma_f32_16x16x32_bf16 v[6:9], v[178:181], v[220:223], v[6:9]
	v_mfma_f32_16x16x32_bf16 v[2:5], v[188:191], v[220:223], v[2:5]
	v_mfma_f32_16x16x32_bf16 v[50:53], v[184:187], v[200:203], v[50:53]
	v_mfma_f32_16x16x32_bf16 v[42:45], v[192:195], v[200:203], v[42:45]
	v_mfma_f32_16x16x32_bf16 v[34:37], v[184:187], v[208:211], v[34:37]
	v_mfma_f32_16x16x32_bf16 v[26:29], v[192:195], v[208:211], v[26:29]
	v_mfma_f32_16x16x32_bf16 v[18:21], v[184:187], v[216:219], v[18:21]
	v_mfma_f32_16x16x32_bf16 v[10:13], v[192:195], v[216:219], v[10:13]
	v_mfma_f32_16x16x32_bf16 v[6:9], v[184:187], v[224:227], v[6:9]
	v_mfma_f32_16x16x32_bf16 v[2:5], v[192:195], v[224:227], v[2:5]
	s_setprio 0
	s_add_i32 s38, s38, 2
	s_add_u32 s36, s36, 0x100
	s_addc_u32 s37, s37, 0
	s_cmp_gt_u32 s38, 13
	s_mov_b64 s[12:13], s[14:15]
	s_add_u32 s14, s12, 0x100
	s_addc_u32 s15, s13, 0
	s_add_i32 s39, 0, 0x10000
	s_cmp_eq_u32 s38, 12
	s_cselect_b32 s19, s5, s15
	s_cselect_b32 s18, s4, s14
	s_cselect_b32 s17, s11, s37
	s_cselect_b32 s16, s10, s36
	s_add_i32 s40, 0, 0x14000
	v_add_u32_e32 v174, s39, v139
	v_add_u32_e32 v192, s40, v139
.LBB0_837:
	s_barrier
	ds_read_b128 v[160:163], v174
	ds_read_b128 v[166:169], v174 offset:1024
	ds_read_b128 v[170:173], v174 offset:2048
	ds_read_b128 v[174:177], v174 offset:3072
	ds_read_b128 v[178:181], v192
	ds_read_b128 v[184:187], v192 offset:1024
	ds_read_b128 v[188:191], v192 offset:2048
	ds_read_b128 v[192:195], v192 offset:3072
	v_lshl_add_u64 v[228:229], s[12:13], 0, v[156:157]
	s_add_i32 m0, s23, 0xc000
	ds_read_b128 v[196:199], v165
	ds_read_b128 v[200:203], v165 offset:1024
	ds_read_b128 v[204:207], v165 offset:2048
	ds_read_b128 v[208:211], v165 offset:3072
	ds_read_b128 v[212:215], v165 offset:4096
	ds_read_b128 v[216:219], v165 offset:5120
	ds_read_b128 v[220:223], v165 offset:6144
	ds_read_b128 v[224:227], v165 offset:7168
	global_load_lds_dwordx4 v[228:229], off
	v_lshl_add_u64 v[228:229], s[12:13], 0, v[158:159]
	s_add_i32 m0, s23, 0xe000
	s_nop 0
	global_load_lds_dwordx4 v[228:229], off
	s_waitcnt vmcnt(8)
	s_waitcnt lgkmcnt(0)
	s_barrier
; #define PG8_STAGE(bufoff, gbase, voff) do { _Pragma("unroll") for (int _i = 0; _i < 2; ++_i) \
;         __builtin_amdgcn_global_load_lds((const unsigned*)((const char*)(gbase) + (voff)[_i]), (LAS unsigned*)(lds + (bufoff) + ldsw + _i * 8192), 16, 0, 0); } while (0)
; #define PG8_LDA(dst, b, h) do { _Pragma("unroll") for (int m = 0; m < 4; ++m) _Pragma("unroll") for (int k = 0; k < 2; ++k) dst[m][k] = *(const LAS bf16x8*)(lds + PG8_SA(b, h) + aoff + m * 2048 + k * 1024); } while (0)
; #define PG8_MMA(ai, bj, At, Bt) do { __builtin_amdgcn_s_setprio(1); _Pragma("unroll") for (int m = 0; m < 4; ++m) _Pragma("unroll") for (int n = 0; n < 2; ++n) _Pragma("unroll") for (int k = 0; k < 2; ++k) \
;         acc[ai][bj][m][n] = __builtin_amdgcn_mfma_f32_16x16x32_bf16(Bt[n][k], At[m][k], acc[ai][bj][m][n], 0, 0, 0); __builtin_amdgcn_s_setprio(0); } while (0)
; #define PG8_WAIT_V(n) asm volatile("s_waitcnt vmcnt(" #n ")" ::: "memory")
; #define PG8_WAIT_L(n) asm volatile("s_waitcnt lgkmcnt(" #n ")" ::: "memory")
; #define PG8_BAR __builtin_amdgcn_s_barrier()
; #define PG8_SCHED __builtin_amdgcn_sched_barrier(0)
; template <class Epi, bool ALIGN_EPI = PG8_ALIGN, bool SP2 = PG8_SP2>
; __device__ __forceinline__ void gemm_phase(LAS uchar* lds, const Gemm g, const StaticOrder& S, const Epi& E) {
;     ...
;             PG8_WAIT_V(8); PG8_WAIT_L(0); PG8_BAR; PG8_MMA(0, 0, At, B0); PG8_MMA(0, 1, At, B1); PG8_BAR; PG8_SCHED;
;             PG8_LDA(At, 0, 1); PG8_STAGE(PG8_SB(0, 0), b2, voffB); PG8_STAGE(PG8_SB(0, 1), b2 + hstepB, voffB); PG8_STAGE(PG8_SA(0, 0), a2, voffA);
;             PG8_WAIT_V(8); PG8_WAIT_L(0); PG8_BAR; PG8_MMA(1, 0, At, B0); PG8_MMA(1, 1, At, B1); PG8_BAR; PG8_SCHED;
	s_setprio 1
	s_waitcnt lgkmcnt(0)
	v_mfma_f32_16x16x32_bf16 v[126:129], v[160:163], v[196:199], v[126:129]
	v_mfma_f32_16x16x32_bf16 v[122:125], v[170:173], v[196:199], v[122:125]
	v_mfma_f32_16x16x32_bf16 v[118:121], v[160:163], v[204:207], v[118:121]
	v_mfma_f32_16x16x32_bf16 v[110:113], v[170:173], v[204:207], v[110:113]
	v_mfma_f32_16x16x32_bf16 v[102:105], v[160:163], v[212:215], v[102:105]
	v_mfma_f32_16x16x32_bf16 v[94:97], v[170:173], v[212:215], v[94:97]
	v_mfma_f32_16x16x32_bf16 v[86:89], v[160:163], v[220:223], v[86:89]
	v_mfma_f32_16x16x32_bf16 v[78:81], v[170:173], v[220:223], v[78:81]
	v_mfma_f32_16x16x32_bf16 v[126:129], v[166:169], v[200:203], v[126:129]
	v_mfma_f32_16x16x32_bf16 v[122:125], v[174:177], v[200:203], v[122:125]
	v_mfma_f32_16x16x32_bf16 v[118:121], v[166:169], v[208:211], v[118:121]
	v_mfma_f32_16x16x32_bf16 v[110:113], v[174:177], v[208:211], v[110:113]
	v_mfma_f32_16x16x32_bf16 v[102:105], v[166:169], v[216:219], v[102:105]
	v_mfma_f32_16x16x32_bf16 v[94:97], v[174:177], v[216:219], v[94:97]
	v_mfma_f32_16x16x32_bf16 v[86:89], v[166:169], v[224:227], v[86:89]
	v_mfma_f32_16x16x32_bf16 v[78:81], v[174:177], v[224:227], v[78:81]
	s_setprio 0
	s_setprio 1
	v_mfma_f32_16x16x32_bf16 v[114:117], v[178:181], v[196:199], v[114:117]
	v_mfma_f32_16x16x32_bf16 v[106:109], v[188:191], v[196:199], v[106:109]
	v_mfma_f32_16x16x32_bf16 v[98:101], v[178:181], v[204:207], v[98:101]
	v_mfma_f32_16x16x32_bf16 v[90:93], v[188:191], v[204:207], v[90:93]
	v_mfma_f32_16x16x32_bf16 v[82:85], v[178:181], v[212:215], v[82:85]
	v_mfma_f32_16x16x32_bf16 v[74:77], v[188:191], v[212:215], v[74:77]
	v_mfma_f32_16x16x32_bf16 v[70:73], v[178:181], v[220:223], v[70:73]
	v_mfma_f32_16x16x32_bf16 v[66:69], v[188:191], v[220:223], v[66:69]
	v_mfma_f32_16x16x32_bf16 v[114:117], v[184:187], v[200:203], v[114:117]
	v_mfma_f32_16x16x32_bf16 v[106:109], v[192:195], v[200:203], v[106:109]
	v_mfma_f32_16x16x32_bf16 v[98:101], v[184:187], v[208:211], v[98:101]
	v_mfma_f32_16x16x32_bf16 v[90:93], v[192:195], v[208:211], v[90:93]
	v_mfma_f32_16x16x32_bf16 v[82:85], v[184:187], v[216:219], v[82:85]
	v_mfma_f32_16x16x32_bf16 v[74:77], v[192:195], v[216:219], v[74:77]
	v_mfma_f32_16x16x32_bf16 v[70:73], v[184:187], v[224:227], v[70:73]
	v_mfma_f32_16x16x32_bf16 v[66:69], v[192:195], v[224:227], v[66:69]
	s_setprio 0
	s_barrier
	s_add_i32 s12, s39, s22
	v_lshl_add_u64 v[228:229], s[16:17], 0, v[132:133]
	s_mov_b32 m0, s12
	ds_read_b128 v[196:199], v165 offset:16384
	ds_read_b128 v[200:203], v165 offset:17408
	ds_read_b128 v[204:207], v165 offset:18432
	ds_read_b128 v[208:211], v165 offset:19456
	ds_read_b128 v[212:215], v165 offset:20480
	ds_read_b128 v[216:219], v165 offset:21504
	ds_read_b128 v[220:223], v165 offset:22528
	ds_read_b128 v[224:227], v165 offset:23552
	global_load_lds_dwordx4 v[228:229], off
	s_add_i32 m0, s12, 0x2000
	s_add_u32 s12, s16, 0x44000
	v_lshl_add_u64 v[230:231], s[16:17], 0, v[152:153]
	s_addc_u32 s13, s17, 0
	s_add_i32 s39, s40, s22
	global_load_lds_dwordx4 v[230:231], off
	v_lshl_add_u64 v[232:233], s[12:13], 0, v[132:133]
	s_mov_b32 m0, s39
	v_lshl_add_u64 v[234:235], s[18:19], 0, v[134:135]
	global_load_lds_dwordx4 v[232:233], off
	v_lshl_add_u64 v[232:233], s[12:13], 0, v[152:153]
	s_add_i32 m0, s39, 0x2000
	s_nop 0
	global_load_lds_dwordx4 v[232:233], off
	v_lshl_add_u64 v[232:233], s[18:19], 0, v[130:131]
	s_mov_b32 m0, s23
	s_nop 0
	global_load_lds_dwordx4 v[232:233], off
	s_mov_b32 m0, s24
	s_nop 0
	global_load_lds_dwordx4 v[234:235], off
	s_waitcnt vmcnt(8)
	s_waitcnt lgkmcnt(0)
	s_barrier
	s_setprio 1
	s_waitcnt lgkmcnt(0)
	v_mfma_f32_16x16x32_bf16 v[62:65], v[160:163], v[196:199], v[62:65]
	v_mfma_f32_16x16x32_bf16 v[58:61], v[170:173], v[196:199], v[58:61]
	v_mfma_f32_16x16x32_bf16 v[54:57], v[160:163], v[204:207], v[54:57]
	v_mfma_f32_16x16x32_bf16 v[46:49], v[170:173], v[204:207], v[46:49]
	v_mfma_f32_16x16x32_bf16 v[38:41], v[160:163], v[212:215], v[38:41]
	v_mfma_f32_16x16x32_bf16 v[30:33], v[170:173], v[212:215], v[30:33]
	v_mfma_f32_16x16x32_bf16 v[22:25], v[160:163], v[220:223], v[22:25]
	v_mfma_f32_16x16x32_bf16 v[14:17], v[170:173], v[220:223], v[14:17]
	v_mfma_f32_16x16x32_bf16 v[62:65], v[166:169], v[200:203], v[62:65]
	v_mfma_f32_16x16x32_bf16 v[58:61], v[174:177], v[200:203], v[58:61]
	v_mfma_f32_16x16x32_bf16 v[54:57], v[166:169], v[208:211], v[54:57]
	v_mfma_f32_16x16x32_bf16 v[46:49], v[174:177], v[208:211], v[46:49]
	v_mfma_f32_16x16x32_bf16 v[38:41], v[166:169], v[216:219], v[38:41]
	v_mfma_f32_16x16x32_bf16 v[30:33], v[174:177], v[216:219], v[30:33]
	v_mfma_f32_16x16x32_bf16 v[22:25], v[166:169], v[224:227], v[22:25]
	v_mfma_f32_16x16x32_bf16 v[14:17], v[174:177], v[224:227], v[14:17]
	s_setprio 0
	s_setprio 1
	v_mfma_f32_16x16x32_bf16 v[50:53], v[178:181], v[196:199], v[50:53]
	v_mfma_f32_16x16x32_bf16 v[42:45], v[188:191], v[196:199], v[42:45]
	v_mfma_f32_16x16x32_bf16 v[34:37], v[178:181], v[204:207], v[34:37]
	v_mfma_f32_16x16x32_bf16 v[26:29], v[188:191], v[204:207], v[26:29]
	v_mfma_f32_16x16x32_bf16 v[18:21], v[178:181], v[212:215], v[18:21]
	v_mfma_f32_16x16x32_bf16 v[10:13], v[188:191], v[212:215], v[10:13]
	v_mfma_f32_16x16x32_bf16 v[6:9], v[178:181], v[220:223], v[6:9]
	v_mfma_f32_16x16x32_bf16 v[2:5], v[188:191], v[220:223], v[2:5]
	v_mfma_f32_16x16x32_bf16 v[50:53], v[184:187], v[200:203], v[50:53]
	v_mfma_f32_16x16x32_bf16 v[42:45], v[192:195], v[200:203], v[42:45]
	v_mfma_f32_16x16x32_bf16 v[34:37], v[184:187], v[208:211], v[34:37]
	v_mfma_f32_16x16x32_bf16 v[26:29], v[192:195], v[208:211], v[26:29]
	v_mfma_f32_16x16x32_bf16 v[18:21], v[184:187], v[216:219], v[18:21]
	v_mfma_f32_16x16x32_bf16 v[10:13], v[192:195], v[216:219], v[10:13]
	v_mfma_f32_16x16x32_bf16 v[6:9], v[184:187], v[224:227], v[6:9]
	v_mfma_f32_16x16x32_bf16 v[2:5], v[192:195], v[224:227], v[2:5]
	s_setprio 0
	s_barrier
; #define PG8_STAGE(bufoff, gbase, voff) do { _Pragma("unroll") for (int _i = 0; _i < 2; ++_i) \
;         __builtin_amdgcn_global_load_lds((const unsigned*)((const char*)(gbase) + (voff)[_i]), (LAS unsigned*)(lds + (bufoff) + ldsw + _i * 8192), 16, 0, 0); } while (0)
; #define PG8_LDA(dst, b, h) do { _Pragma("unroll") for (int m = 0; m < 4; ++m) _Pragma("unroll") for (int k = 0; k < 2; ++k) dst[m][k] = *(const LAS bf16x8*)(lds + PG8_SA(b, h) + aoff + m * 2048 + k * 1024); } while (0)
; #define PG8_LDB(dst, b, h) do { _Pragma("unroll") for (int n = 0; n < 2; ++n) _Pragma("unroll") for (int k = 0; k < 2; ++k) dst[n][k] = *(const LAS bf16x8*)(lds + PG8_SB(b, h) + boff + n * 2048 + k * 1024); } while (0)
; #define PG8_MMA(ai, bj, At, Bt) do { __builtin_amdgcn_s_setprio(1); _Pragma("unroll") for (int m = 0; m < 4; ++m) _Pragma("unroll") for (int n = 0; n < 2; ++n) _Pragma("unroll") for (int k = 0; k < 2; ++k) \
;         acc[ai][bj][m][n] = __builtin_amdgcn_mfma_f32_16x16x32_bf16(Bt[n][k], At[m][k], acc[ai][bj][m][n], 0, 0, 0); __builtin_amdgcn_s_setprio(0); } while (0)
; #define PG8_WAIT_V(n) asm volatile("s_waitcnt vmcnt(" #n ")" ::: "memory")
; #define PG8_WAIT_L(n) asm volatile("s_waitcnt lgkmcnt(" #n ")" ::: "memory")
; #define PG8_BAR __builtin_amdgcn_s_barrier()
; #define PG8_SCHED __builtin_amdgcn_sched_barrier(0)
; template <class Epi, bool ALIGN_EPI = PG8_ALIGN, bool SP2 = PG8_SP2>
; __device__ __forceinline__ void gemm_phase(LAS uchar* lds, const Gemm g, const StaticOrder& S, const Epi& E) {
;     ...
;             PG8_LDB(B0, 1, 0); PG8_LDB(B1, 1, 1); PG8_SCHED; PG8_LDA(At, 1, 0); PG8_STAGE(PG8_SA(0, 1), a2 + hstepA, voffA);
;             PG8_WAIT_V(8); PG8_WAIT_L(0); PG8_BAR; PG8_MMA(0, 0, At, B0); PG8_MMA(0, 1, At, B1); PG8_BAR; PG8_SCHED;
	s_add_i32 s39, 0, 0x18000
	s_add_i32 s40, 0, 0x1c000
	v_add_u32_e32 v174, s39, v139
	v_add_u32_e32 v192, s40, v139
	ds_read_b128 v[160:163], v174
	ds_read_b128 v[166:169], v174 offset:1024
	ds_read_b128 v[170:173], v174 offset:2048
	ds_read_b128 v[174:177], v174 offset:3072
	ds_read_b128 v[178:181], v192
	ds_read_b128 v[184:187], v192 offset:1024
	ds_read_b128 v[188:191], v192 offset:2048
	ds_read_b128 v[192:195], v192 offset:3072
	s_add_u32 s12, s18, 0x44000
	s_addc_u32 s13, s19, 0
	s_mov_b32 m0, s25
	v_lshl_add_u64 v[236:237], s[12:13], 0, v[130:131]
	ds_read_b128 v[196:199], v165 offset:32768
	ds_read_b128 v[200:203], v165 offset:33792
	ds_read_b128 v[204:207], v165 offset:34816
	ds_read_b128 v[208:211], v165 offset:35840
	ds_read_b128 v[212:215], v165 offset:36864
	ds_read_b128 v[216:219], v165 offset:37888
	ds_read_b128 v[220:223], v165 offset:38912
	ds_read_b128 v[224:227], v165 offset:39936
	global_load_lds_dwordx4 v[236:237], off
	v_lshl_add_u64 v[236:237], s[12:13], 0, v[134:135]
	s_mov_b32 m0, s26
	s_nop 0
	global_load_lds_dwordx4 v[236:237], off
	s_waitcnt vmcnt(8)
	s_waitcnt lgkmcnt(0)
	s_barrier
	s_setprio 1
	s_waitcnt lgkmcnt(0)
	v_mfma_f32_16x16x32_bf16 v[126:129], v[160:163], v[196:199], v[126:129]
	v_mfma_f32_16x16x32_bf16 v[122:125], v[170:173], v[196:199], v[122:125]
	v_mfma_f32_16x16x32_bf16 v[118:121], v[160:163], v[204:207], v[118:121]
	v_mfma_f32_16x16x32_bf16 v[110:113], v[170:173], v[204:207], v[110:113]
	v_mfma_f32_16x16x32_bf16 v[102:105], v[160:163], v[212:215], v[102:105]
	v_mfma_f32_16x16x32_bf16 v[94:97], v[170:173], v[212:215], v[94:97]
	v_mfma_f32_16x16x32_bf16 v[86:89], v[160:163], v[220:223], v[86:89]
	v_mfma_f32_16x16x32_bf16 v[78:81], v[170:173], v[220:223], v[78:81]
	v_mfma_f32_16x16x32_bf16 v[126:129], v[166:169], v[200:203], v[126:129]
	v_mfma_f32_16x16x32_bf16 v[122:125], v[174:177], v[200:203], v[122:125]
	v_mfma_f32_16x16x32_bf16 v[118:121], v[166:169], v[208:211], v[118:121]
	v_mfma_f32_16x16x32_bf16 v[110:113], v[174:177], v[208:211], v[110:113]
	v_mfma_f32_16x16x32_bf16 v[102:105], v[166:169], v[216:219], v[102:105]
	v_mfma_f32_16x16x32_bf16 v[94:97], v[174:177], v[216:219], v[94:97]
	v_mfma_f32_16x16x32_bf16 v[86:89], v[166:169], v[224:227], v[86:89]
	v_mfma_f32_16x16x32_bf16 v[78:81], v[174:177], v[224:227], v[78:81]
	s_setprio 0
	s_setprio 1
	v_mfma_f32_16x16x32_bf16 v[114:117], v[178:181], v[196:199], v[114:117]
	v_mfma_f32_16x16x32_bf16 v[106:109], v[188:191], v[196:199], v[106:109]
	v_mfma_f32_16x16x32_bf16 v[98:101], v[178:181], v[204:207], v[98:101]
	v_mfma_f32_16x16x32_bf16 v[90:93], v[188:191], v[204:207], v[90:93]
	v_mfma_f32_16x16x32_bf16 v[82:85], v[178:181], v[212:215], v[82:85]
	v_mfma_f32_16x16x32_bf16 v[74:77], v[188:191], v[212:215], v[74:77]
	v_mfma_f32_16x16x32_bf16 v[70:73], v[178:181], v[220:223], v[70:73]
	v_mfma_f32_16x16x32_bf16 v[66:69], v[188:191], v[220:223], v[66:69]
	v_mfma_f32_16x16x32_bf16 v[114:117], v[184:187], v[200:203], v[114:117]
	v_mfma_f32_16x16x32_bf16 v[106:109], v[192:195], v[200:203], v[106:109]
	v_mfma_f32_16x16x32_bf16 v[98:101], v[184:187], v[208:211], v[98:101]
	v_mfma_f32_16x16x32_bf16 v[90:93], v[192:195], v[208:211], v[90:93]
	v_mfma_f32_16x16x32_bf16 v[82:85], v[184:187], v[216:219], v[82:85]
	v_mfma_f32_16x16x32_bf16 v[74:77], v[192:195], v[216:219], v[74:77]
	v_mfma_f32_16x16x32_bf16 v[70:73], v[184:187], v[224:227], v[70:73]
	v_mfma_f32_16x16x32_bf16 v[66:69], v[192:195], v[224:227], v[66:69]
	s_setprio 0
	s_barrier
; #define PG8_STAGE(bufoff, gbase, voff) do { _Pragma("unroll") for (int _i = 0; _i < 2; ++_i) \
;         __builtin_amdgcn_global_load_lds((const unsigned*)((const char*)(gbase) + (voff)[_i]), (LAS unsigned*)(lds + (bufoff) + ldsw + _i * 8192), 16, 0, 0); } while (0)
; #define PG8_LDA(dst, b, h) do { _Pragma("unroll") for (int m = 0; m < 4; ++m) _Pragma("unroll") for (int k = 0; k < 2; ++k) dst[m][k] = *(const LAS bf16x8*)(lds + PG8_SA(b, h) + aoff + m * 2048 + k * 1024); } while (0)
; #define PG8_MMA(ai, bj, At, Bt) do { __builtin_amdgcn_s_setprio(1); _Pragma("unroll") for (int m = 0; m < 4; ++m) _Pragma("unroll") for (int n = 0; n < 2; ++n) _Pragma("unroll") for (int k = 0; k < 2; ++k) \
;         acc[ai][bj][m][n] = __builtin_amdgcn_mfma_f32_16x16x32_bf16(Bt[n][k], At[m][k], acc[ai][bj][m][n], 0, 0, 0); __builtin_amdgcn_s_setprio(0); } while (0)
; #define PG8_WAIT_V(n) asm volatile("s_waitcnt vmcnt(" #n ")" ::: "memory")
; #define PG8_WAIT_L(n) asm volatile("s_waitcnt lgkmcnt(" #n ")" ::: "memory")
; #define PG8_BAR __builtin_amdgcn_s_barrier()
; #define PG8_SCHED __builtin_amdgcn_sched_barrier(0)
; template <class Epi, bool ALIGN_EPI = PG8_ALIGN, bool SP2 = PG8_SP2>
; __device__ __forceinline__ void gemm_phase(LAS uchar* lds, const Gemm g, const StaticOrder& S, const Epi& E) {
;     ...
;             PG8_WAIT_V(8); PG8_WAIT_L(0); PG8_BAR; PG8_MMA(0, 0, At, B0); PG8_MMA(0, 1, At, B1); PG8_BAR; PG8_SCHED;
;             PG8_LDA(At, 1, 1); PG8_STAGE(PG8_SB(1, 0), b3, voffB); PG8_STAGE(PG8_SB(1, 1), b3 + hstepB, voffB); PG8_STAGE(PG8_SA(1, 0), a3, voffA);
;             PG8_WAIT_V(8); PG8_WAIT_L(0); PG8_BAR; PG8_MMA(1, 0, At, B0); PG8_MMA(1, 1, At, B1); PG8_BAR; PG8_SCHED;
	s_add_i32 s12, s39, s22
	v_lshl_add_u64 v[228:229], v[228:229], 0, s[84:85]
	s_mov_b32 m0, s12
	ds_read_b128 v[196:199], v165 offset:49152
	ds_read_b128 v[200:203], v165 offset:50176
	ds_read_b128 v[204:207], v165 offset:51200
	ds_read_b128 v[208:211], v165 offset:52224
	ds_read_b128 v[212:215], v165 offset:53248
	ds_read_b128 v[216:219], v165 offset:54272
	ds_read_b128 v[220:223], v165 offset:55296
	ds_read_b128 v[224:227], v165 offset:56320
	global_load_lds_dwordx4 v[228:229], off
	s_add_i32 m0, s12, 0x2000
	s_add_u32 s12, s16, 0x44080
	v_lshl_add_u64 v[228:229], v[230:231], 0, s[84:85]
	s_addc_u32 s13, s17, 0
	s_add_i32 s16, s40, s22
	global_load_lds_dwordx4 v[228:229], off
	v_lshl_add_u64 v[228:229], s[12:13], 0, v[132:133]
	s_mov_b32 m0, s16
	s_nop 0
	global_load_lds_dwordx4 v[228:229], off
	v_lshl_add_u64 v[228:229], s[12:13], 0, v[152:153]
	s_add_i32 m0, s16, 0x2000
	s_nop 0
	global_load_lds_dwordx4 v[228:229], off
	v_lshl_add_u64 v[228:229], v[232:233], 0, s[84:85]
	s_mov_b32 m0, s27
	s_nop 0
	global_load_lds_dwordx4 v[228:229], off
	v_lshl_add_u64 v[228:229], v[234:235], 0, s[84:85]
	s_mov_b32 m0, s28
	s_nop 0
	global_load_lds_dwordx4 v[228:229], off
	s_waitcnt vmcnt(8)
	s_waitcnt lgkmcnt(0)
	s_barrier
	s_setprio 1
	s_waitcnt lgkmcnt(0)
	v_mfma_f32_16x16x32_bf16 v[62:65], v[160:163], v[196:199], v[62:65]
	v_mfma_f32_16x16x32_bf16 v[58:61], v[170:173], v[196:199], v[58:61]
	v_mfma_f32_16x16x32_bf16 v[54:57], v[160:163], v[204:207], v[54:57]
	v_mfma_f32_16x16x32_bf16 v[46:49], v[170:173], v[204:207], v[46:49]
	v_mfma_f32_16x16x32_bf16 v[38:41], v[160:163], v[212:215], v[38:41]
	v_mfma_f32_16x16x32_bf16 v[30:33], v[170:173], v[212:215], v[30:33]
	v_mfma_f32_16x16x32_bf16 v[22:25], v[160:163], v[220:223], v[22:25]
	v_mfma_f32_16x16x32_bf16 v[14:17], v[170:173], v[220:223], v[14:17]
	v_mfma_f32_16x16x32_bf16 v[62:65], v[166:169], v[200:203], v[62:65]
	v_mfma_f32_16x16x32_bf16 v[58:61], v[174:177], v[200:203], v[58:61]
	v_mfma_f32_16x16x32_bf16 v[54:57], v[166:169], v[208:211], v[54:57]
	v_mfma_f32_16x16x32_bf16 v[46:49], v[174:177], v[208:211], v[46:49]
	v_mfma_f32_16x16x32_bf16 v[38:41], v[166:169], v[216:219], v[38:41]
	v_mfma_f32_16x16x32_bf16 v[30:33], v[174:177], v[216:219], v[30:33]
	v_mfma_f32_16x16x32_bf16 v[22:25], v[166:169], v[224:227], v[22:25]
	v_mfma_f32_16x16x32_bf16 v[14:17], v[174:177], v[224:227], v[14:17]
	s_setprio 0
	s_setprio 1
	v_mfma_f32_16x16x32_bf16 v[50:53], v[178:181], v[196:199], v[50:53]
	v_mfma_f32_16x16x32_bf16 v[42:45], v[188:191], v[196:199], v[42:45]
	v_mfma_f32_16x16x32_bf16 v[34:37], v[178:181], v[204:207], v[34:37]
	v_mfma_f32_16x16x32_bf16 v[26:29], v[188:191], v[204:207], v[26:29]
	v_mfma_f32_16x16x32_bf16 v[18:21], v[178:181], v[212:215], v[18:21]
	v_mfma_f32_16x16x32_bf16 v[10:13], v[188:191], v[212:215], v[10:13]
	v_mfma_f32_16x16x32_bf16 v[6:9], v[178:181], v[220:223], v[6:9]
	v_mfma_f32_16x16x32_bf16 v[2:5], v[188:191], v[220:223], v[2:5]
	v_mfma_f32_16x16x32_bf16 v[50:53], v[184:187], v[200:203], v[50:53]
	v_mfma_f32_16x16x32_bf16 v[42:45], v[192:195], v[200:203], v[42:45]
	v_mfma_f32_16x16x32_bf16 v[34:37], v[184:187], v[208:211], v[34:37]
	v_mfma_f32_16x16x32_bf16 v[26:29], v[192:195], v[208:211], v[26:29]
	v_mfma_f32_16x16x32_bf16 v[18:21], v[184:187], v[216:219], v[18:21]
	v_mfma_f32_16x16x32_bf16 v[10:13], v[192:195], v[216:219], v[10:13]
	v_mfma_f32_16x16x32_bf16 v[6:9], v[184:187], v[224:227], v[6:9]
	v_mfma_f32_16x16x32_bf16 v[2:5], v[192:195], v[224:227], v[2:5]
	s_setprio 0
	s_add_i32 s38, s38, 2
	s_add_u32 s36, s36, 0x100
	s_addc_u32 s37, s37, 0
	s_cmp_gt_u32 s38, 13
	s_mov_b64 s[12:13], s[14:15]
	s_cbranch_scc1 .Lrot_exit_837
	s_add_u32 s14, s12, 0x100
	s_addc_u32 s15, s13, 0
	s_add_i32 s39, 0, 0x10000
	s_cmp_eq_u32 s38, 12
	s_cselect_b32 s19, s5, s15
	s_cselect_b32 s18, s4, s14
	s_cselect_b32 s17, s11, s37
	s_cselect_b32 s16, s10, s36
	s_add_i32 s40, 0, 0x14000
	v_add_u32_e32 v174, s39, v139
	v_add_u32_e32 v192, s40, v139
	s_branch .LBB0_837

; #define PG8_STAGE(bufoff, gbase, voff) do { _Pragma("unroll") for (int _i = 0; _i < 2; ++_i) \
;         __builtin_amdgcn_global_load_lds((const unsigned*)((const char*)(gbase) + (voff)[_i]), (LAS unsigned*)(lds + (bufoff) + ldsw + _i * 8192), 16, 0, 0); } while (0)
; #define PG8_LDA(dst, b, h) do { _Pragma("unroll") for (int m = 0; m < 4; ++m) _Pragma("unroll") for (int k = 0; k < 2; ++k) dst[m][k] = *(const LAS bf16x8*)(lds + PG8_SA(b, h) + aoff + m * 2048 + k * 1024); } while (0)
; #define PG8_LDB(dst, b, h) do { _Pragma("unroll") for (int n = 0; n < 2; ++n) _Pragma("unroll") for (int k = 0; k < 2; ++k) dst[n][k] = *(const LAS bf16x8*)(lds + PG8_SB(b, h) + boff + n * 2048 + k * 1024); } while (0)
; #define PG8_MMA(ai, bj, At, Bt) do { __builtin_amdgcn_s_setprio(1); _Pragma("unroll") for (int m = 0; m < 4; ++m) _Pragma("unroll") for (int n = 0; n < 2; ++n) _Pragma("unroll") for (int k = 0; k < 2; ++k) \
;         acc[ai][bj][m][n] = __builtin_amdgcn_mfma_f32_16x16x32_bf16(Bt[n][k], At[m][k], acc[ai][bj][m][n], 0, 0, 0); __builtin_amdgcn_s_setprio(0); } while (0)
; #define PG8_WAIT_V(n) asm volatile("s_waitcnt vmcnt(" #n ")" ::: "memory")
; #define PG8_WAIT_L(n) asm volatile("s_waitcnt lgkmcnt(" #n ")" ::: "memory")
; #define PG8_BAR __builtin_amdgcn_s_barrier()
; #define PG8_SCHED __builtin_amdgcn_sched_barrier(0)
; template <class Epi, bool ALIGN_EPI = PG8_ALIGN, bool SP2 = PG8_SP2>
; __device__ __forceinline__ void gemm_phase(LAS uchar* lds, const Gemm g, const StaticOrder& S, const Epi& E) {
;     ...
;             PG8_WAIT_V(8); PG8_WAIT_L(0); PG8_BAR; PG8_MMA(1, 0, At, B0); PG8_MMA(1, 1, At, B1); PG8_BAR; PG8_SCHED;
;             PG8_LDB(B0, 1, 0); PG8_LDB(B1, 1, 1); PG8_SCHED; PG8_LDA(At, 1, 0); PG8_STAGE(PG8_SA(0, 1), a2 + hstepA, voffA);
;             PG8_WAIT_V(8); PG8_WAIT_L(0); PG8_BAR; PG8_MMA(0, 0, At, B0); PG8_MMA(0, 1, At, B1); PG8_BAR; PG8_SCHED;
.Lrw_done_1050_1_pl:
	s_waitcnt lgkmcnt(0)
	s_barrier
	s_setprio 1
	s_waitcnt lgkmcnt(0)
	v_mfma_f32_16x16x32_bf16 v[62:65], v[164:167], v[200:203], 0
	v_mfma_f32_16x16x32_bf16 v[54:57], v[172:175], v[200:203], 0
	v_mfma_f32_16x16x32_bf16 v[46:49], v[164:167], v[208:211], 0
	v_mfma_f32_16x16x32_bf16 v[38:41], v[172:175], v[208:211], 0
	v_mfma_f32_16x16x32_bf16 v[30:33], v[164:167], v[216:219], 0
	v_mfma_f32_16x16x32_bf16 v[22:25], v[172:175], v[216:219], 0
	v_mfma_f32_16x16x32_bf16 v[14:17], v[164:167], v[224:227], 0
	v_mfma_f32_16x16x32_bf16 v[6:9], v[172:175], v[224:227], 0
	v_mfma_f32_16x16x32_bf16 v[62:65], v[168:171], v[204:207], v[62:65]
	v_mfma_f32_16x16x32_bf16 v[54:57], v[176:179], v[204:207], v[54:57]
	v_mfma_f32_16x16x32_bf16 v[46:49], v[168:171], v[212:215], v[46:49]
	v_mfma_f32_16x16x32_bf16 v[38:41], v[176:179], v[212:215], v[38:41]
	v_mfma_f32_16x16x32_bf16 v[30:33], v[168:171], v[220:223], v[30:33]
	v_mfma_f32_16x16x32_bf16 v[22:25], v[176:179], v[220:223], v[22:25]
	v_mfma_f32_16x16x32_bf16 v[14:17], v[168:171], v[228:231], v[14:17]
	v_mfma_f32_16x16x32_bf16 v[6:9], v[176:179], v[228:231], v[6:9]
	s_setprio 0
	s_setprio 1
	v_mfma_f32_16x16x32_bf16 v[58:61], v[184:187], v[200:203], 0
	v_mfma_f32_16x16x32_bf16 v[50:53], v[192:195], v[200:203], 0
	v_mfma_f32_16x16x32_bf16 v[42:45], v[184:187], v[208:211], 0
	v_mfma_f32_16x16x32_bf16 v[34:37], v[192:195], v[208:211], 0
	v_mfma_f32_16x16x32_bf16 v[26:29], v[184:187], v[216:219], 0
	v_mfma_f32_16x16x32_bf16 v[18:21], v[192:195], v[216:219], 0
	v_mfma_f32_16x16x32_bf16 v[10:13], v[184:187], v[224:227], 0
	v_mfma_f32_16x16x32_bf16 v[2:5], v[192:195], v[224:227], 0
	v_mfma_f32_16x16x32_bf16 v[58:61], v[188:191], v[204:207], v[58:61]
	v_mfma_f32_16x16x32_bf16 v[50:53], v[196:199], v[204:207], v[50:53]
	v_mfma_f32_16x16x32_bf16 v[42:45], v[188:191], v[212:215], v[42:45]
	v_mfma_f32_16x16x32_bf16 v[34:37], v[196:199], v[212:215], v[34:37]
	v_mfma_f32_16x16x32_bf16 v[26:29], v[188:191], v[220:223], v[26:29]
	v_mfma_f32_16x16x32_bf16 v[18:21], v[196:199], v[220:223], v[18:21]
	v_mfma_f32_16x16x32_bf16 v[10:13], v[188:191], v[228:231], v[10:13]
	v_mfma_f32_16x16x32_bf16 v[2:5], v[196:199], v[228:231], v[2:5]
	s_setprio 0
	s_barrier
	s_add_i32 s39, 0, 0x18000
	v_add_u32_e32 v144, s39, v139
	s_add_i32 s40, 0, 0x1c000
	ds_read_b128 v[164:167], v144
	ds_read_b128 v[168:171], v144 offset:1024
	ds_read_b128 v[172:175], v144 offset:2048
	ds_read_b128 v[176:179], v144 offset:3072
	v_add_u32_e32 v144, s40, v139
	ds_read_b128 v[184:187], v144
	ds_read_b128 v[188:191], v144 offset:1024
	ds_read_b128 v[192:195], v144 offset:2048
	ds_read_b128 v[196:199], v144 offset:3072
	s_add_u32 s12, s18, 0x44000
	s_addc_u32 s13, s19, 0
	s_mov_b32 m0, s25
	v_lshl_add_u64 v[236:237], s[12:13], 0, v[154:155]
	ds_read_b128 v[200:203], v163 offset:32768
	ds_read_b128 v[204:207], v163 offset:33792
	ds_read_b128 v[208:211], v163 offset:34816
	ds_read_b128 v[212:215], v163 offset:35840
	ds_read_b128 v[216:219], v163 offset:36864
	ds_read_b128 v[220:223], v163 offset:37888
	ds_read_b128 v[224:227], v163 offset:38912
	ds_read_b128 v[228:231], v163 offset:39936
	global_load_lds_dwordx4 v[236:237], off
	v_lshl_add_u64 v[236:237], s[12:13], 0, v[132:133]
	s_mov_b32 m0, s26
	s_nop 0
	global_load_lds_dwordx4 v[236:237], off
	s_waitcnt vmcnt(8)
	s_waitcnt lgkmcnt(0)
	s_barrier
	s_setprio 1
	s_waitcnt lgkmcnt(0)
	v_mfma_f32_16x16x32_bf16 v[126:129], v[164:167], v[200:203], v[126:129]
	v_mfma_f32_16x16x32_bf16 v[118:121], v[172:175], v[200:203], v[118:121]
	v_mfma_f32_16x16x32_bf16 v[110:113], v[164:167], v[208:211], v[110:113]
	v_mfma_f32_16x16x32_bf16 v[102:105], v[172:175], v[208:211], v[102:105]
	v_mfma_f32_16x16x32_bf16 v[94:97], v[164:167], v[216:219], v[94:97]
	v_mfma_f32_16x16x32_bf16 v[86:89], v[172:175], v[216:219], v[86:89]
	v_mfma_f32_16x16x32_bf16 v[78:81], v[164:167], v[224:227], v[78:81]
	v_mfma_f32_16x16x32_bf16 v[70:73], v[172:175], v[224:227], v[70:73]
	v_mfma_f32_16x16x32_bf16 v[126:129], v[168:171], v[204:207], v[126:129]
	v_mfma_f32_16x16x32_bf16 v[118:121], v[176:179], v[204:207], v[118:121]
	v_mfma_f32_16x16x32_bf16 v[110:113], v[168:171], v[212:215], v[110:113]
	v_mfma_f32_16x16x32_bf16 v[102:105], v[176:179], v[212:215], v[102:105]
	v_mfma_f32_16x16x32_bf16 v[94:97], v[168:171], v[220:223], v[94:97]
	v_mfma_f32_16x16x32_bf16 v[86:89], v[176:179], v[220:223], v[86:89]
	v_mfma_f32_16x16x32_bf16 v[78:81], v[168:171], v[228:231], v[78:81]
	v_mfma_f32_16x16x32_bf16 v[70:73], v[176:179], v[228:231], v[70:73]
	s_setprio 0
	s_setprio 1
	v_mfma_f32_16x16x32_bf16 v[122:125], v[184:187], v[200:203], v[122:125]
	v_mfma_f32_16x16x32_bf16 v[114:117], v[192:195], v[200:203], v[114:117]
	v_mfma_f32_16x16x32_bf16 v[106:109], v[184:187], v[208:211], v[106:109]
	v_mfma_f32_16x16x32_bf16 v[98:101], v[192:195], v[208:211], v[98:101]
	v_mfma_f32_16x16x32_bf16 v[90:93], v[184:187], v[216:219], v[90:93]
	v_mfma_f32_16x16x32_bf16 v[82:85], v[192:195], v[216:219], v[82:85]
	v_mfma_f32_16x16x32_bf16 v[74:77], v[184:187], v[224:227], v[74:77]
	v_mfma_f32_16x16x32_bf16 v[66:69], v[192:195], v[224:227], v[66:69]
	v_mfma_f32_16x16x32_bf16 v[122:125], v[188:191], v[204:207], v[122:125]
	v_mfma_f32_16x16x32_bf16 v[114:117], v[196:199], v[204:207], v[114:117]
	v_mfma_f32_16x16x32_bf16 v[106:109], v[188:191], v[212:215], v[106:109]
	v_mfma_f32_16x16x32_bf16 v[98:101], v[196:199], v[212:215], v[98:101]
	v_mfma_f32_16x16x32_bf16 v[90:93], v[188:191], v[220:223], v[90:93]
	v_mfma_f32_16x16x32_bf16 v[82:85], v[196:199], v[220:223], v[82:85]
	v_mfma_f32_16x16x32_bf16 v[74:77], v[188:191], v[228:231], v[74:77]
	v_mfma_f32_16x16x32_bf16 v[66:69], v[196:199], v[228:231], v[66:69]
	s_setprio 0
	s_barrier
; #define PG8_STAGE(bufoff, gbase, voff) do { _Pragma("unroll") for (int _i = 0; _i < 2; ++_i) \
;         __builtin_amdgcn_global_load_lds((const unsigned*)((const char*)(gbase) + (voff)[_i]), (LAS unsigned*)(lds + (bufoff) + ldsw + _i * 8192), 16, 0, 0); } while (0)
; #define PG8_LDA(dst, b, h) do { _Pragma("unroll") for (int m = 0; m < 4; ++m) _Pragma("unroll") for (int k = 0; k < 2; ++k) dst[m][k] = *(const LAS bf16x8*)(lds + PG8_SA(b, h) + aoff + m * 2048 + k * 1024); } while (0)
; #define PG8_LDB(dst, b, h) do { _Pragma("unroll") for (int n = 0; n < 2; ++n) _Pragma("unroll") for (int k = 0; k < 2; ++k) dst[n][k] = *(const LAS bf16x8*)(lds + PG8_SB(b, h) + boff + n * 2048 + k * 1024); } while (0)
; #define PG8_BAR __builtin_amdgcn_s_barrier()
; template <class Epi, bool ALIGN_EPI = PG8_ALIGN, bool SP2 = PG8_SP2>
; __device__ __forceinline__ void gemm_phase(LAS uchar* lds, const Gemm g, const StaticOrder& S, const Epi& E) {
;     ...
;         for (int t = tb; t < tb + tblk; t += 2) {
;             const bool last = (t == nt - 2);
;             const char* a1 = cA + (size_t)(t + 1) * kstep;
;             const char* a2 = last ? nA : cA + (size_t)(t + 2) * kstep; const char* b2 = last ? nB : cB + (size_t)(t + 2) * kstep;
;             const char* a3 = a2 + kstep; const char* b3 = b2 + kstep;
;             if constexpr (SP2) {
;             PG8_LDB(B0, 0, 0); PG8_LDB(B1, 0, 1); PG8_SCHED; PG8_LDA(At, 0, 0); PG8_STAGE(PG8_SA(1, 1), a1 + hstepA, voffA);
;             PG8_WAIT_V(8); PG8_WAIT_L(0); PG8_BAR; PG8_MMA(0, 0, At, B0); PG8_MMA(0, 1, At, B1); PG8_BAR; PG8_SCHED;
;             PG8_LDA(At, 0, 1); PG8_STAGE(PG8_SB(0, 0), b2, voffB); PG8_STAGE(PG8_SB(0, 1), b2 + hstepB, voffB); PG8_STAGE(PG8_SA(0, 0), a2, voffA);
;             PG8_WAIT_V(8); PG8_WAIT_L(0); PG8_BAR; PG8_MMA(1, 0, At, B0); PG8_MMA(1, 1, At, B1); PG8_BAR; PG8_SCHED;
;             PG8_LDB(B0, 1, 0); PG8_LDB(B1, 1, 1); PG8_SCHED; PG8_LDA(At, 1, 0); PG8_STAGE(PG8_SA(0, 1), a2 + hstepA, voffA);
;             PG8_WAIT_V(8); PG8_WAIT_L(0); PG8_BAR; PG8_MMA(0, 0, At, B0); PG8_MMA(0, 1, At, B1); PG8_BAR; PG8_SCHED;
;             PG8_LDA(At, 1, 1); PG8_STAGE(PG8_SB(1, 0), b3, voffB); PG8_STAGE(PG8_SB(1, 1), b3 + hstepB, voffB); PG8_STAGE(PG8_SA(1, 0), a3, voffA);
;             PG8_WAIT_V(8); PG8_WAIT_L(0); PG8_BAR; PG8_MMA(1, 0, At, B0); PG8_MMA(1, 1, At, B1); PG8_BAR; PG8_SCHED;
	s_add_i32 s12, s39, s21
	v_lshl_add_u64 v[160:161], v[160:161], 0, s[84:85]
	s_mov_b32 m0, s12
	ds_read_b128 v[200:203], v163 offset:49152
	ds_read_b128 v[204:207], v163 offset:50176
	ds_read_b128 v[208:211], v163 offset:51200
	ds_read_b128 v[212:215], v163 offset:52224
	ds_read_b128 v[216:219], v163 offset:53248
	ds_read_b128 v[220:223], v163 offset:54272
	ds_read_b128 v[224:227], v163 offset:55296
	ds_read_b128 v[228:231], v163 offset:56320
	global_load_lds_dwordx4 v[160:161], off
	s_add_i32 m0, s12, 0x2000
	s_add_u32 s12, s16, 0x44080
	v_lshl_add_u64 v[160:161], v[180:181], 0, s[84:85]
	s_addc_u32 s13, s17, 0
	s_add_i32 s16, s40, s21
	global_load_lds_dwordx4 v[160:161], off
	v_lshl_add_u64 v[160:161], s[12:13], 0, v[134:135]
	s_mov_b32 m0, s16
	s_nop 0
	global_load_lds_dwordx4 v[160:161], off
	v_lshl_add_u64 v[160:161], s[12:13], 0, v[130:131]
	s_add_i32 m0, s16, 0x2000
	s_nop 0
	global_load_lds_dwordx4 v[160:161], off
	v_lshl_add_u64 v[160:161], v[232:233], 0, s[84:85]
	s_mov_b32 m0, s27
	s_nop 0
	global_load_lds_dwordx4 v[160:161], off
	v_lshl_add_u64 v[160:161], v[234:235], 0, s[84:85]
	s_mov_b32 m0, s28
	s_nop 0
	global_load_lds_dwordx4 v[160:161], off
	s_waitcnt vmcnt(8)
	s_waitcnt lgkmcnt(0)
	s_barrier
	s_setprio 1
	s_waitcnt lgkmcnt(0)
	v_mfma_f32_16x16x32_bf16 v[62:65], v[164:167], v[200:203], v[62:65]
	v_mfma_f32_16x16x32_bf16 v[54:57], v[172:175], v[200:203], v[54:57]
	v_mfma_f32_16x16x32_bf16 v[46:49], v[164:167], v[208:211], v[46:49]
	v_mfma_f32_16x16x32_bf16 v[38:41], v[172:175], v[208:211], v[38:41]
	v_mfma_f32_16x16x32_bf16 v[30:33], v[164:167], v[216:219], v[30:33]
	v_mfma_f32_16x16x32_bf16 v[22:25], v[172:175], v[216:219], v[22:25]
	v_mfma_f32_16x16x32_bf16 v[14:17], v[164:167], v[224:227], v[14:17]
	v_mfma_f32_16x16x32_bf16 v[6:9], v[172:175], v[224:227], v[6:9]
	v_mfma_f32_16x16x32_bf16 v[62:65], v[168:171], v[204:207], v[62:65]
	v_mfma_f32_16x16x32_bf16 v[54:57], v[176:179], v[204:207], v[54:57]
	v_mfma_f32_16x16x32_bf16 v[46:49], v[168:171], v[212:215], v[46:49]
	v_mfma_f32_16x16x32_bf16 v[38:41], v[176:179], v[212:215], v[38:41]
	v_mfma_f32_16x16x32_bf16 v[30:33], v[168:171], v[220:223], v[30:33]
	v_mfma_f32_16x16x32_bf16 v[22:25], v[176:179], v[220:223], v[22:25]
	v_mfma_f32_16x16x32_bf16 v[14:17], v[168:171], v[228:231], v[14:17]
	v_mfma_f32_16x16x32_bf16 v[6:9], v[176:179], v[228:231], v[6:9]
	s_setprio 0
	s_setprio 1
	v_mfma_f32_16x16x32_bf16 v[58:61], v[184:187], v[200:203], v[58:61]
	v_mfma_f32_16x16x32_bf16 v[50:53], v[192:195], v[200:203], v[50:53]
	v_mfma_f32_16x16x32_bf16 v[42:45], v[184:187], v[208:211], v[42:45]
	v_mfma_f32_16x16x32_bf16 v[34:37], v[192:195], v[208:211], v[34:37]
	v_mfma_f32_16x16x32_bf16 v[26:29], v[184:187], v[216:219], v[26:29]
	v_mfma_f32_16x16x32_bf16 v[18:21], v[192:195], v[216:219], v[18:21]
	v_mfma_f32_16x16x32_bf16 v[10:13], v[184:187], v[224:227], v[10:13]
	v_mfma_f32_16x16x32_bf16 v[2:5], v[192:195], v[224:227], v[2:5]
	v_mfma_f32_16x16x32_bf16 v[58:61], v[188:191], v[204:207], v[58:61]
	v_mfma_f32_16x16x32_bf16 v[50:53], v[196:199], v[204:207], v[50:53]
	v_mfma_f32_16x16x32_bf16 v[42:45], v[188:191], v[212:215], v[42:45]
	v_mfma_f32_16x16x32_bf16 v[34:37], v[196:199], v[212:215], v[34:37]
	v_mfma_f32_16x16x32_bf16 v[26:29], v[188:191], v[220:223], v[26:29]
	v_mfma_f32_16x16x32_bf16 v[18:21], v[196:199], v[220:223], v[18:21]
	v_mfma_f32_16x16x32_bf16 v[10:13], v[188:191], v[228:231], v[10:13]
	v_mfma_f32_16x16x32_bf16 v[2:5], v[196:199], v[228:231], v[2:5]
	s_setprio 0
	s_add_i32 s38, s38, 2
	s_add_u32 s36, s36, 0x100
	s_addc_u32 s37, s37, 0
	s_cmp_gt_u32 s38, 13
	s_mov_b64 s[12:13], s[14:15]
	s_add_u32 s14, s12, 0x100
	s_addc_u32 s15, s13, 0
	s_add_i32 s39, 0, 0x10000
	s_cmp_eq_u32 s38, 12
	s_cselect_b32 s19, s1, s15
	s_cselect_b32 s18, s0, s14
	s_cselect_b32 s17, s11, s37
	s_cselect_b32 s16, s10, s36
	s_add_i32 s40, 0, 0x14000
	v_add_u32_e32 v144, s39, v139
.LBB0_1050:
	s_barrier
	ds_read_b128 v[164:167], v144
	ds_read_b128 v[168:171], v144 offset:1024
	ds_read_b128 v[172:175], v144 offset:2048
	ds_read_b128 v[176:179], v144 offset:3072
	v_add_u32_e32 v144, s40, v139
	ds_read_b128 v[184:187], v144
	ds_read_b128 v[188:191], v144 offset:1024
	ds_read_b128 v[192:195], v144 offset:2048
	ds_read_b128 v[196:199], v144 offset:3072
	v_lshl_add_u64 v[160:161], s[12:13], 0, v[156:157]
	s_add_i32 m0, s23, 0xc000
	ds_read_b128 v[200:203], v163
	ds_read_b128 v[204:207], v163 offset:1024
	ds_read_b128 v[208:211], v163 offset:2048
	ds_read_b128 v[212:215], v163 offset:3072
	ds_read_b128 v[216:219], v163 offset:4096
	ds_read_b128 v[220:223], v163 offset:5120
	ds_read_b128 v[224:227], v163 offset:6144
	ds_read_b128 v[228:231], v163 offset:7168
	global_load_lds_dwordx4 v[160:161], off
	v_lshl_add_u64 v[160:161], s[12:13], 0, v[158:159]
	s_add_i32 m0, s23, 0xe000
	s_nop 0
	global_load_lds_dwordx4 v[160:161], off
	s_waitcnt vmcnt(8)
	s_waitcnt lgkmcnt(0)
	s_barrier
; #define PG8_STAGE(bufoff, gbase, voff) do { _Pragma("unroll") for (int _i = 0; _i < 2; ++_i) \
;         __builtin_amdgcn_global_load_lds((const unsigned*)((const char*)(gbase) + (voff)[_i]), (LAS unsigned*)(lds + (bufoff) + ldsw + _i * 8192), 16, 0, 0); } while (0)
; #define PG8_LDA(dst, b, h) do { _Pragma("unroll") for (int m = 0; m < 4; ++m) _Pragma("unroll") for (int k = 0; k < 2; ++k) dst[m][k] = *(const LAS bf16x8*)(lds + PG8_SA(b, h) + aoff + m * 2048 + k * 1024); } while (0)
; #define PG8_MMA(ai, bj, At, Bt) do { __builtin_amdgcn_s_setprio(1); _Pragma("unroll") for (int m = 0; m < 4; ++m) _Pragma("unroll") for (int n = 0; n < 2; ++n) _Pragma("unroll") for (int k = 0; k < 2; ++k) \
;         acc[ai][bj][m][n] = __builtin_amdgcn_mfma_f32_16x16x32_bf16(Bt[n][k], At[m][k], acc[ai][bj][m][n], 0, 0, 0); __builtin_amdgcn_s_setprio(0); } while (0)
; #define PG8_WAIT_V(n) asm volatile("s_waitcnt vmcnt(" #n ")" ::: "memory")
; #define PG8_WAIT_L(n) asm volatile("s_waitcnt lgkmcnt(" #n ")" ::: "memory")
; #define PG8_BAR __builtin_amdgcn_s_barrier()
; #define PG8_SCHED __builtin_amdgcn_sched_barrier(0)
; template <class Epi, bool ALIGN_EPI = PG8_ALIGN, bool SP2 = PG8_SP2>
; __device__ __forceinline__ void gemm_phase(LAS uchar* lds, const Gemm g, const StaticOrder& S, const Epi& E) {
;     ...
;             PG8_WAIT_V(8); PG8_WAIT_L(0); PG8_BAR; PG8_MMA(0, 0, At, B0); PG8_MMA(0, 1, At, B1); PG8_BAR; PG8_SCHED;
;             PG8_LDA(At, 0, 1); PG8_STAGE(PG8_SB(0, 0), b2, voffB); PG8_STAGE(PG8_SB(0, 1), b2 + hstepB, voffB); PG8_STAGE(PG8_SA(0, 0), a2, voffA);
;             PG8_WAIT_V(8); PG8_WAIT_L(0); PG8_BAR; PG8_MMA(1, 0, At, B0); PG8_MMA(1, 1, At, B1); PG8_BAR; PG8_SCHED;
	s_setprio 1
	s_waitcnt lgkmcnt(0)
	v_mfma_f32_16x16x32_bf16 v[126:129], v[164:167], v[200:203], v[126:129]
	v_mfma_f32_16x16x32_bf16 v[118:121], v[172:175], v[200:203], v[118:121]
	v_mfma_f32_16x16x32_bf16 v[110:113], v[164:167], v[208:211], v[110:113]
	v_mfma_f32_16x16x32_bf16 v[102:105], v[172:175], v[208:211], v[102:105]
	v_mfma_f32_16x16x32_bf16 v[94:97], v[164:167], v[216:219], v[94:97]
	v_mfma_f32_16x16x32_bf16 v[86:89], v[172:175], v[216:219], v[86:89]
	v_mfma_f32_16x16x32_bf16 v[78:81], v[164:167], v[224:227], v[78:81]
	v_mfma_f32_16x16x32_bf16 v[70:73], v[172:175], v[224:227], v[70:73]
	v_mfma_f32_16x16x32_bf16 v[126:129], v[168:171], v[204:207], v[126:129]
	v_mfma_f32_16x16x32_bf16 v[118:121], v[176:179], v[204:207], v[118:121]
	v_mfma_f32_16x16x32_bf16 v[110:113], v[168:171], v[212:215], v[110:113]
	v_mfma_f32_16x16x32_bf16 v[102:105], v[176:179], v[212:215], v[102:105]
	v_mfma_f32_16x16x32_bf16 v[94:97], v[168:171], v[220:223], v[94:97]
	v_mfma_f32_16x16x32_bf16 v[86:89], v[176:179], v[220:223], v[86:89]
	v_mfma_f32_16x16x32_bf16 v[78:81], v[168:171], v[228:231], v[78:81]
	v_mfma_f32_16x16x32_bf16 v[70:73], v[176:179], v[228:231], v[70:73]
	s_setprio 0
	s_setprio 1
	v_mfma_f32_16x16x32_bf16 v[122:125], v[184:187], v[200:203], v[122:125]
	v_mfma_f32_16x16x32_bf16 v[114:117], v[192:195], v[200:203], v[114:117]
	v_mfma_f32_16x16x32_bf16 v[106:109], v[184:187], v[208:211], v[106:109]
	v_mfma_f32_16x16x32_bf16 v[98:101], v[192:195], v[208:211], v[98:101]
	v_mfma_f32_16x16x32_bf16 v[90:93], v[184:187], v[216:219], v[90:93]
	v_mfma_f32_16x16x32_bf16 v[82:85], v[192:195], v[216:219], v[82:85]
	v_mfma_f32_16x16x32_bf16 v[74:77], v[184:187], v[224:227], v[74:77]
	v_mfma_f32_16x16x32_bf16 v[66:69], v[192:195], v[224:227], v[66:69]
	v_mfma_f32_16x16x32_bf16 v[122:125], v[188:191], v[204:207], v[122:125]
	v_mfma_f32_16x16x32_bf16 v[114:117], v[196:199], v[204:207], v[114:117]
	v_mfma_f32_16x16x32_bf16 v[106:109], v[188:191], v[212:215], v[106:109]
	v_mfma_f32_16x16x32_bf16 v[98:101], v[196:199], v[212:215], v[98:101]
	v_mfma_f32_16x16x32_bf16 v[90:93], v[188:191], v[220:223], v[90:93]
	v_mfma_f32_16x16x32_bf16 v[82:85], v[196:199], v[220:223], v[82:85]
	v_mfma_f32_16x16x32_bf16 v[74:77], v[188:191], v[228:231], v[74:77]
	v_mfma_f32_16x16x32_bf16 v[66:69], v[196:199], v[228:231], v[66:69]
	s_setprio 0
	s_barrier
	s_add_i32 s12, s39, s21
	v_lshl_add_u64 v[160:161], s[16:17], 0, v[134:135]
	s_mov_b32 m0, s12
	ds_read_b128 v[200:203], v163 offset:16384
	ds_read_b128 v[204:207], v163 offset:17408
	ds_read_b128 v[208:211], v163 offset:18432
	ds_read_b128 v[212:215], v163 offset:19456
	ds_read_b128 v[216:219], v163 offset:20480
	ds_read_b128 v[220:223], v163 offset:21504
	ds_read_b128 v[224:227], v163 offset:22528
	ds_read_b128 v[228:231], v163 offset:23552
	global_load_lds_dwordx4 v[160:161], off
	s_add_i32 m0, s12, 0x2000
	s_add_u32 s12, s16, 0x44000
	v_lshl_add_u64 v[180:181], s[16:17], 0, v[130:131]
	s_addc_u32 s13, s17, 0
	s_add_i32 s39, s40, s21
	global_load_lds_dwordx4 v[180:181], off
	v_lshl_add_u64 v[232:233], s[12:13], 0, v[134:135]
	s_mov_b32 m0, s39
	v_lshl_add_u64 v[234:235], s[18:19], 0, v[132:133]
	global_load_lds_dwordx4 v[232:233], off
	v_lshl_add_u64 v[232:233], s[12:13], 0, v[130:131]
	s_add_i32 m0, s39, 0x2000
	s_nop 0
	global_load_lds_dwordx4 v[232:233], off
	v_lshl_add_u64 v[232:233], s[18:19], 0, v[154:155]
	s_mov_b32 m0, s23
	s_nop 0
	global_load_lds_dwordx4 v[232:233], off
	s_mov_b32 m0, s24
	s_nop 0
	global_load_lds_dwordx4 v[234:235], off
	s_waitcnt vmcnt(8)
	s_waitcnt lgkmcnt(0)
	s_barrier
	s_setprio 1
	s_waitcnt lgkmcnt(0)
	v_mfma_f32_16x16x32_bf16 v[62:65], v[164:167], v[200:203], v[62:65]
	v_mfma_f32_16x16x32_bf16 v[54:57], v[172:175], v[200:203], v[54:57]
	v_mfma_f32_16x16x32_bf16 v[46:49], v[164:167], v[208:211], v[46:49]
	v_mfma_f32_16x16x32_bf16 v[38:41], v[172:175], v[208:211], v[38:41]
	v_mfma_f32_16x16x32_bf16 v[30:33], v[164:167], v[216:219], v[30:33]
	v_mfma_f32_16x16x32_bf16 v[22:25], v[172:175], v[216:219], v[22:25]
	v_mfma_f32_16x16x32_bf16 v[14:17], v[164:167], v[224:227], v[14:17]
	v_mfma_f32_16x16x32_bf16 v[6:9], v[172:175], v[224:227], v[6:9]
	v_mfma_f32_16x16x32_bf16 v[62:65], v[168:171], v[204:207], v[62:65]
	v_mfma_f32_16x16x32_bf16 v[54:57], v[176:179], v[204:207], v[54:57]
	v_mfma_f32_16x16x32_bf16 v[46:49], v[168:171], v[212:215], v[46:49]
	v_mfma_f32_16x16x32_bf16 v[38:41], v[176:179], v[212:215], v[38:41]
	v_mfma_f32_16x16x32_bf16 v[30:33], v[168:171], v[220:223], v[30:33]
	v_mfma_f32_16x16x32_bf16 v[22:25], v[176:179], v[220:223], v[22:25]
	v_mfma_f32_16x16x32_bf16 v[14:17], v[168:171], v[228:231], v[14:17]
	v_mfma_f32_16x16x32_bf16 v[6:9], v[176:179], v[228:231], v[6:9]
	s_setprio 0
	s_setprio 1
	v_mfma_f32_16x16x32_bf16 v[58:61], v[184:187], v[200:203], v[58:61]
	v_mfma_f32_16x16x32_bf16 v[50:53], v[192:195], v[200:203], v[50:53]
	v_mfma_f32_16x16x32_bf16 v[42:45], v[184:187], v[208:211], v[42:45]
	v_mfma_f32_16x16x32_bf16 v[34:37], v[192:195], v[208:211], v[34:37]
	v_mfma_f32_16x16x32_bf16 v[26:29], v[184:187], v[216:219], v[26:29]
	v_mfma_f32_16x16x32_bf16 v[18:21], v[192:195], v[216:219], v[18:21]
	v_mfma_f32_16x16x32_bf16 v[10:13], v[184:187], v[224:227], v[10:13]
	v_mfma_f32_16x16x32_bf16 v[2:5], v[192:195], v[224:227], v[2:5]
	v_mfma_f32_16x16x32_bf16 v[58:61], v[188:191], v[204:207], v[58:61]
	v_mfma_f32_16x16x32_bf16 v[50:53], v[196:199], v[204:207], v[50:53]
	v_mfma_f32_16x16x32_bf16 v[42:45], v[188:191], v[212:215], v[42:45]
	v_mfma_f32_16x16x32_bf16 v[34:37], v[196:199], v[212:215], v[34:37]
	v_mfma_f32_16x16x32_bf16 v[26:29], v[188:191], v[220:223], v[26:29]
	v_mfma_f32_16x16x32_bf16 v[18:21], v[196:199], v[220:223], v[18:21]
	v_mfma_f32_16x16x32_bf16 v[10:13], v[188:191], v[228:231], v[10:13]
	v_mfma_f32_16x16x32_bf16 v[2:5], v[196:199], v[228:231], v[2:5]
	s_setprio 0
	s_barrier
; #define PG8_STAGE(bufoff, gbase, voff) do { _Pragma("unroll") for (int _i = 0; _i < 2; ++_i) \
;         __builtin_amdgcn_global_load_lds((const unsigned*)((const char*)(gbase) + (voff)[_i]), (LAS unsigned*)(lds + (bufoff) + ldsw + _i * 8192), 16, 0, 0); } while (0)
; #define PG8_LDA(dst, b, h) do { _Pragma("unroll") for (int m = 0; m < 4; ++m) _Pragma("unroll") for (int k = 0; k < 2; ++k) dst[m][k] = *(const LAS bf16x8*)(lds + PG8_SA(b, h) + aoff + m * 2048 + k * 1024); } while (0)
; #define PG8_LDB(dst, b, h) do { _Pragma("unroll") for (int n = 0; n < 2; ++n) _Pragma("unroll") for (int k = 0; k < 2; ++k) dst[n][k] = *(const LAS bf16x8*)(lds + PG8_SB(b, h) + boff + n * 2048 + k * 1024); } while (0)
; #define PG8_MMA(ai, bj, At, Bt) do { __builtin_amdgcn_s_setprio(1); _Pragma("unroll") for (int m = 0; m < 4; ++m) _Pragma("unroll") for (int n = 0; n < 2; ++n) _Pragma("unroll") for (int k = 0; k < 2; ++k) \
;         acc[ai][bj][m][n] = __builtin_amdgcn_mfma_f32_16x16x32_bf16(Bt[n][k], At[m][k], acc[ai][bj][m][n], 0, 0, 0); __builtin_amdgcn_s_setprio(0); } while (0)
; #define PG8_WAIT_V(n) asm volatile("s_waitcnt vmcnt(" #n ")" ::: "memory")
; #define PG8_WAIT_L(n) asm volatile("s_waitcnt lgkmcnt(" #n ")" ::: "memory")
; #define PG8_BAR __builtin_amdgcn_s_barrier()
; #define PG8_SCHED __builtin_amdgcn_sched_barrier(0)
; template <class Epi, bool ALIGN_EPI = PG8_ALIGN, bool SP2 = PG8_SP2>
; __device__ __forceinline__ void gemm_phase(LAS uchar* lds, const Gemm g, const StaticOrder& S, const Epi& E) {
;     ...
;             PG8_LDB(B0, 1, 0); PG8_LDB(B1, 1, 1); PG8_SCHED; PG8_LDA(At, 1, 0); PG8_STAGE(PG8_SA(0, 1), a2 + hstepA, voffA);
;             PG8_WAIT_V(8); PG8_WAIT_L(0); PG8_BAR; PG8_MMA(0, 0, At, B0); PG8_MMA(0, 1, At, B1); PG8_BAR; PG8_SCHED;
	s_add_i32 s39, 0, 0x18000
	v_add_u32_e32 v144, s39, v139
	s_add_i32 s40, 0, 0x1c000
	ds_read_b128 v[164:167], v144
	ds_read_b128 v[168:171], v144 offset:1024
	ds_read_b128 v[172:175], v144 offset:2048
	ds_read_b128 v[176:179], v144 offset:3072
	v_add_u32_e32 v144, s40, v139
	ds_read_b128 v[184:187], v144
	ds_read_b128 v[188:191], v144 offset:1024
	ds_read_b128 v[192:195], v144 offset:2048
	ds_read_b128 v[196:199], v144 offset:3072
	s_add_u32 s12, s18, 0x44000
	s_addc_u32 s13, s19, 0
	s_mov_b32 m0, s25
	v_lshl_add_u64 v[236:237], s[12:13], 0, v[154:155]
	ds_read_b128 v[200:203], v163 offset:32768
	ds_read_b128 v[204:207], v163 offset:33792
	ds_read_b128 v[208:211], v163 offset:34816
	ds_read_b128 v[212:215], v163 offset:35840
	ds_read_b128 v[216:219], v163 offset:36864
	ds_read_b128 v[220:223], v163 offset:37888
	ds_read_b128 v[224:227], v163 offset:38912
	ds_read_b128 v[228:231], v163 offset:39936
	global_load_lds_dwordx4 v[236:237], off
	v_lshl_add_u64 v[236:237], s[12:13], 0, v[132:133]
	s_mov_b32 m0, s26
	s_nop 0
	global_load_lds_dwordx4 v[236:237], off
	s_waitcnt vmcnt(8)
	s_waitcnt lgkmcnt(0)
	s_barrier
	s_setprio 1
	s_waitcnt lgkmcnt(0)
	v_mfma_f32_16x16x32_bf16 v[126:129], v[164:167], v[200:203], v[126:129]
	v_mfma_f32_16x16x32_bf16 v[118:121], v[172:175], v[200:203], v[118:121]
	v_mfma_f32_16x16x32_bf16 v[110:113], v[164:167], v[208:211], v[110:113]
	v_mfma_f32_16x16x32_bf16 v[102:105], v[172:175], v[208:211], v[102:105]
	v_mfma_f32_16x16x32_bf16 v[94:97], v[164:167], v[216:219], v[94:97]
	v_mfma_f32_16x16x32_bf16 v[86:89], v[172:175], v[216:219], v[86:89]
	v_mfma_f32_16x16x32_bf16 v[78:81], v[164:167], v[224:227], v[78:81]
	v_mfma_f32_16x16x32_bf16 v[70:73], v[172:175], v[224:227], v[70:73]
	v_mfma_f32_16x16x32_bf16 v[126:129], v[168:171], v[204:207], v[126:129]
	v_mfma_f32_16x16x32_bf16 v[118:121], v[176:179], v[204:207], v[118:121]
	v_mfma_f32_16x16x32_bf16 v[110:113], v[168:171], v[212:215], v[110:113]
	v_mfma_f32_16x16x32_bf16 v[102:105], v[176:179], v[212:215], v[102:105]
	v_mfma_f32_16x16x32_bf16 v[94:97], v[168:171], v[220:223], v[94:97]
	v_mfma_f32_16x16x32_bf16 v[86:89], v[176:179], v[220:223], v[86:89]
	v_mfma_f32_16x16x32_bf16 v[78:81], v[168:171], v[228:231], v[78:81]
	v_mfma_f32_16x16x32_bf16 v[70:73], v[176:179], v[228:231], v[70:73]
	s_setprio 0
	s_setprio 1
	v_mfma_f32_16x16x32_bf16 v[122:125], v[184:187], v[200:203], v[122:125]
	v_mfma_f32_16x16x32_bf16 v[114:117], v[192:195], v[200:203], v[114:117]
	v_mfma_f32_16x16x32_bf16 v[106:109], v[184:187], v[208:211], v[106:109]
	v_mfma_f32_16x16x32_bf16 v[98:101], v[192:195], v[208:211], v[98:101]
	v_mfma_f32_16x16x32_bf16 v[90:93], v[184:187], v[216:219], v[90:93]
	v_mfma_f32_16x16x32_bf16 v[82:85], v[192:195], v[216:219], v[82:85]
	v_mfma_f32_16x16x32_bf16 v[74:77], v[184:187], v[224:227], v[74:77]
	v_mfma_f32_16x16x32_bf16 v[66:69], v[192:195], v[224:227], v[66:69]
	v_mfma_f32_16x16x32_bf16 v[122:125], v[188:191], v[204:207], v[122:125]
	v_mfma_f32_16x16x32_bf16 v[114:117], v[196:199], v[204:207], v[114:117]
	v_mfma_f32_16x16x32_bf16 v[106:109], v[188:191], v[212:215], v[106:109]
	v_mfma_f32_16x16x32_bf16 v[98:101], v[196:199], v[212:215], v[98:101]
	v_mfma_f32_16x16x32_bf16 v[90:93], v[188:191], v[220:223], v[90:93]
	v_mfma_f32_16x16x32_bf16 v[82:85], v[196:199], v[220:223], v[82:85]
	v_mfma_f32_16x16x32_bf16 v[74:77], v[188:191], v[228:231], v[74:77]
	v_mfma_f32_16x16x32_bf16 v[66:69], v[196:199], v[228:231], v[66:69]
	s_setprio 0
	s_barrier
; #define PG8_STAGE(bufoff, gbase, voff) do { _Pragma("unroll") for (int _i = 0; _i < 2; ++_i) \
;         __builtin_amdgcn_global_load_lds((const unsigned*)((const char*)(gbase) + (voff)[_i]), (LAS unsigned*)(lds + (bufoff) + ldsw + _i * 8192), 16, 0, 0); } while (0)
; #define PG8_LDA(dst, b, h) do { _Pragma("unroll") for (int m = 0; m < 4; ++m) _Pragma("unroll") for (int k = 0; k < 2; ++k) dst[m][k] = *(const LAS bf16x8*)(lds + PG8_SA(b, h) + aoff + m * 2048 + k * 1024); } while (0)
; #define PG8_LDB(dst, b, h) do { _Pragma("unroll") for (int n = 0; n < 2; ++n) _Pragma("unroll") for (int k = 0; k < 2; ++k) dst[n][k] = *(const LAS bf16x8*)(lds + PG8_SB(b, h) + boff + n * 2048 + k * 1024); } while (0)
; #define PG8_BAR __builtin_amdgcn_s_barrier()
; template <class Epi, bool ALIGN_EPI = PG8_ALIGN, bool SP2 = PG8_SP2>
; __device__ __forceinline__ void gemm_phase(LAS uchar* lds, const Gemm g, const StaticOrder& S, const Epi& E) {
;     ...
;         for (int t = tb; t < tb + tblk; t += 2) {
;             const bool last = (t == nt - 2);
;             const char* a1 = cA + (size_t)(t + 1) * kstep;
;             const char* a2 = last ? nA : cA + (size_t)(t + 2) * kstep; const char* b2 = last ? nB : cB + (size_t)(t + 2) * kstep;
;             const char* a3 = a2 + kstep; const char* b3 = b2 + kstep;
;             if constexpr (SP2) {
;             PG8_LDB(B0, 0, 0); PG8_LDB(B1, 0, 1); PG8_SCHED; PG8_LDA(At, 0, 0); PG8_STAGE(PG8_SA(1, 1), a1 + hstepA, voffA);
;             PG8_WAIT_V(8); PG8_WAIT_L(0); PG8_BAR; PG8_MMA(0, 0, At, B0); PG8_MMA(0, 1, At, B1); PG8_BAR; PG8_SCHED;
;             PG8_LDA(At, 0, 1); PG8_STAGE(PG8_SB(0, 0), b2, voffB); PG8_STAGE(PG8_SB(0, 1), b2 + hstepB, voffB); PG8_STAGE(PG8_SA(0, 0), a2, voffA);
;             PG8_WAIT_V(8); PG8_WAIT_L(0); PG8_BAR; PG8_MMA(1, 0, At, B0); PG8_MMA(1, 1, At, B1); PG8_BAR; PG8_SCHED;
;             PG8_LDB(B0, 1, 0); PG8_LDB(B1, 1, 1); PG8_SCHED; PG8_LDA(At, 1, 0); PG8_STAGE(PG8_SA(0, 1), a2 + hstepA, voffA);
;             PG8_WAIT_V(8); PG8_WAIT_L(0); PG8_BAR; PG8_MMA(0, 0, At, B0); PG8_MMA(0, 1, At, B1); PG8_BAR; PG8_SCHED;
;             PG8_LDA(At, 1, 1); PG8_STAGE(PG8_SB(1, 0), b3, voffB); PG8_STAGE(PG8_SB(1, 1), b3 + hstepB, voffB); PG8_STAGE(PG8_SA(1, 0), a3, voffA);
;             PG8_WAIT_V(8); PG8_WAIT_L(0); PG8_BAR; PG8_MMA(1, 0, At, B0); PG8_MMA(1, 1, At, B1); PG8_BAR; PG8_SCHED;
	s_add_i32 s12, s39, s21
	v_lshl_add_u64 v[160:161], v[160:161], 0, s[84:85]
	s_mov_b32 m0, s12
	ds_read_b128 v[200:203], v163 offset:49152
	ds_read_b128 v[204:207], v163 offset:50176
	ds_read_b128 v[208:211], v163 offset:51200
	ds_read_b128 v[212:215], v163 offset:52224
	ds_read_b128 v[216:219], v163 offset:53248
	ds_read_b128 v[220:223], v163 offset:54272
	ds_read_b128 v[224:227], v163 offset:55296
	ds_read_b128 v[228:231], v163 offset:56320
	global_load_lds_dwordx4 v[160:161], off
	s_add_i32 m0, s12, 0x2000
	s_add_u32 s12, s16, 0x44080
	v_lshl_add_u64 v[160:161], v[180:181], 0, s[84:85]
	s_addc_u32 s13, s17, 0
	s_add_i32 s16, s40, s21
	global_load_lds_dwordx4 v[160:161], off
	v_lshl_add_u64 v[160:161], s[12:13], 0, v[134:135]
	s_mov_b32 m0, s16
	s_nop 0
	global_load_lds_dwordx4 v[160:161], off
	v_lshl_add_u64 v[160:161], s[12:13], 0, v[130:131]
	s_add_i32 m0, s16, 0x2000
	s_nop 0
	global_load_lds_dwordx4 v[160:161], off
	v_lshl_add_u64 v[160:161], v[232:233], 0, s[84:85]
	s_mov_b32 m0, s27
	s_nop 0
	global_load_lds_dwordx4 v[160:161], off
	v_lshl_add_u64 v[160:161], v[234:235], 0, s[84:85]
	s_mov_b32 m0, s28
	s_nop 0
	global_load_lds_dwordx4 v[160:161], off
	s_waitcnt vmcnt(8)
	s_waitcnt lgkmcnt(0)
	s_barrier
	s_setprio 1
	s_waitcnt lgkmcnt(0)
	v_mfma_f32_16x16x32_bf16 v[62:65], v[164:167], v[200:203], v[62:65]
	v_mfma_f32_16x16x32_bf16 v[54:57], v[172:175], v[200:203], v[54:57]
	v_mfma_f32_16x16x32_bf16 v[46:49], v[164:167], v[208:211], v[46:49]
	v_mfma_f32_16x16x32_bf16 v[38:41], v[172:175], v[208:211], v[38:41]
	v_mfma_f32_16x16x32_bf16 v[30:33], v[164:167], v[216:219], v[30:33]
	v_mfma_f32_16x16x32_bf16 v[22:25], v[172:175], v[216:219], v[22:25]
	v_mfma_f32_16x16x32_bf16 v[14:17], v[164:167], v[224:227], v[14:17]
	v_mfma_f32_16x16x32_bf16 v[6:9], v[172:175], v[224:227], v[6:9]
	v_mfma_f32_16x16x32_bf16 v[62:65], v[168:171], v[204:207], v[62:65]
	v_mfma_f32_16x16x32_bf16 v[54:57], v[176:179], v[204:207], v[54:57]
	v_mfma_f32_16x16x32_bf16 v[46:49], v[168:171], v[212:215], v[46:49]
	v_mfma_f32_16x16x32_bf16 v[38:41], v[176:179], v[212:215], v[38:41]
	v_mfma_f32_16x16x32_bf16 v[30:33], v[168:171], v[220:223], v[30:33]
	v_mfma_f32_16x16x32_bf16 v[22:25], v[176:179], v[220:223], v[22:25]
	v_mfma_f32_16x16x32_bf16 v[14:17], v[168:171], v[228:231], v[14:17]
	v_mfma_f32_16x16x32_bf16 v[6:9], v[176:179], v[228:231], v[6:9]
	s_setprio 0
	s_setprio 1
	v_mfma_f32_16x16x32_bf16 v[58:61], v[184:187], v[200:203], v[58:61]
	v_mfma_f32_16x16x32_bf16 v[50:53], v[192:195], v[200:203], v[50:53]
	v_mfma_f32_16x16x32_bf16 v[42:45], v[184:187], v[208:211], v[42:45]
	v_mfma_f32_16x16x32_bf16 v[34:37], v[192:195], v[208:211], v[34:37]
	v_mfma_f32_16x16x32_bf16 v[26:29], v[184:187], v[216:219], v[26:29]
	v_mfma_f32_16x16x32_bf16 v[18:21], v[192:195], v[216:219], v[18:21]
	v_mfma_f32_16x16x32_bf16 v[10:13], v[184:187], v[224:227], v[10:13]
	v_mfma_f32_16x16x32_bf16 v[2:5], v[192:195], v[224:227], v[2:5]
	v_mfma_f32_16x16x32_bf16 v[58:61], v[188:191], v[204:207], v[58:61]
	v_mfma_f32_16x16x32_bf16 v[50:53], v[196:199], v[204:207], v[50:53]
	v_mfma_f32_16x16x32_bf16 v[42:45], v[188:191], v[212:215], v[42:45]
	v_mfma_f32_16x16x32_bf16 v[34:37], v[196:199], v[212:215], v[34:37]
	v_mfma_f32_16x16x32_bf16 v[26:29], v[188:191], v[220:223], v[26:29]
	v_mfma_f32_16x16x32_bf16 v[18:21], v[196:199], v[220:223], v[18:21]
	v_mfma_f32_16x16x32_bf16 v[10:13], v[188:191], v[228:231], v[10:13]
	v_mfma_f32_16x16x32_bf16 v[2:5], v[196:199], v[228:231], v[2:5]
	s_setprio 0
	s_add_i32 s38, s38, 2
	s_add_u32 s36, s36, 0x100
	s_addc_u32 s37, s37, 0
	s_cmp_gt_u32 s38, 13
	s_mov_b64 s[12:13], s[14:15]
	s_cbranch_scc1 .Lrot_exit_1050
	s_add_u32 s14, s12, 0x100
	s_addc_u32 s15, s13, 0
	s_add_i32 s39, 0, 0x10000
	s_cmp_eq_u32 s38, 12
	s_cselect_b32 s19, s1, s15
	s_cselect_b32 s18, s0, s14
	s_cselect_b32 s17, s11, s37
	s_cselect_b32 s16, s10, s36
	s_add_i32 s40, 0, 0x14000
	v_add_u32_e32 v144, s39, v139
	s_branch .LBB0_1050

; #define PG8_STAGE(bufoff, gbase, voff) do { _Pragma("unroll") for (int _i = 0; _i < 2; ++_i) \
;         __builtin_amdgcn_global_load_lds((const unsigned*)((const char*)(gbase) + (voff)[_i]), (LAS unsigned*)(lds + (bufoff) + ldsw + _i * 8192), 16, 0, 0); } while (0)
; #define PG8_LDA(dst, b, h) do { _Pragma("unroll") for (int m = 0; m < 4; ++m) _Pragma("unroll") for (int k = 0; k < 2; ++k) dst[m][k] = *(const LAS bf16x8*)(lds + PG8_SA(b, h) + aoff + m * 2048 + k * 1024); } while (0)
; #define PG8_LDB(dst, b, h) do { _Pragma("unroll") for (int n = 0; n < 2; ++n) _Pragma("unroll") for (int k = 0; k < 2; ++k) dst[n][k] = *(const LAS bf16x8*)(lds + PG8_SB(b, h) + boff + n * 2048 + k * 1024); } while (0)
; #define PG8_MMA(ai, bj, At, Bt) do { __builtin_amdgcn_s_setprio(1); _Pragma("unroll") for (int m = 0; m < 4; ++m) _Pragma("unroll") for (int n = 0; n < 2; ++n) _Pragma("unroll") for (int k = 0; k < 2; ++k) \
;         acc[ai][bj][m][n] = __builtin_amdgcn_mfma_f32_16x16x32_bf16(Bt[n][k], At[m][k], acc[ai][bj][m][n], 0, 0, 0); __builtin_amdgcn_s_setprio(0); } while (0)
; #define PG8_WAIT_V(n) asm volatile("s_waitcnt vmcnt(" #n ")" ::: "memory")
; #define PG8_WAIT_L(n) asm volatile("s_waitcnt lgkmcnt(" #n ")" ::: "memory")
; #define PG8_BAR __builtin_amdgcn_s_barrier()
; #define PG8_SCHED __builtin_amdgcn_sched_barrier(0)
; template <class Epi, bool ALIGN_EPI = PG8_ALIGN, bool SP2 = PG8_SP2>
; __device__ __forceinline__ void gemm_phase(LAS uchar* lds, const Gemm g, const StaticOrder& S, const Epi& E) {
;     ...
;             const bool last = (t == nt - 2);
;             const char* a1 = cA + (size_t)(t + 1) * kstep;
;             const char* a2 = last ? nA : cA + (size_t)(t + 2) * kstep; const char* b2 = last ? nB : cB + (size_t)(t + 2) * kstep;
;             const char* a3 = a2 + kstep; const char* b3 = b2 + kstep;
;             if constexpr (SP2) {
;             PG8_LDB(B0, 0, 0); PG8_LDB(B1, 0, 1); PG8_SCHED; PG8_LDA(At, 0, 0); PG8_STAGE(PG8_SA(1, 1), a1 + hstepA, voffA);
;             PG8_WAIT_V(8); PG8_WAIT_L(0); PG8_BAR; PG8_MMA(0, 0, At, B0); PG8_MMA(0, 1, At, B1); PG8_BAR; PG8_SCHED;
;             PG8_LDA(At, 0, 1); PG8_STAGE(PG8_SB(0, 0), b2, voffB); PG8_STAGE(PG8_SB(0, 1), b2 + hstepB, voffB); PG8_STAGE(PG8_SA(0, 0), a2, voffA);
;             PG8_WAIT_V(8); PG8_WAIT_L(0); PG8_BAR; PG8_MMA(1, 0, At, B0); PG8_MMA(1, 1, At, B1); PG8_BAR; PG8_SCHED;
.LBB0_1142:
	s_add_u32 s38, s16, 0x100
	s_addc_u32 s39, s17, 0
	s_mov_b32 s40, -2
	s_add_u32 s16, s14, 0x100
	s_addc_u32 s17, s15, 0
	s_add_i32 s41, 0, 0x10000
	s_cmp_eq_u32 s40, 40
	s_cselect_b32 s21, s5, s17
	s_cselect_b32 s20, s4, s16
	v_add_u32_e32 v144, s41, v139
	s_cselect_b32 s19, s13, s39
	s_cselect_b32 s18, s12, s38
	s_add_i32 s42, 0, 0x14000
	ds_read_b128 v[160:163], v144
	ds_read_b128 v[166:169], v144 offset:1024
	ds_read_b128 v[170:173], v144 offset:2048
	ds_read_b128 v[174:177], v144 offset:3072
	v_add_u32_e32 v144, s42, v139
	ds_read_b128 v[178:181], v144
	ds_read_b128 v[184:187], v144 offset:1024
	ds_read_b128 v[188:191], v144 offset:2048
	ds_read_b128 v[192:195], v144 offset:3072
	v_lshl_add_u64 v[228:229], s[14:15], 0, v[156:157]
	s_add_i32 m0, s25, 0xc000
	ds_read_b128 v[196:199], v165
	ds_read_b128 v[200:203], v165 offset:1024
	ds_read_b128 v[204:207], v165 offset:2048
	ds_read_b128 v[208:211], v165 offset:3072
	ds_read_b128 v[212:215], v165 offset:4096
	ds_read_b128 v[216:219], v165 offset:5120
	ds_read_b128 v[220:223], v165 offset:6144
	ds_read_b128 v[224:227], v165 offset:7168
	global_load_lds_dwordx4 v[228:229], off
	v_lshl_add_u64 v[228:229], s[14:15], 0, v[158:159]
	s_add_i32 m0, s25, 0xe000
	s_nop 0
	global_load_lds_dwordx4 v[228:229], off
	s_waitcnt vmcnt(8)
	s_waitcnt lgkmcnt(0)
	s_barrier
	s_setprio 1
	s_waitcnt lgkmcnt(0)
	v_mfma_f32_16x16x32_bf16 v[126:129], v[160:163], v[196:199], 0
	v_mfma_f32_16x16x32_bf16 v[122:125], v[170:173], v[196:199], 0
	v_mfma_f32_16x16x32_bf16 v[118:121], v[160:163], v[204:207], 0
	v_mfma_f32_16x16x32_bf16 v[110:113], v[170:173], v[204:207], 0
	v_mfma_f32_16x16x32_bf16 v[102:105], v[160:163], v[212:215], 0
	v_mfma_f32_16x16x32_bf16 v[94:97], v[170:173], v[212:215], 0
	v_mfma_f32_16x16x32_bf16 v[86:89], v[160:163], v[220:223], 0
	v_mfma_f32_16x16x32_bf16 v[78:81], v[170:173], v[220:223], 0
	v_mfma_f32_16x16x32_bf16 v[126:129], v[166:169], v[200:203], v[126:129]
	v_mfma_f32_16x16x32_bf16 v[122:125], v[174:177], v[200:203], v[122:125]
	v_mfma_f32_16x16x32_bf16 v[118:121], v[166:169], v[208:211], v[118:121]
	v_mfma_f32_16x16x32_bf16 v[110:113], v[174:177], v[208:211], v[110:113]
	v_mfma_f32_16x16x32_bf16 v[102:105], v[166:169], v[216:219], v[102:105]
	v_mfma_f32_16x16x32_bf16 v[94:97], v[174:177], v[216:219], v[94:97]
	v_mfma_f32_16x16x32_bf16 v[86:89], v[166:169], v[224:227], v[86:89]
	v_mfma_f32_16x16x32_bf16 v[78:81], v[174:177], v[224:227], v[78:81]
	s_setprio 0
	s_setprio 1
	v_mfma_f32_16x16x32_bf16 v[114:117], v[178:181], v[196:199], 0
	v_mfma_f32_16x16x32_bf16 v[106:109], v[188:191], v[196:199], 0
	v_mfma_f32_16x16x32_bf16 v[98:101], v[178:181], v[204:207], 0
	v_mfma_f32_16x16x32_bf16 v[90:93], v[188:191], v[204:207], 0
	v_mfma_f32_16x16x32_bf16 v[82:85], v[178:181], v[212:215], 0
	v_mfma_f32_16x16x32_bf16 v[74:77], v[188:191], v[212:215], 0
	v_mfma_f32_16x16x32_bf16 v[70:73], v[178:181], v[220:223], 0
	v_mfma_f32_16x16x32_bf16 v[66:69], v[188:191], v[220:223], 0
	v_mfma_f32_16x16x32_bf16 v[114:117], v[184:187], v[200:203], v[114:117]
	v_mfma_f32_16x16x32_bf16 v[106:109], v[192:195], v[200:203], v[106:109]
	v_mfma_f32_16x16x32_bf16 v[98:101], v[184:187], v[208:211], v[98:101]
	v_mfma_f32_16x16x32_bf16 v[90:93], v[192:195], v[208:211], v[90:93]
	v_mfma_f32_16x16x32_bf16 v[82:85], v[184:187], v[216:219], v[82:85]
	v_mfma_f32_16x16x32_bf16 v[74:77], v[192:195], v[216:219], v[74:77]
	v_mfma_f32_16x16x32_bf16 v[70:73], v[184:187], v[224:227], v[70:73]
	v_mfma_f32_16x16x32_bf16 v[66:69], v[192:195], v[224:227], v[66:69]
	s_setprio 0
	s_barrier
	s_add_i32 s14, s41, s24
	v_lshl_add_u64 v[228:229], s[18:19], 0, v[132:133]
	s_mov_b32 m0, s14
	ds_read_b128 v[196:199], v165 offset:16384
	ds_read_b128 v[200:203], v165 offset:17408
	ds_read_b128 v[204:207], v165 offset:18432
	ds_read_b128 v[208:211], v165 offset:19456
	ds_read_b128 v[212:215], v165 offset:20480
	ds_read_b128 v[216:219], v165 offset:21504
	ds_read_b128 v[220:223], v165 offset:22528
	ds_read_b128 v[224:227], v165 offset:23552
	global_load_lds_dwordx4 v[228:229], off
	s_add_i32 m0, s14, 0x2000
	s_add_u32 s14, s18, 0xb0000
	v_lshl_add_u64 v[230:231], s[18:19], 0, v[154:155]
	s_addc_u32 s15, s19, 0
	s_add_i32 s41, s42, s24
	global_load_lds_dwordx4 v[230:231], off
	v_lshl_add_u64 v[232:233], s[14:15], 0, v[132:133]
	s_mov_b32 m0, s41
	v_lshl_add_u64 v[234:235], s[20:21], 0, v[134:135]
	global_load_lds_dwordx4 v[232:233], off
	v_lshl_add_u64 v[232:233], s[14:15], 0, v[154:155]
	s_add_i32 m0, s41, 0x2000
	s_nop 0
	global_load_lds_dwordx4 v[232:233], off
	v_lshl_add_u64 v[232:233], s[20:21], 0, v[130:131]
	s_mov_b32 m0, s25
	s_nop 0
	global_load_lds_dwordx4 v[232:233], off
	s_mov_b32 m0, s26
	s_nop 0
	global_load_lds_dwordx4 v[234:235], off
	s_waitcnt vmcnt(8)
	s_waitcnt lgkmcnt(0)
	s_barrier
; #define PG8_STAGE(bufoff, gbase, voff) do { _Pragma("unroll") for (int _i = 0; _i < 2; ++_i) \
;         __builtin_amdgcn_global_load_lds((const unsigned*)((const char*)(gbase) + (voff)[_i]), (LAS unsigned*)(lds + (bufoff) + ldsw + _i * 8192), 16, 0, 0); } while (0)
; #define PG8_LDA(dst, b, h) do { _Pragma("unroll") for (int m = 0; m < 4; ++m) _Pragma("unroll") for (int k = 0; k < 2; ++k) dst[m][k] = *(const LAS bf16x8*)(lds + PG8_SA(b, h) + aoff + m * 2048 + k * 1024); } while (0)
; #define PG8_LDB(dst, b, h) do { _Pragma("unroll") for (int n = 0; n < 2; ++n) _Pragma("unroll") for (int k = 0; k < 2; ++k) dst[n][k] = *(const LAS bf16x8*)(lds + PG8_SB(b, h) + boff + n * 2048 + k * 1024); } while (0)
; #define PG8_MMA(ai, bj, At, Bt) do { __builtin_amdgcn_s_setprio(1); _Pragma("unroll") for (int m = 0; m < 4; ++m) _Pragma("unroll") for (int n = 0; n < 2; ++n) _Pragma("unroll") for (int k = 0; k < 2; ++k) \
;         acc[ai][bj][m][n] = __builtin_amdgcn_mfma_f32_16x16x32_bf16(Bt[n][k], At[m][k], acc[ai][bj][m][n], 0, 0, 0); __builtin_amdgcn_s_setprio(0); } while (0)
; #define PG8_WAIT_V(n) asm volatile("s_waitcnt vmcnt(" #n ")" ::: "memory")
; #define PG8_WAIT_L(n) asm volatile("s_waitcnt lgkmcnt(" #n ")" ::: "memory")
; #define PG8_BAR __builtin_amdgcn_s_barrier()
; #define PG8_SCHED __builtin_amdgcn_sched_barrier(0)
; template <class Epi, bool ALIGN_EPI = PG8_ALIGN, bool SP2 = PG8_SP2>
; __device__ __forceinline__ void gemm_phase(LAS uchar* lds, const Gemm g, const StaticOrder& S, const Epi& E) {
;     ...
;             PG8_WAIT_V(8); PG8_WAIT_L(0); PG8_BAR; PG8_MMA(1, 0, At, B0); PG8_MMA(1, 1, At, B1); PG8_BAR; PG8_SCHED;
;             PG8_LDB(B0, 1, 0); PG8_LDB(B1, 1, 1); PG8_SCHED; PG8_LDA(At, 1, 0); PG8_STAGE(PG8_SA(0, 1), a2 + hstepA, voffA);
;             PG8_WAIT_V(8); PG8_WAIT_L(0); PG8_BAR; PG8_MMA(0, 0, At, B0); PG8_MMA(0, 1, At, B1); PG8_BAR; PG8_SCHED;
	s_setprio 1
	s_waitcnt lgkmcnt(0)
	v_mfma_f32_16x16x32_bf16 v[62:65], v[160:163], v[196:199], 0
	v_mfma_f32_16x16x32_bf16 v[58:61], v[170:173], v[196:199], 0
	v_mfma_f32_16x16x32_bf16 v[54:57], v[160:163], v[204:207], 0
	v_mfma_f32_16x16x32_bf16 v[46:49], v[170:173], v[204:207], 0
	v_mfma_f32_16x16x32_bf16 v[38:41], v[160:163], v[212:215], 0
	v_mfma_f32_16x16x32_bf16 v[30:33], v[170:173], v[212:215], 0
	v_mfma_f32_16x16x32_bf16 v[22:25], v[160:163], v[220:223], 0
	v_mfma_f32_16x16x32_bf16 v[14:17], v[170:173], v[220:223], 0
	v_mfma_f32_16x16x32_bf16 v[62:65], v[166:169], v[200:203], v[62:65]
	v_mfma_f32_16x16x32_bf16 v[58:61], v[174:177], v[200:203], v[58:61]
	v_mfma_f32_16x16x32_bf16 v[54:57], v[166:169], v[208:211], v[54:57]
	v_mfma_f32_16x16x32_bf16 v[46:49], v[174:177], v[208:211], v[46:49]
	v_mfma_f32_16x16x32_bf16 v[38:41], v[166:169], v[216:219], v[38:41]
	v_mfma_f32_16x16x32_bf16 v[30:33], v[174:177], v[216:219], v[30:33]
	v_mfma_f32_16x16x32_bf16 v[22:25], v[166:169], v[224:227], v[22:25]
	v_mfma_f32_16x16x32_bf16 v[14:17], v[174:177], v[224:227], v[14:17]
	s_setprio 0
	s_setprio 1
	v_mfma_f32_16x16x32_bf16 v[50:53], v[178:181], v[196:199], 0
	v_mfma_f32_16x16x32_bf16 v[42:45], v[188:191], v[196:199], 0
	v_mfma_f32_16x16x32_bf16 v[34:37], v[178:181], v[204:207], 0
	v_mfma_f32_16x16x32_bf16 v[26:29], v[188:191], v[204:207], 0
	v_mfma_f32_16x16x32_bf16 v[18:21], v[178:181], v[212:215], 0
	v_mfma_f32_16x16x32_bf16 v[10:13], v[188:191], v[212:215], 0
	v_mfma_f32_16x16x32_bf16 v[6:9], v[178:181], v[220:223], 0
	v_mfma_f32_16x16x32_bf16 v[2:5], v[188:191], v[220:223], 0
	v_mfma_f32_16x16x32_bf16 v[50:53], v[184:187], v[200:203], v[50:53]
	v_mfma_f32_16x16x32_bf16 v[42:45], v[192:195], v[200:203], v[42:45]
	v_mfma_f32_16x16x32_bf16 v[34:37], v[184:187], v[208:211], v[34:37]
	v_mfma_f32_16x16x32_bf16 v[26:29], v[192:195], v[208:211], v[26:29]
	v_mfma_f32_16x16x32_bf16 v[18:21], v[184:187], v[216:219], v[18:21]
	v_mfma_f32_16x16x32_bf16 v[10:13], v[192:195], v[216:219], v[10:13]
	v_mfma_f32_16x16x32_bf16 v[6:9], v[184:187], v[224:227], v[6:9]
	v_mfma_f32_16x16x32_bf16 v[2:5], v[192:195], v[224:227], v[2:5]
	s_setprio 0
	s_barrier
	s_add_i32 s41, 0, 0x18000
	v_add_u32_e32 v144, s41, v139
	s_add_i32 s42, 0, 0x1c000
	ds_read_b128 v[160:163], v144
	ds_read_b128 v[166:169], v144 offset:1024
	ds_read_b128 v[170:173], v144 offset:2048
	ds_read_b128 v[174:177], v144 offset:3072
	v_add_u32_e32 v144, s42, v139
	ds_read_b128 v[178:181], v144
	ds_read_b128 v[184:187], v144 offset:1024
	ds_read_b128 v[188:191], v144 offset:2048
	ds_read_b128 v[192:195], v144 offset:3072
	s_add_u32 s14, s20, 0xb0000
	s_addc_u32 s15, s21, 0
	s_mov_b32 m0, s27
	v_lshl_add_u64 v[236:237], s[14:15], 0, v[130:131]
	ds_read_b128 v[196:199], v165 offset:32768
	ds_read_b128 v[200:203], v165 offset:33792
	ds_read_b128 v[204:207], v165 offset:34816
	ds_read_b128 v[208:211], v165 offset:35840
	ds_read_b128 v[212:215], v165 offset:36864
	ds_read_b128 v[216:219], v165 offset:37888
	ds_read_b128 v[220:223], v165 offset:38912
	ds_read_b128 v[224:227], v165 offset:39936
	global_load_lds_dwordx4 v[236:237], off
	v_lshl_add_u64 v[236:237], s[14:15], 0, v[134:135]
	s_mov_b32 m0, s28
	s_nop 0
	global_load_lds_dwordx4 v[236:237], off
	s_waitcnt vmcnt(8)
	s_waitcnt lgkmcnt(0)
	s_barrier
	s_setprio 1
	s_waitcnt lgkmcnt(0)
	v_mfma_f32_16x16x32_bf16 v[126:129], v[160:163], v[196:199], v[126:129]
	v_mfma_f32_16x16x32_bf16 v[122:125], v[170:173], v[196:199], v[122:125]
	v_mfma_f32_16x16x32_bf16 v[118:121], v[160:163], v[204:207], v[118:121]
	v_mfma_f32_16x16x32_bf16 v[110:113], v[170:173], v[204:207], v[110:113]
	v_mfma_f32_16x16x32_bf16 v[102:105], v[160:163], v[212:215], v[102:105]
	v_mfma_f32_16x16x32_bf16 v[94:97], v[170:173], v[212:215], v[94:97]
	v_mfma_f32_16x16x32_bf16 v[86:89], v[160:163], v[220:223], v[86:89]
	v_mfma_f32_16x16x32_bf16 v[78:81], v[170:173], v[220:223], v[78:81]
	v_mfma_f32_16x16x32_bf16 v[126:129], v[166:169], v[200:203], v[126:129]
	v_mfma_f32_16x16x32_bf16 v[122:125], v[174:177], v[200:203], v[122:125]
	v_mfma_f32_16x16x32_bf16 v[118:121], v[166:169], v[208:211], v[118:121]
	v_mfma_f32_16x16x32_bf16 v[110:113], v[174:177], v[208:211], v[110:113]
	v_mfma_f32_16x16x32_bf16 v[102:105], v[166:169], v[216:219], v[102:105]
	v_mfma_f32_16x16x32_bf16 v[94:97], v[174:177], v[216:219], v[94:97]
	v_mfma_f32_16x16x32_bf16 v[86:89], v[166:169], v[224:227], v[86:89]
	v_mfma_f32_16x16x32_bf16 v[78:81], v[174:177], v[224:227], v[78:81]
	s_setprio 0
	s_setprio 1
	v_mfma_f32_16x16x32_bf16 v[114:117], v[178:181], v[196:199], v[114:117]
	v_mfma_f32_16x16x32_bf16 v[106:109], v[188:191], v[196:199], v[106:109]
	v_mfma_f32_16x16x32_bf16 v[98:101], v[178:181], v[204:207], v[98:101]
	v_mfma_f32_16x16x32_bf16 v[90:93], v[188:191], v[204:207], v[90:93]
	v_mfma_f32_16x16x32_bf16 v[82:85], v[178:181], v[212:215], v[82:85]
	v_mfma_f32_16x16x32_bf16 v[74:77], v[188:191], v[212:215], v[74:77]
	v_mfma_f32_16x16x32_bf16 v[70:73], v[178:181], v[220:223], v[70:73]
	v_mfma_f32_16x16x32_bf16 v[66:69], v[188:191], v[220:223], v[66:69]
	v_mfma_f32_16x16x32_bf16 v[114:117], v[184:187], v[200:203], v[114:117]
	v_mfma_f32_16x16x32_bf16 v[106:109], v[192:195], v[200:203], v[106:109]
	v_mfma_f32_16x16x32_bf16 v[98:101], v[184:187], v[208:211], v[98:101]
	v_mfma_f32_16x16x32_bf16 v[90:93], v[192:195], v[208:211], v[90:93]
	v_mfma_f32_16x16x32_bf16 v[82:85], v[184:187], v[216:219], v[82:85]
	v_mfma_f32_16x16x32_bf16 v[74:77], v[192:195], v[216:219], v[74:77]
	v_mfma_f32_16x16x32_bf16 v[70:73], v[184:187], v[224:227], v[70:73]
	v_mfma_f32_16x16x32_bf16 v[66:69], v[192:195], v[224:227], v[66:69]
	s_setprio 0
	s_barrier
; #define PG8_STAGE(bufoff, gbase, voff) do { _Pragma("unroll") for (int _i = 0; _i < 2; ++_i) \
;         __builtin_amdgcn_global_load_lds((const unsigned*)((const char*)(gbase) + (voff)[_i]), (LAS unsigned*)(lds + (bufoff) + ldsw + _i * 8192), 16, 0, 0); } while (0)
; #define PG8_LDA(dst, b, h) do { _Pragma("unroll") for (int m = 0; m < 4; ++m) _Pragma("unroll") for (int k = 0; k < 2; ++k) dst[m][k] = *(const LAS bf16x8*)(lds + PG8_SA(b, h) + aoff + m * 2048 + k * 1024); } while (0)
; #define PG8_LDB(dst, b, h) do { _Pragma("unroll") for (int n = 0; n < 2; ++n) _Pragma("unroll") for (int k = 0; k < 2; ++k) dst[n][k] = *(const LAS bf16x8*)(lds + PG8_SB(b, h) + boff + n * 2048 + k * 1024); } while (0)
; #define PG8_BAR __builtin_amdgcn_s_barrier()
; template <class Epi, bool ALIGN_EPI = PG8_ALIGN, bool SP2 = PG8_SP2>
; __device__ __forceinline__ void gemm_phase(LAS uchar* lds, const Gemm g, const StaticOrder& S, const Epi& E) {
;     ...
;         for (int t = tb; t < tb + tblk; t += 2) {
;             const bool last = (t == nt - 2);
;             const char* a1 = cA + (size_t)(t + 1) * kstep;
;             const char* a2 = last ? nA : cA + (size_t)(t + 2) * kstep; const char* b2 = last ? nB : cB + (size_t)(t + 2) * kstep;
;             const char* a3 = a2 + kstep; const char* b3 = b2 + kstep;
;             if constexpr (SP2) {
;             PG8_LDB(B0, 0, 0); PG8_LDB(B1, 0, 1); PG8_SCHED; PG8_LDA(At, 0, 0); PG8_STAGE(PG8_SA(1, 1), a1 + hstepA, voffA);
;             PG8_WAIT_V(8); PG8_WAIT_L(0); PG8_BAR; PG8_MMA(0, 0, At, B0); PG8_MMA(0, 1, At, B1); PG8_BAR; PG8_SCHED;
;             PG8_LDA(At, 0, 1); PG8_STAGE(PG8_SB(0, 0), b2, voffB); PG8_STAGE(PG8_SB(0, 1), b2 + hstepB, voffB); PG8_STAGE(PG8_SA(0, 0), a2, voffA);
;             PG8_WAIT_V(8); PG8_WAIT_L(0); PG8_BAR; PG8_MMA(1, 0, At, B0); PG8_MMA(1, 1, At, B1); PG8_BAR; PG8_SCHED;
;             PG8_LDB(B0, 1, 0); PG8_LDB(B1, 1, 1); PG8_SCHED; PG8_LDA(At, 1, 0); PG8_STAGE(PG8_SA(0, 1), a2 + hstepA, voffA);
;             PG8_WAIT_V(8); PG8_WAIT_L(0); PG8_BAR; PG8_MMA(0, 0, At, B0); PG8_MMA(0, 1, At, B1); PG8_BAR; PG8_SCHED;
;             PG8_LDA(At, 1, 1); PG8_STAGE(PG8_SB(1, 0), b3, voffB); PG8_STAGE(PG8_SB(1, 1), b3 + hstepB, voffB); PG8_STAGE(PG8_SA(1, 0), a3, voffA);
;             PG8_WAIT_V(8); PG8_WAIT_L(0); PG8_BAR; PG8_MMA(1, 0, At, B0); PG8_MMA(1, 1, At, B1); PG8_BAR; PG8_SCHED;
	s_add_i32 s14, s41, s24
	v_lshl_add_u64 v[228:229], v[228:229], 0, s[84:85]
	s_mov_b32 m0, s14
	ds_read_b128 v[196:199], v165 offset:49152
	ds_read_b128 v[200:203], v165 offset:50176
	ds_read_b128 v[204:207], v165 offset:51200
	ds_read_b128 v[208:211], v165 offset:52224
	ds_read_b128 v[212:215], v165 offset:53248
	ds_read_b128 v[216:219], v165 offset:54272
	ds_read_b128 v[220:223], v165 offset:55296
	ds_read_b128 v[224:227], v165 offset:56320
	global_load_lds_dwordx4 v[228:229], off
	s_add_i32 m0, s14, 0x2000
	s_add_u32 s14, s18, 0xb0080
	v_lshl_add_u64 v[228:229], v[230:231], 0, s[84:85]
	s_addc_u32 s15, s19, 0
	s_add_i32 s18, s42, s24
	global_load_lds_dwordx4 v[228:229], off
	v_lshl_add_u64 v[228:229], s[14:15], 0, v[132:133]
	s_mov_b32 m0, s18
	s_nop 0
	global_load_lds_dwordx4 v[228:229], off
	v_lshl_add_u64 v[228:229], s[14:15], 0, v[154:155]
	s_add_i32 m0, s18, 0x2000
	s_nop 0
	global_load_lds_dwordx4 v[228:229], off
	v_lshl_add_u64 v[228:229], v[232:233], 0, s[84:85]
	s_mov_b32 m0, s29
	s_nop 0
	global_load_lds_dwordx4 v[228:229], off
	v_lshl_add_u64 v[228:229], v[234:235], 0, s[84:85]
	s_mov_b32 m0, s30
	s_nop 0
	global_load_lds_dwordx4 v[228:229], off
	s_waitcnt vmcnt(8)
	s_waitcnt lgkmcnt(0)
	s_barrier
	s_setprio 1
	s_waitcnt lgkmcnt(0)
	v_mfma_f32_16x16x32_bf16 v[62:65], v[160:163], v[196:199], v[62:65]
	v_mfma_f32_16x16x32_bf16 v[58:61], v[170:173], v[196:199], v[58:61]
	v_mfma_f32_16x16x32_bf16 v[54:57], v[160:163], v[204:207], v[54:57]
	v_mfma_f32_16x16x32_bf16 v[46:49], v[170:173], v[204:207], v[46:49]
	v_mfma_f32_16x16x32_bf16 v[38:41], v[160:163], v[212:215], v[38:41]
	v_mfma_f32_16x16x32_bf16 v[30:33], v[170:173], v[212:215], v[30:33]
	v_mfma_f32_16x16x32_bf16 v[22:25], v[160:163], v[220:223], v[22:25]
	v_mfma_f32_16x16x32_bf16 v[14:17], v[170:173], v[220:223], v[14:17]
	v_mfma_f32_16x16x32_bf16 v[62:65], v[166:169], v[200:203], v[62:65]
	v_mfma_f32_16x16x32_bf16 v[58:61], v[174:177], v[200:203], v[58:61]
	v_mfma_f32_16x16x32_bf16 v[54:57], v[166:169], v[208:211], v[54:57]
	v_mfma_f32_16x16x32_bf16 v[46:49], v[174:177], v[208:211], v[46:49]
	v_mfma_f32_16x16x32_bf16 v[38:41], v[166:169], v[216:219], v[38:41]
	v_mfma_f32_16x16x32_bf16 v[30:33], v[174:177], v[216:219], v[30:33]
	v_mfma_f32_16x16x32_bf16 v[22:25], v[166:169], v[224:227], v[22:25]
	v_mfma_f32_16x16x32_bf16 v[14:17], v[174:177], v[224:227], v[14:17]
	s_setprio 0
	s_setprio 1
	v_mfma_f32_16x16x32_bf16 v[50:53], v[178:181], v[196:199], v[50:53]
	v_mfma_f32_16x16x32_bf16 v[42:45], v[188:191], v[196:199], v[42:45]
	v_mfma_f32_16x16x32_bf16 v[34:37], v[178:181], v[204:207], v[34:37]
	v_mfma_f32_16x16x32_bf16 v[26:29], v[188:191], v[204:207], v[26:29]
	v_mfma_f32_16x16x32_bf16 v[18:21], v[178:181], v[212:215], v[18:21]
	v_mfma_f32_16x16x32_bf16 v[10:13], v[188:191], v[212:215], v[10:13]
	v_mfma_f32_16x16x32_bf16 v[6:9], v[178:181], v[220:223], v[6:9]
	v_mfma_f32_16x16x32_bf16 v[2:5], v[188:191], v[220:223], v[2:5]
	v_mfma_f32_16x16x32_bf16 v[50:53], v[184:187], v[200:203], v[50:53]
	v_mfma_f32_16x16x32_bf16 v[42:45], v[192:195], v[200:203], v[42:45]
	v_mfma_f32_16x16x32_bf16 v[34:37], v[184:187], v[208:211], v[34:37]
	v_mfma_f32_16x16x32_bf16 v[26:29], v[192:195], v[208:211], v[26:29]
	v_mfma_f32_16x16x32_bf16 v[18:21], v[184:187], v[216:219], v[18:21]
	v_mfma_f32_16x16x32_bf16 v[10:13], v[192:195], v[216:219], v[10:13]
	v_mfma_f32_16x16x32_bf16 v[6:9], v[184:187], v[224:227], v[6:9]
	v_mfma_f32_16x16x32_bf16 v[2:5], v[192:195], v[224:227], v[2:5]
	s_setprio 0
	s_add_i32 s40, s40, 2
	s_add_u32 s38, s38, 0x100
	s_addc_u32 s39, s39, 0
	s_cmp_gt_u32 s40, 41
	s_mov_b64 s[14:15], s[16:17]
	s_add_u32 s16, s14, 0x100
	s_addc_u32 s17, s15, 0
	s_add_i32 s41, 0, 0x10000
	s_cmp_eq_u32 s40, 40
	s_cselect_b32 s21, s5, s17
	s_cselect_b32 s20, s4, s16
	s_cselect_b32 s19, s13, s39
	s_cselect_b32 s18, s12, s38
	s_add_i32 s42, 0, 0x14000
	v_add_u32_e32 v144, s41, v139
.LBB0_1143:
	s_barrier
	ds_read_b128 v[160:163], v144
	ds_read_b128 v[166:169], v144 offset:1024
	ds_read_b128 v[170:173], v144 offset:2048
	ds_read_b128 v[174:177], v144 offset:3072
	v_add_u32_e32 v144, s42, v139
	ds_read_b128 v[178:181], v144
	ds_read_b128 v[184:187], v144 offset:1024
	ds_read_b128 v[188:191], v144 offset:2048
	ds_read_b128 v[192:195], v144 offset:3072
	v_lshl_add_u64 v[228:229], s[14:15], 0, v[156:157]
	s_add_i32 m0, s25, 0xc000
	ds_read_b128 v[196:199], v165
	ds_read_b128 v[200:203], v165 offset:1024
	ds_read_b128 v[204:207], v165 offset:2048
	ds_read_b128 v[208:211], v165 offset:3072
	ds_read_b128 v[212:215], v165 offset:4096
	ds_read_b128 v[216:219], v165 offset:5120
	ds_read_b128 v[220:223], v165 offset:6144
	ds_read_b128 v[224:227], v165 offset:7168
	global_load_lds_dwordx4 v[228:229], off
	v_lshl_add_u64 v[228:229], s[14:15], 0, v[158:159]
	s_add_i32 m0, s25, 0xe000
	s_nop 0
	global_load_lds_dwordx4 v[228:229], off
	s_waitcnt vmcnt(8)
	s_waitcnt lgkmcnt(0)
	s_barrier
; #define PG8_STAGE(bufoff, gbase, voff) do { _Pragma("unroll") for (int _i = 0; _i < 2; ++_i) \
;         __builtin_amdgcn_global_load_lds((const unsigned*)((const char*)(gbase) + (voff)[_i]), (LAS unsigned*)(lds + (bufoff) + ldsw + _i * 8192), 16, 0, 0); } while (0)
; #define PG8_LDA(dst, b, h) do { _Pragma("unroll") for (int m = 0; m < 4; ++m) _Pragma("unroll") for (int k = 0; k < 2; ++k) dst[m][k] = *(const LAS bf16x8*)(lds + PG8_SA(b, h) + aoff + m * 2048 + k * 1024); } while (0)
; #define PG8_LDB(dst, b, h) do { _Pragma("unroll") for (int n = 0; n < 2; ++n) _Pragma("unroll") for (int k = 0; k < 2; ++k) dst[n][k] = *(const LAS bf16x8*)(lds + PG8_SB(b, h) + boff + n * 2048 + k * 1024); } while (0)
; #define PG8_MMA(ai, bj, At, Bt) do { __builtin_amdgcn_s_setprio(1); _Pragma("unroll") for (int m = 0; m < 4; ++m) _Pragma("unroll") for (int n = 0; n < 2; ++n) _Pragma("unroll") for (int k = 0; k < 2; ++k) \
;         acc[ai][bj][m][n] = __builtin_amdgcn_mfma_f32_16x16x32_bf16(Bt[n][k], At[m][k], acc[ai][bj][m][n], 0, 0, 0); __builtin_amdgcn_s_setprio(0); } while (0)
; #define PG8_WAIT_V(n) asm volatile("s_waitcnt vmcnt(" #n ")" ::: "memory")
; #define PG8_WAIT_L(n) asm volatile("s_waitcnt lgkmcnt(" #n ")" ::: "memory")
; #define PG8_BAR __builtin_amdgcn_s_barrier()
; #define PG8_SCHED __builtin_amdgcn_sched_barrier(0)
; template <class Epi, bool ALIGN_EPI = PG8_ALIGN, bool SP2 = PG8_SP2>
; __device__ __forceinline__ void gemm_phase(LAS uchar* lds, const Gemm g, const StaticOrder& S, const Epi& E) {
;     ...
;             PG8_LDB(B0, 0, 0); PG8_LDB(B1, 0, 1); PG8_SCHED; PG8_LDA(At, 0, 0); PG8_STAGE(PG8_SA(1, 1), a1 + hstepA, voffA);
;             PG8_WAIT_V(8); PG8_WAIT_L(0); PG8_BAR; PG8_MMA(0, 0, At, B0); PG8_MMA(0, 1, At, B1); PG8_BAR; PG8_SCHED;
;             PG8_LDA(At, 0, 1); PG8_STAGE(PG8_SB(0, 0), b2, voffB); PG8_STAGE(PG8_SB(0, 1), b2 + hstepB, voffB); PG8_STAGE(PG8_SA(0, 0), a2, voffA);
;             PG8_WAIT_V(8); PG8_WAIT_L(0); PG8_BAR; PG8_MMA(1, 0, At, B0); PG8_MMA(1, 1, At, B1); PG8_BAR; PG8_SCHED;
	s_setprio 1
	s_waitcnt lgkmcnt(0)
	v_mfma_f32_16x16x32_bf16 v[126:129], v[160:163], v[196:199], v[126:129]
	v_mfma_f32_16x16x32_bf16 v[122:125], v[170:173], v[196:199], v[122:125]
	v_mfma_f32_16x16x32_bf16 v[118:121], v[160:163], v[204:207], v[118:121]
	v_mfma_f32_16x16x32_bf16 v[110:113], v[170:173], v[204:207], v[110:113]
	v_mfma_f32_16x16x32_bf16 v[102:105], v[160:163], v[212:215], v[102:105]
	v_mfma_f32_16x16x32_bf16 v[94:97], v[170:173], v[212:215], v[94:97]
	v_mfma_f32_16x16x32_bf16 v[86:89], v[160:163], v[220:223], v[86:89]
	v_mfma_f32_16x16x32_bf16 v[78:81], v[170:173], v[220:223], v[78:81]
	v_mfma_f32_16x16x32_bf16 v[126:129], v[166:169], v[200:203], v[126:129]
	v_mfma_f32_16x16x32_bf16 v[122:125], v[174:177], v[200:203], v[122:125]
	v_mfma_f32_16x16x32_bf16 v[118:121], v[166:169], v[208:211], v[118:121]
	v_mfma_f32_16x16x32_bf16 v[110:113], v[174:177], v[208:211], v[110:113]
	v_mfma_f32_16x16x32_bf16 v[102:105], v[166:169], v[216:219], v[102:105]
	v_mfma_f32_16x16x32_bf16 v[94:97], v[174:177], v[216:219], v[94:97]
	v_mfma_f32_16x16x32_bf16 v[86:89], v[166:169], v[224:227], v[86:89]
	v_mfma_f32_16x16x32_bf16 v[78:81], v[174:177], v[224:227], v[78:81]
	s_setprio 0
	s_setprio 1
	v_mfma_f32_16x16x32_bf16 v[114:117], v[178:181], v[196:199], v[114:117]
	v_mfma_f32_16x16x32_bf16 v[106:109], v[188:191], v[196:199], v[106:109]
	v_mfma_f32_16x16x32_bf16 v[98:101], v[178:181], v[204:207], v[98:101]
	v_mfma_f32_16x16x32_bf16 v[90:93], v[188:191], v[204:207], v[90:93]
	v_mfma_f32_16x16x32_bf16 v[82:85], v[178:181], v[212:215], v[82:85]
	v_mfma_f32_16x16x32_bf16 v[74:77], v[188:191], v[212:215], v[74:77]
	v_mfma_f32_16x16x32_bf16 v[70:73], v[178:181], v[220:223], v[70:73]
	v_mfma_f32_16x16x32_bf16 v[66:69], v[188:191], v[220:223], v[66:69]
	v_mfma_f32_16x16x32_bf16 v[114:117], v[184:187], v[200:203], v[114:117]
	v_mfma_f32_16x16x32_bf16 v[106:109], v[192:195], v[200:203], v[106:109]
	v_mfma_f32_16x16x32_bf16 v[98:101], v[184:187], v[208:211], v[98:101]
	v_mfma_f32_16x16x32_bf16 v[90:93], v[192:195], v[208:211], v[90:93]
	v_mfma_f32_16x16x32_bf16 v[82:85], v[184:187], v[216:219], v[82:85]
	v_mfma_f32_16x16x32_bf16 v[74:77], v[192:195], v[216:219], v[74:77]
	v_mfma_f32_16x16x32_bf16 v[70:73], v[184:187], v[224:227], v[70:73]
	v_mfma_f32_16x16x32_bf16 v[66:69], v[192:195], v[224:227], v[66:69]
	s_setprio 0
	s_barrier
	s_add_i32 s14, s41, s24
	v_lshl_add_u64 v[228:229], s[18:19], 0, v[132:133]
	s_mov_b32 m0, s14
	ds_read_b128 v[196:199], v165 offset:16384
	ds_read_b128 v[200:203], v165 offset:17408
	ds_read_b128 v[204:207], v165 offset:18432
	ds_read_b128 v[208:211], v165 offset:19456
	ds_read_b128 v[212:215], v165 offset:20480
	ds_read_b128 v[216:219], v165 offset:21504
	ds_read_b128 v[220:223], v165 offset:22528
	ds_read_b128 v[224:227], v165 offset:23552
	global_load_lds_dwordx4 v[228:229], off
	s_add_i32 m0, s14, 0x2000
	s_add_u32 s14, s18, 0xb0000
	v_lshl_add_u64 v[230:231], s[18:19], 0, v[154:155]
	s_addc_u32 s15, s19, 0
	s_add_i32 s41, s42, s24
	global_load_lds_dwordx4 v[230:231], off
	v_lshl_add_u64 v[232:233], s[14:15], 0, v[132:133]
	s_mov_b32 m0, s41
	v_lshl_add_u64 v[234:235], s[20:21], 0, v[134:135]
	global_load_lds_dwordx4 v[232:233], off
	v_lshl_add_u64 v[232:233], s[14:15], 0, v[154:155]
	s_add_i32 m0, s41, 0x2000
	s_nop 0
	global_load_lds_dwordx4 v[232:233], off
	v_lshl_add_u64 v[232:233], s[20:21], 0, v[130:131]
	s_mov_b32 m0, s25
	s_nop 0
	global_load_lds_dwordx4 v[232:233], off
	s_mov_b32 m0, s26
	s_nop 0
	global_load_lds_dwordx4 v[234:235], off
	s_waitcnt vmcnt(8)
	s_waitcnt lgkmcnt(0)
	s_barrier
	s_setprio 1
	s_waitcnt lgkmcnt(0)
	v_mfma_f32_16x16x32_bf16 v[62:65], v[160:163], v[196:199], v[62:65]
	v_mfma_f32_16x16x32_bf16 v[58:61], v[170:173], v[196:199], v[58:61]
	v_mfma_f32_16x16x32_bf16 v[54:57], v[160:163], v[204:207], v[54:57]
	v_mfma_f32_16x16x32_bf16 v[46:49], v[170:173], v[204:207], v[46:49]
	v_mfma_f32_16x16x32_bf16 v[38:41], v[160:163], v[212:215], v[38:41]
	v_mfma_f32_16x16x32_bf16 v[30:33], v[170:173], v[212:215], v[30:33]
	v_mfma_f32_16x16x32_bf16 v[22:25], v[160:163], v[220:223], v[22:25]
	v_mfma_f32_16x16x32_bf16 v[14:17], v[170:173], v[220:223], v[14:17]
	v_mfma_f32_16x16x32_bf16 v[62:65], v[166:169], v[200:203], v[62:65]
	v_mfma_f32_16x16x32_bf16 v[58:61], v[174:177], v[200:203], v[58:61]
	v_mfma_f32_16x16x32_bf16 v[54:57], v[166:169], v[208:211], v[54:57]
	v_mfma_f32_16x16x32_bf16 v[46:49], v[174:177], v[208:211], v[46:49]
	v_mfma_f32_16x16x32_bf16 v[38:41], v[166:169], v[216:219], v[38:41]
	v_mfma_f32_16x16x32_bf16 v[30:33], v[174:177], v[216:219], v[30:33]
	v_mfma_f32_16x16x32_bf16 v[22:25], v[166:169], v[224:227], v[22:25]
	v_mfma_f32_16x16x32_bf16 v[14:17], v[174:177], v[224:227], v[14:17]
	s_setprio 0
	s_setprio 1
	v_mfma_f32_16x16x32_bf16 v[50:53], v[178:181], v[196:199], v[50:53]
	v_mfma_f32_16x16x32_bf16 v[42:45], v[188:191], v[196:199], v[42:45]
	v_mfma_f32_16x16x32_bf16 v[34:37], v[178:181], v[204:207], v[34:37]
	v_mfma_f32_16x16x32_bf16 v[26:29], v[188:191], v[204:207], v[26:29]
	v_mfma_f32_16x16x32_bf16 v[18:21], v[178:181], v[212:215], v[18:21]
	v_mfma_f32_16x16x32_bf16 v[10:13], v[188:191], v[212:215], v[10:13]
	v_mfma_f32_16x16x32_bf16 v[6:9], v[178:181], v[220:223], v[6:9]
	v_mfma_f32_16x16x32_bf16 v[2:5], v[188:191], v[220:223], v[2:5]
	v_mfma_f32_16x16x32_bf16 v[50:53], v[184:187], v[200:203], v[50:53]
	v_mfma_f32_16x16x32_bf16 v[42:45], v[192:195], v[200:203], v[42:45]
	v_mfma_f32_16x16x32_bf16 v[34:37], v[184:187], v[208:211], v[34:37]
	v_mfma_f32_16x16x32_bf16 v[26:29], v[192:195], v[208:211], v[26:29]
	v_mfma_f32_16x16x32_bf16 v[18:21], v[184:187], v[216:219], v[18:21]
	v_mfma_f32_16x16x32_bf16 v[10:13], v[192:195], v[216:219], v[10:13]
	v_mfma_f32_16x16x32_bf16 v[6:9], v[184:187], v[224:227], v[6:9]
	v_mfma_f32_16x16x32_bf16 v[2:5], v[192:195], v[224:227], v[2:5]
	s_setprio 0
	s_barrier
; #define PG8_STAGE(bufoff, gbase, voff) do { _Pragma("unroll") for (int _i = 0; _i < 2; ++_i) \
;         __builtin_amdgcn_global_load_lds((const unsigned*)((const char*)(gbase) + (voff)[_i]), (LAS unsigned*)(lds + (bufoff) + ldsw + _i * 8192), 16, 0, 0); } while (0)
; #define PG8_LDA(dst, b, h) do { _Pragma("unroll") for (int m = 0; m < 4; ++m) _Pragma("unroll") for (int k = 0; k < 2; ++k) dst[m][k] = *(const LAS bf16x8*)(lds + PG8_SA(b, h) + aoff + m * 2048 + k * 1024); } while (0)
; #define PG8_LDB(dst, b, h) do { _Pragma("unroll") for (int n = 0; n < 2; ++n) _Pragma("unroll") for (int k = 0; k < 2; ++k) dst[n][k] = *(const LAS bf16x8*)(lds + PG8_SB(b, h) + boff + n * 2048 + k * 1024); } while (0)
; #define PG8_MMA(ai, bj, At, Bt) do { __builtin_amdgcn_s_setprio(1); _Pragma("unroll") for (int m = 0; m < 4; ++m) _Pragma("unroll") for (int n = 0; n < 2; ++n) _Pragma("unroll") for (int k = 0; k < 2; ++k) \
;         acc[ai][bj][m][n] = __builtin_amdgcn_mfma_f32_16x16x32_bf16(Bt[n][k], At[m][k], acc[ai][bj][m][n], 0, 0, 0); __builtin_amdgcn_s_setprio(0); } while (0)
; #define PG8_WAIT_V(n) asm volatile("s_waitcnt vmcnt(" #n ")" ::: "memory")
; #define PG8_WAIT_L(n) asm volatile("s_waitcnt lgkmcnt(" #n ")" ::: "memory")
; #define PG8_BAR __builtin_amdgcn_s_barrier()
; #define PG8_SCHED __builtin_amdgcn_sched_barrier(0)
; template <class Epi, bool ALIGN_EPI = PG8_ALIGN, bool SP2 = PG8_SP2>
; __device__ __forceinline__ void gemm_phase(LAS uchar* lds, const Gemm g, const StaticOrder& S, const Epi& E) {
;     ...
;             PG8_LDB(B0, 1, 0); PG8_LDB(B1, 1, 1); PG8_SCHED; PG8_LDA(At, 1, 0); PG8_STAGE(PG8_SA(0, 1), a2 + hstepA, voffA);
;             PG8_WAIT_V(8); PG8_WAIT_L(0); PG8_BAR; PG8_MMA(0, 0, At, B0); PG8_MMA(0, 1, At, B1); PG8_BAR; PG8_SCHED;
	s_add_i32 s41, 0, 0x18000
	v_add_u32_e32 v144, s41, v139
	s_add_i32 s42, 0, 0x1c000
	ds_read_b128 v[160:163], v144
	ds_read_b128 v[166:169], v144 offset:1024
	ds_read_b128 v[170:173], v144 offset:2048
	ds_read_b128 v[174:177], v144 offset:3072
	v_add_u32_e32 v144, s42, v139
	ds_read_b128 v[178:181], v144
	ds_read_b128 v[184:187], v144 offset:1024
	ds_read_b128 v[188:191], v144 offset:2048
	ds_read_b128 v[192:195], v144 offset:3072
	s_add_u32 s14, s20, 0xb0000
	s_addc_u32 s15, s21, 0
	s_mov_b32 m0, s27
	v_lshl_add_u64 v[236:237], s[14:15], 0, v[130:131]
	ds_read_b128 v[196:199], v165 offset:32768
	ds_read_b128 v[200:203], v165 offset:33792
	ds_read_b128 v[204:207], v165 offset:34816
	ds_read_b128 v[208:211], v165 offset:35840
	ds_read_b128 v[212:215], v165 offset:36864
	ds_read_b128 v[216:219], v165 offset:37888
	ds_read_b128 v[220:223], v165 offset:38912
	ds_read_b128 v[224:227], v165 offset:39936
	global_load_lds_dwordx4 v[236:237], off
	v_lshl_add_u64 v[236:237], s[14:15], 0, v[134:135]
	s_mov_b32 m0, s28
	s_nop 0
	global_load_lds_dwordx4 v[236:237], off
	s_waitcnt vmcnt(8)
	s_waitcnt lgkmcnt(0)
	s_barrier
	s_setprio 1
	s_waitcnt lgkmcnt(0)
	v_mfma_f32_16x16x32_bf16 v[126:129], v[160:163], v[196:199], v[126:129]
	v_mfma_f32_16x16x32_bf16 v[122:125], v[170:173], v[196:199], v[122:125]
	v_mfma_f32_16x16x32_bf16 v[118:121], v[160:163], v[204:207], v[118:121]
	v_mfma_f32_16x16x32_bf16 v[110:113], v[170:173], v[204:207], v[110:113]
	v_mfma_f32_16x16x32_bf16 v[102:105], v[160:163], v[212:215], v[102:105]
	v_mfma_f32_16x16x32_bf16 v[94:97], v[170:173], v[212:215], v[94:97]
	v_mfma_f32_16x16x32_bf16 v[86:89], v[160:163], v[220:223], v[86:89]
	v_mfma_f32_16x16x32_bf16 v[78:81], v[170:173], v[220:223], v[78:81]
	v_mfma_f32_16x16x32_bf16 v[126:129], v[166:169], v[200:203], v[126:129]
	v_mfma_f32_16x16x32_bf16 v[122:125], v[174:177], v[200:203], v[122:125]
	v_mfma_f32_16x16x32_bf16 v[118:121], v[166:169], v[208:211], v[118:121]
	v_mfma_f32_16x16x32_bf16 v[110:113], v[174:177], v[208:211], v[110:113]
	v_mfma_f32_16x16x32_bf16 v[102:105], v[166:169], v[216:219], v[102:105]
	v_mfma_f32_16x16x32_bf16 v[94:97], v[174:177], v[216:219], v[94:97]
	v_mfma_f32_16x16x32_bf16 v[86:89], v[166:169], v[224:227], v[86:89]
	v_mfma_f32_16x16x32_bf16 v[78:81], v[174:177], v[224:227], v[78:81]
	s_setprio 0
	s_setprio 1
	v_mfma_f32_16x16x32_bf16 v[114:117], v[178:181], v[196:199], v[114:117]
	v_mfma_f32_16x16x32_bf16 v[106:109], v[188:191], v[196:199], v[106:109]
	v_mfma_f32_16x16x32_bf16 v[98:101], v[178:181], v[204:207], v[98:101]
	v_mfma_f32_16x16x32_bf16 v[90:93], v[188:191], v[204:207], v[90:93]
	v_mfma_f32_16x16x32_bf16 v[82:85], v[178:181], v[212:215], v[82:85]
	v_mfma_f32_16x16x32_bf16 v[74:77], v[188:191], v[212:215], v[74:77]
	v_mfma_f32_16x16x32_bf16 v[70:73], v[178:181], v[220:223], v[70:73]
	v_mfma_f32_16x16x32_bf16 v[66:69], v[188:191], v[220:223], v[66:69]
	v_mfma_f32_16x16x32_bf16 v[114:117], v[184:187], v[200:203], v[114:117]
	v_mfma_f32_16x16x32_bf16 v[106:109], v[192:195], v[200:203], v[106:109]
	v_mfma_f32_16x16x32_bf16 v[98:101], v[184:187], v[208:211], v[98:101]
	v_mfma_f32_16x16x32_bf16 v[90:93], v[192:195], v[208:211], v[90:93]
	v_mfma_f32_16x16x32_bf16 v[82:85], v[184:187], v[216:219], v[82:85]
	v_mfma_f32_16x16x32_bf16 v[74:77], v[192:195], v[216:219], v[74:77]
	v_mfma_f32_16x16x32_bf16 v[70:73], v[184:187], v[224:227], v[70:73]
	v_mfma_f32_16x16x32_bf16 v[66:69], v[192:195], v[224:227], v[66:69]
	s_setprio 0
	s_barrier
; #define PG8_STAGE(bufoff, gbase, voff) do { _Pragma("unroll") for (int _i = 0; _i < 2; ++_i) \
;         __builtin_amdgcn_global_load_lds((const unsigned*)((const char*)(gbase) + (voff)[_i]), (LAS unsigned*)(lds + (bufoff) + ldsw + _i * 8192), 16, 0, 0); } while (0)
; #define PG8_LDA(dst, b, h) do { _Pragma("unroll") for (int m = 0; m < 4; ++m) _Pragma("unroll") for (int k = 0; k < 2; ++k) dst[m][k] = *(const LAS bf16x8*)(lds + PG8_SA(b, h) + aoff + m * 2048 + k * 1024); } while (0)
; #define PG8_LDB(dst, b, h) do { _Pragma("unroll") for (int n = 0; n < 2; ++n) _Pragma("unroll") for (int k = 0; k < 2; ++k) dst[n][k] = *(const LAS bf16x8*)(lds + PG8_SB(b, h) + boff + n * 2048 + k * 1024); } while (0)
; template <class Epi, bool ALIGN_EPI = PG8_ALIGN, bool SP2 = PG8_SP2>
; __device__ __forceinline__ void gemm_phase(LAS uchar* lds, const Gemm g, const StaticOrder& S, const Epi& E) {
;     ...
;         for (int t = tb; t < tb + tblk; t += 2) {
;             const bool last = (t == nt - 2);
;             const char* a1 = cA + (size_t)(t + 1) * kstep;
;             const char* a2 = last ? nA : cA + (size_t)(t + 2) * kstep; const char* b2 = last ? nB : cB + (size_t)(t + 2) * kstep;
;             const char* a3 = a2 + kstep; const char* b3 = b2 + kstep;
;             if constexpr (SP2) {
;             PG8_LDB(B0, 0, 0); PG8_LDB(B1, 0, 1); PG8_SCHED; PG8_LDA(At, 0, 0); PG8_STAGE(PG8_SA(1, 1), a1 + hstepA, voffA);
;             PG8_WAIT_V(8); PG8_WAIT_L(0); PG8_BAR; PG8_MMA(0, 0, At, B0); PG8_MMA(0, 1, At, B1); PG8_BAR; PG8_SCHED;
;             PG8_LDA(At, 0, 1); PG8_STAGE(PG8_SB(0, 0), b2, voffB); PG8_STAGE(PG8_SB(0, 1), b2 + hstepB, voffB); PG8_STAGE(PG8_SA(0, 0), a2, voffA);
;             PG8_WAIT_V(8); PG8_WAIT_L(0); PG8_BAR; PG8_MMA(1, 0, At, B0); PG8_MMA(1, 1, At, B1); PG8_BAR; PG8_SCHED;
;             PG8_LDB(B0, 1, 0); PG8_LDB(B1, 1, 1); PG8_SCHED; PG8_LDA(At, 1, 0); PG8_STAGE(PG8_SA(0, 1), a2 + hstepA, voffA);
;             PG8_WAIT_V(8); PG8_WAIT_L(0); PG8_BAR; PG8_MMA(0, 0, At, B0); PG8_MMA(0, 1, At, B1); PG8_BAR; PG8_SCHED;
;             PG8_LDA(At, 1, 1); PG8_STAGE(PG8_SB(1, 0), b3, voffB); PG8_STAGE(PG8_SB(1, 1), b3 + hstepB, voffB); PG8_STAGE(PG8_SA(1, 0), a3, voffA);
;             PG8_WAIT_V(8); PG8_WAIT_L(0); PG8_BAR; PG8_MMA(1, 0, At, B0); PG8_MMA(1, 1, At, B1); PG8_BAR; PG8_SCHED;
;     ...
;         if constexpr (ALIGN_EPI) { if (wr == 0) PG8_BAR; }
	s_add_i32 s14, s41, s24
	v_lshl_add_u64 v[228:229], v[228:229], 0, s[84:85]
	s_mov_b32 m0, s14
	ds_read_b128 v[196:199], v165 offset:49152
	ds_read_b128 v[200:203], v165 offset:50176
	ds_read_b128 v[204:207], v165 offset:51200
	ds_read_b128 v[208:211], v165 offset:52224
	ds_read_b128 v[212:215], v165 offset:53248
	ds_read_b128 v[216:219], v165 offset:54272
	ds_read_b128 v[220:223], v165 offset:55296
	ds_read_b128 v[224:227], v165 offset:56320
	global_load_lds_dwordx4 v[228:229], off
	s_add_i32 m0, s14, 0x2000
	s_add_u32 s14, s18, 0xb0080
	v_lshl_add_u64 v[228:229], v[230:231], 0, s[84:85]
	s_addc_u32 s15, s19, 0
	s_add_i32 s18, s42, s24
	global_load_lds_dwordx4 v[228:229], off
	v_lshl_add_u64 v[228:229], s[14:15], 0, v[132:133]
	s_mov_b32 m0, s18
	s_nop 0
	global_load_lds_dwordx4 v[228:229], off
	v_lshl_add_u64 v[228:229], s[14:15], 0, v[154:155]
	s_add_i32 m0, s18, 0x2000
	s_nop 0
	global_load_lds_dwordx4 v[228:229], off
	v_lshl_add_u64 v[228:229], v[232:233], 0, s[84:85]
	s_mov_b32 m0, s29
	s_nop 0
	global_load_lds_dwordx4 v[228:229], off
	v_lshl_add_u64 v[228:229], v[234:235], 0, s[84:85]
	s_mov_b32 m0, s30
	s_nop 0
	global_load_lds_dwordx4 v[228:229], off
	s_waitcnt vmcnt(8)
	s_waitcnt lgkmcnt(0)
	s_barrier
	s_setprio 1
	s_waitcnt lgkmcnt(0)
	v_mfma_f32_16x16x32_bf16 v[62:65], v[160:163], v[196:199], v[62:65]
	v_mfma_f32_16x16x32_bf16 v[58:61], v[170:173], v[196:199], v[58:61]
	v_mfma_f32_16x16x32_bf16 v[54:57], v[160:163], v[204:207], v[54:57]
	v_mfma_f32_16x16x32_bf16 v[46:49], v[170:173], v[204:207], v[46:49]
	v_mfma_f32_16x16x32_bf16 v[38:41], v[160:163], v[212:215], v[38:41]
	v_mfma_f32_16x16x32_bf16 v[30:33], v[170:173], v[212:215], v[30:33]
	v_mfma_f32_16x16x32_bf16 v[22:25], v[160:163], v[220:223], v[22:25]
	v_mfma_f32_16x16x32_bf16 v[14:17], v[170:173], v[220:223], v[14:17]
	v_mfma_f32_16x16x32_bf16 v[62:65], v[166:169], v[200:203], v[62:65]
	v_mfma_f32_16x16x32_bf16 v[58:61], v[174:177], v[200:203], v[58:61]
	v_mfma_f32_16x16x32_bf16 v[54:57], v[166:169], v[208:211], v[54:57]
	v_mfma_f32_16x16x32_bf16 v[46:49], v[174:177], v[208:211], v[46:49]
	v_mfma_f32_16x16x32_bf16 v[38:41], v[166:169], v[216:219], v[38:41]
	v_mfma_f32_16x16x32_bf16 v[30:33], v[174:177], v[216:219], v[30:33]
	v_mfma_f32_16x16x32_bf16 v[22:25], v[166:169], v[224:227], v[22:25]
	v_mfma_f32_16x16x32_bf16 v[14:17], v[174:177], v[224:227], v[14:17]
	s_setprio 0
	s_setprio 1
	v_mfma_f32_16x16x32_bf16 v[50:53], v[178:181], v[196:199], v[50:53]
	v_mfma_f32_16x16x32_bf16 v[42:45], v[188:191], v[196:199], v[42:45]
	v_mfma_f32_16x16x32_bf16 v[34:37], v[178:181], v[204:207], v[34:37]
	v_mfma_f32_16x16x32_bf16 v[26:29], v[188:191], v[204:207], v[26:29]
	v_mfma_f32_16x16x32_bf16 v[18:21], v[178:181], v[212:215], v[18:21]
	v_mfma_f32_16x16x32_bf16 v[10:13], v[188:191], v[212:215], v[10:13]
	v_mfma_f32_16x16x32_bf16 v[6:9], v[178:181], v[220:223], v[6:9]
	v_mfma_f32_16x16x32_bf16 v[2:5], v[188:191], v[220:223], v[2:5]
	v_mfma_f32_16x16x32_bf16 v[50:53], v[184:187], v[200:203], v[50:53]
	v_mfma_f32_16x16x32_bf16 v[42:45], v[192:195], v[200:203], v[42:45]
	v_mfma_f32_16x16x32_bf16 v[34:37], v[184:187], v[208:211], v[34:37]
	v_mfma_f32_16x16x32_bf16 v[26:29], v[192:195], v[208:211], v[26:29]
	v_mfma_f32_16x16x32_bf16 v[18:21], v[184:187], v[216:219], v[18:21]
	v_mfma_f32_16x16x32_bf16 v[10:13], v[192:195], v[216:219], v[10:13]
	v_mfma_f32_16x16x32_bf16 v[6:9], v[184:187], v[224:227], v[6:9]
	v_mfma_f32_16x16x32_bf16 v[2:5], v[192:195], v[224:227], v[2:5]
	s_setprio 0
	s_add_i32 s40, s40, 2
	s_add_u32 s38, s38, 0x100
	s_addc_u32 s39, s39, 0
	s_cmp_gt_u32 s40, 41
	s_mov_b64 s[14:15], s[16:17]
	s_cbranch_scc1 .Lrot_exit_1143
	s_add_u32 s16, s14, 0x100
	s_addc_u32 s17, s15, 0
	s_add_i32 s41, 0, 0x10000
	s_cmp_eq_u32 s40, 40
	s_cselect_b32 s21, s5, s17
	s_cselect_b32 s20, s4, s16
	s_cselect_b32 s19, s13, s39
	s_cselect_b32 s18, s12, s38
	s_add_i32 s42, 0, 0x14000
	v_add_u32_e32 v144, s41, v139
	s_branch .LBB0_1143
.Lrot_exit_1143:
	s_barrier
	s_and_b64 vcc, exec, s[10:11]
	s_cbranch_vccz .LBB0_1146
	s_barrier
